# GEMM epilogue write-through stores marked non-temporal (sc1 nt)
# speedup vs baseline: 1.0126x; 1.0126x over previous
; __device__ __forceinline__ void conv_pass(const bf16_t* __restrict__ U, const float* __restrict__ cw, const float* __restrict__ cb, bf16_t* __restrict__ GA, int tg, int wv) {
;     ...
;     for (int it = gt; it < NITEM; it += NGT) {
;         const int ch = it % NCH, run = it / NCH, c0 = ch * 8, t0 = run * RUN;
;         const u32x4 zero = {0u, 0u, 0u, 0u};
;         u32x4 ra[RUN + 2], rb[RUN + 2];
; #pragma unroll
;         for (int i = 0; i < RUN + 2; ++i) {
;             const int t = t0 - 1 + i;
;             const bool ok = !((i == 0 && (t0 & (SEQ - 1)) == 0) || (i == RUN + 1 && ((t0 + RUN) & (SEQ - 1)) == 0));
;             const bf16_t* p = U + (size_t)(ok ? t : t0) * DFF2 + c0;
;             const u32x4 a = *(const u32x4*)p, b = *(const u32x4*)(p + DFF);
;             ra[i] = ok ? a : zero; rb[i] = ok ? b : zero;
;         }
;         f32x4 wa[3][2], wb[3][2], ba[2], bb[2];
; #pragma unroll
;         for (int k = 0; k < 3; ++k) { wa[k][0] = *(const f32x4*)(cw + k * DFF2 + c0); wa[k][1] = *(const f32x4*)(cw + k * DFF2 + c0 + 4);
;                                       wb[k][0] = *(const f32x4*)(cw + k * DFF2 + DFF + c0); wb[k][1] = *(const f32x4*)(cw + k * DFF2 + DFF + c0 + 4); }
;         ba[0] = *(const f32x4*)(cb + c0); ba[1] = *(const f32x4*)(cb + c0 + 4); bb[0] = *(const f32x4*)(cb + DFF + c0); bb[1] = *(const f32x4*)(cb + DFF + c0 + 4);
.LBB0_189:
	s_mov_b32 s0, 0x2e8ba2e9
	v_mul_hi_i32 v2, v0, s0
	v_lshrrev_b32_e32 v3, 31, v2
	v_ashrrev_i32_e32 v2, 6, v2
	v_add_u32_e32 v2, v2, v3
	v_mul_i32_i24_e32 v3, 0x160, v2
	v_lshlrev_b32_e32 v3, 3, v3
	v_sub_u32_e32 v10, v154, v3
	v_lshlrev_b32_e32 v170, 3, v2
	v_and_b32_e32 v2, 0x3ff, v2
	v_ashrrev_i32_e32 v11, 31, v10
	v_lshlrev_b64 v[130:131], 1, v[10:11]
	v_cmp_ne_u32_e64 s[2:3], 0, v2
	v_add_u32_e32 v14, 8, v170
	v_lshl_add_u64 v[12:13], s[12:13], 0, v[130:131]
	v_subbrev_co_u32_e64 v2, s[4:5], 0, v170, s[2:3]
	v_and_b32_e32 v3, 0x1ff8, v14
	v_mad_i64_i32 v[6:7], s[0:1], v2, s95, v[12:13]
	v_cmp_eq_u32_e32 vcc, 0, v3
	global_load_dwordx4 v[2:5], v[6:7], off
	v_add_co_u32_e64 v6, s[4:5], s93, v6
	v_or_b32_e32 v169, 1, v170
	s_nop 0
	v_addc_co_u32_e64 v7, s[4:5], 0, v7, s[4:5]
	global_load_dwordx4 v[6:9], v[6:7], off offset:1536
	v_or_b32_e32 v168, 2, v170
	v_or_b32_e32 v167, 3, v170
	v_or_b32_e32 v166, 4, v170
	v_or_b32_e32 v165, 5, v170
	v_or_b32_e32 v163, 6, v170
	v_or_b32_e32 v155, 7, v170
	v_lshl_add_u64 v[130:131], s[68:69], 0, v[130:131]
	v_add_u32_e32 v0, s28, v0
	v_add_u32_e32 v154, s46, v154
	s_waitcnt vmcnt(0)
	v_cndmask_b32_e64 v150, 0, v3, s[2:3]
	v_cndmask_b32_e64 v133, 0, v2, s[2:3]
	v_mad_i64_i32 v[2:3], s[0:1], v170, s95, v[12:13]
	v_cndmask_b32_e64 v152, 0, v5, s[2:3]
	v_cndmask_b32_e64 v138, 0, v4, s[2:3]
	global_load_dwordx4 v[118:121], v[2:3], off
	s_waitcnt vmcnt(1)
	v_cndmask_b32_e64 v171, 0, v9, s[2:3]
	v_cndmask_b32_e64 v153, 0, v8, s[2:3]
	v_cndmask_b32_e64 v139, 0, v7, s[2:3]
	v_cndmask_b32_e64 v140, 0, v6, s[2:3]
	v_add_co_u32_e64 v2, s[2:3], s93, v2
	v_lshlrev_b32_e32 v132, 16, v133
	s_nop 0
	v_addc_co_u32_e64 v3, s[2:3], 0, v3, s[2:3]
	global_load_dwordx4 v[114:117], v[2:3], off offset:1536
	v_mad_i64_i32 v[2:3], s[0:1], v169, s95, v[12:13]
	global_load_dwordx4 v[126:129], v[2:3], off
	v_add_co_u32_e64 v2, s[2:3], s93, v2
	v_and_b32_e32 v133, 0xffff0000, v133
	s_nop 0
	v_addc_co_u32_e64 v3, s[2:3], 0, v3, s[2:3]
	global_load_dwordx4 v[122:125], v[2:3], off offset:1536
	v_mad_i64_i32 v[2:3], s[0:1], v168, s95, v[12:13]
	global_load_dwordx4 v[110:113], v[2:3], off
	v_add_co_u32_e64 v2, s[2:3], s93, v2
	s_waitcnt vmcnt(4)
	v_lshlrev_b32_e32 v146, 16, v118
	v_addc_co_u32_e64 v3, s[2:3], 0, v3, s[2:3]
	global_load_dwordx4 v[106:109], v[2:3], off offset:1536
	v_mad_i64_i32 v[2:3], s[0:1], v167, s95, v[12:13]
	global_load_dwordx4 v[102:105], v[2:3], off
	v_add_co_u32_e64 v2, s[2:3], s93, v2
	v_and_b32_e32 v147, 0xffff0000, v118
	s_nop 0
	v_addc_co_u32_e64 v3, s[2:3], 0, v3, s[2:3]
	global_load_dwordx4 v[98:101], v[2:3], off offset:1536
	v_mad_i64_i32 v[2:3], s[0:1], v166, s95, v[12:13]
	global_load_dwordx4 v[94:97], v[2:3], off
	v_add_co_u32_e64 v2, s[2:3], s93, v2
	s_waitcnt vmcnt(7)
	v_and_b32_e32 v141, 0xffff0000, v114
	v_addc_co_u32_e64 v3, s[2:3], 0, v3, s[2:3]
	global_load_dwordx4 v[90:93], v[2:3], off offset:1536
	v_mad_i64_i32 v[2:3], s[0:1], v165, s95, v[12:13]
	global_load_dwordx4 v[86:89], v[2:3], off
	v_add_co_u32_e64 v2, s[2:3], s93, v2
	v_and_b32_e32 v151, 0xffff0000, v120
	s_nop 0
	v_addc_co_u32_e64 v3, s[2:3], 0, v3, s[2:3]
	global_load_dwordx4 v[82:85], v[2:3], off offset:1536
	v_mad_i64_i32 v[2:3], s[0:1], v163, s95, v[12:13]
	global_load_dwordx4 v[78:81], v[2:3], off
	v_add_co_u32_e64 v2, s[2:3], s93, v2
	s_nop 1
	v_addc_co_u32_e64 v3, s[2:3], 0, v3, s[2:3]
	global_load_dwordx4 v[74:77], v[2:3], off offset:1536
	v_mad_i64_i32 v[2:3], s[0:1], v155, s95, v[12:13]
	global_load_dwordx4 v[70:73], v[2:3], off
	v_add_co_u32_e64 v2, s[2:3], s93, v2
	s_nop 1
	v_addc_co_u32_e64 v3, s[2:3], 0, v3, s[2:3]
	global_load_dwordx4 v[66:69], v[2:3], off offset:1536
	v_cndmask_b32_e32 v2, v14, v170, vcc
	v_mad_i64_i32 v[6:7], s[0:1], v2, s95, v[12:13]
	global_load_dwordx4 v[2:5], v[6:7], off
	v_add_co_u32_e64 v6, s[2:3], s93, v6
	v_lshlrev_b64 v[14:15], 2, v[10:11]
	s_nop 0
	v_addc_co_u32_e64 v7, s[2:3], 0, v7, s[2:3]
	global_load_dwordx4 v[6:9], v[6:7], off offset:1536
	v_lshl_add_u64 v[10:11], s[76:77], 0, v[14:15]
	v_lshl_add_u64 v[16:17], s[80:81], 0, v[14:15]
	v_lshl_add_u64 v[54:55], s[70:71], 0, v[14:15]
	s_waitcnt vmcnt(1)
	v_cndmask_b32_e64 v161, v3, 0, vcc
	v_cndmask_b32_e64 v164, v2, 0, vcc
	v_lshl_add_u64 v[2:3], s[64:65], 0, v[14:15]
	v_cndmask_b32_e64 v157, v5, 0, vcc
	v_cndmask_b32_e64 v159, v4, 0, vcc
	global_load_dwordx4 v[18:21], v[2:3], off offset:16
	global_load_dwordx4 v[38:41], v[2:3], off
	s_waitcnt vmcnt(2)
	v_cndmask_b32_e64 v160, v7, 0, vcc
	v_cndmask_b32_e64 v162, v6, 0, vcc
	v_lshl_add_u64 v[6:7], s[72:73], 0, v[14:15]
	global_load_dwordx4 v[2:5], v[6:7], off offset:16
	global_load_dwordx4 v[34:37], v[6:7], off
	v_lshl_add_u64 v[6:7], s[74:75], 0, v[14:15]
	global_load_dwordx4 v[30:33], v[6:7], off offset:16
	global_load_dwordx4 v[50:53], v[6:7], off
	v_cndmask_b32_e64 v156, v9, 0, vcc
	v_cndmask_b32_e64 v158, v8, 0, vcc
	global_load_dwordx4 v[6:9], v[10:11], off offset:16
	global_load_dwordx4 v[42:45], v[10:11], off
	v_lshl_add_u64 v[10:11], s[78:79], 0, v[14:15]
	global_load_dwordx4 v[22:25], v[10:11], off offset:16
	global_load_dwordx4 v[58:61], v[10:11], off
	s_nop 0
	global_load_dwordx4 v[10:13], v[16:17], off offset:16
	global_load_dwordx4 v[46:49], v[16:17], off
	v_lshl_add_u64 v[16:17], s[66:67], 0, v[14:15]
	global_load_dwordx4 v[26:29], v[16:17], off offset:16
	global_load_dwordx4 v[62:65], v[16:17], off
	s_nop 0
	global_load_dwordx4 v[14:17], v[54:55], off offset:16
	s_nop 0
	global_load_dwordx4 v[54:57], v[54:55], off
	v_cmp_le_i32_e32 vcc, s22, v0
	s_or_b64 s[82:83], vcc, s[82:83]
	s_waitcnt vmcnt(10)
; __device__ __forceinline__ float gelu_tanh(float x) { const float u = 0.7978845608028654f * (x + 0.044715f * x * x * x); return x * sigmoidf_(2.0f * u); }
; __device__ __forceinline__ float bfe(const u32x4& w, int e) { return (e & 1) ? __builtin_bit_cast(float, w[e >> 1] & 0xffff0000u) : __builtin_bit_cast(float, w[e >> 1] << 16); }
; __device__ __forceinline__ void conv_pass(const bf16_t* __restrict__ U, const float* __restrict__ cw, const float* __restrict__ cb, bf16_t* __restrict__ GA, int tg, int wv) {
;     ...
; #pragma unroll
;         for (int i = 0; i < RUN; ++i) {
;             float o[8];
; #pragma unroll
;             for (int e = 0; e < 8; ++e) {
;                 const float ua = bfe(ra[i], e) * wa[0][e >> 2][e & 3] + bfe(ra[i + 1], e) * wa[1][e >> 2][e & 3] + bfe(ra[i + 2], e) * wa[2][e >> 2][e & 3] + ba[e >> 2][e & 3];
;                 const float ub = bfe(rb[i], e) * wb[0][e >> 2][e & 3] + bfe(rb[i + 1], e) * wb[1][e >> 2][e & 3] + bfe(rb[i + 2], e) * wb[2][e >> 2][e & 3] + bb[e >> 2][e & 3];
;                 o[e] = gelu_tanh(ua) * ub;
	v_pk_mul_f32 v[134:135], v[50:51], v[146:147]
	s_nop 0
	v_pk_fma_f32 v[132:133], v[38:39], v[132:133], v[134:135]
	v_lshlrev_b32_e32 v134, 16, v126
	v_and_b32_e32 v135, 0xffff0000, v126
	v_lshlrev_b32_e32 v126, 16, v139
	s_waitcnt vmcnt(6)
	v_pk_fma_f32 v[132:133], v[58:59], v[134:135], v[132:133]
	s_waitcnt vmcnt(2)
	v_pk_add_f32 v[136:137], v[132:133], v[62:63]
	s_nop 0
	v_mul_f32_e32 v118, 0x3d372713, v136
	v_lshlrev_b32_e32 v132, 16, v140
	v_and_b32_e32 v133, 0xffff0000, v140
	v_lshlrev_b32_e32 v140, 16, v114
	v_mul_f32_e32 v114, 0x3d372713, v137
	v_mul_f32_e32 v118, v136, v118
	v_mul_f32_e32 v114, v137, v114
	v_fma_f32 v118, v136, v118, v136
	v_fma_f32 v114, v137, v114, v137
	v_mul_f32_e32 v118, 0x3f4c422a, v118
	v_mul_f32_e32 v114, 0x3f4c422a, v114
	v_add_f32_e32 v118, v118, v118
	v_add_f32_e32 v114, v114, v114
	v_mul_f32_e32 v118, 0xbfb8aa3b, v118
	v_mul_f32_e32 v114, 0xbfb8aa3b, v114
	v_exp_f32_e32 v118, v118
	v_exp_f32_e32 v114, v114
	v_pk_mul_f32 v[144:145], v[42:43], v[140:141]
	v_add_f32_e32 v118, 1.0, v118
	v_add_f32_e32 v114, 1.0, v114
	v_rcp_f32_e32 v142, v118
	v_rcp_f32_e32 v143, v114
	v_pk_fma_f32 v[144:145], v[34:35], v[132:133], v[144:145]
	v_lshlrev_b32_e32 v132, 16, v122
	v_and_b32_e32 v133, 0xffff0000, v122
	v_pk_fma_f32 v[144:145], v[46:47], v[132:133], v[144:145]
	v_pk_mul_f32 v[136:137], v[136:137], v[142:143]
	s_waitcnt vmcnt(0)
	v_pk_add_f32 v[144:145], v[144:145], v[54:55]
	v_lshlrev_b32_e32 v142, 16, v115
	v_pk_mul_f32 v[148:149], v[144:145], v[136:137]
	v_lshlrev_b32_e32 v144, 16, v119
	v_and_b32_e32 v145, 0xffff0000, v119
	v_lshlrev_b32_e32 v136, 16, v150
	v_and_b32_e32 v137, 0xffff0000, v150
	v_pk_mul_f32 v[118:119], v[52:53], v[144:145]
	v_and_b32_e32 v143, 0xffff0000, v115
	v_pk_fma_f32 v[118:119], v[40:41], v[136:137], v[118:119]
	v_lshlrev_b32_e32 v136, 16, v127
	v_and_b32_e32 v137, 0xffff0000, v127
	v_pk_fma_f32 v[118:119], v[60:61], v[136:137], v[118:119]
	v_and_b32_e32 v127, 0xffff0000, v139
	v_pk_add_f32 v[118:119], v[118:119], v[64:65]
	v_lshlrev_b32_e32 v150, 16, v120
	v_mul_f32_e32 v114, 0x3d372713, v118
	v_mul_f32_e32 v114, v118, v114
	v_fma_f32 v114, v118, v114, v118
	v_mul_f32_e32 v114, 0x3f4c422a, v114
	v_add_f32_e32 v114, v114, v114
	v_mul_f32_e32 v114, 0xbfb8aa3b, v114
	v_exp_f32_e32 v114, v114
	v_and_b32_e32 v139, 0xffff0000, v128
	v_add_f32_e32 v114, 1.0, v114
	v_rcp_f32_e32 v122, v114
	v_pk_mul_f32 v[114:115], v[44:45], v[142:143]
	s_nop 0
	v_pk_fma_f32 v[126:127], v[36:37], v[126:127], v[114:115]
	v_lshlrev_b32_e32 v114, 16, v123
	v_and_b32_e32 v115, 0xffff0000, v123
	v_mul_f32_e32 v123, 0x3d372713, v119
	v_mul_f32_e32 v123, v119, v123
	v_fma_f32 v123, v119, v123, v119
	v_mul_f32_e32 v123, 0x3f4c422a, v123
	v_add_f32_e32 v123, v123, v123
	v_mul_f32_e32 v123, 0xbfb8aa3b, v123
	v_exp_f32_e32 v123, v123
	v_pk_fma_f32 v[126:127], v[48:49], v[114:115], v[126:127]
	v_add_f32_e32 v123, 1.0, v123
	v_rcp_f32_e32 v123, v123
	v_pk_add_f32 v[126:127], v[126:127], v[56:57]
	v_pk_mul_f32 v[118:119], v[118:119], v[122:123]
	s_nop 0
	v_pk_mul_f32 v[126:127], v[126:127], v[118:119]
	v_lshlrev_b32_e32 v118, 16, v138
	v_and_b32_e32 v119, 0xffff0000, v138
	v_pk_mul_f32 v[122:123], v[30:31], v[150:151]
	v_lshlrev_b32_e32 v138, 16, v128
	v_pk_fma_f32 v[118:119], v[18:19], v[118:119], v[122:123]
	v_lshlrev_b32_e32 v122, 16, v116
	v_pk_fma_f32 v[118:119], v[22:23], v[138:139], v[118:119]
	v_and_b32_e32 v123, 0xffff0000, v116
	v_pk_add_f32 v[172:173], v[118:119], v[26:27]
	v_and_b32_e32 v119, 0xffff0000, v153
	v_mul_f32_e32 v118, 0x3d372713, v172
	v_mul_f32_e32 v116, 0x3d372713, v173
	v_mul_f32_e32 v118, v172, v118
	v_mul_f32_e32 v116, v173, v116
	v_fma_f32 v118, v172, v118, v172
	v_fma_f32 v116, v173, v116, v173
	v_mul_f32_e32 v118, 0x3f4c422a, v118
	v_mul_f32_e32 v116, 0x3f4c422a, v116
	v_add_f32_e32 v118, v118, v118
	v_add_f32_e32 v116, v116, v116
	v_mul_f32_e32 v118, 0xbfb8aa3b, v118
	v_mul_f32_e32 v116, 0xbfb8aa3b, v116
	v_exp_f32_e32 v118, v118
	v_exp_f32_e32 v116, v116
	v_lshlrev_b32_e32 v128, 16, v129
	v_and_b32_e32 v129, 0xffff0000, v129
	v_add_f32_e32 v118, 1.0, v118
	v_add_f32_e32 v116, 1.0, v116
	v_rcp_f32_e32 v174, v118
	v_rcp_f32_e32 v175, v116
	v_lshlrev_b32_e32 v118, 16, v153
	v_and_b32_e32 v153, 0xffff0000, v121
	v_pk_mul_f32 v[176:177], v[6:7], v[122:123]
	v_pk_mul_f32 v[172:173], v[172:173], v[174:175]
	v_lshlrev_b32_e32 v174, 16, v152
	v_and_b32_e32 v175, 0xffff0000, v152
	v_lshlrev_b32_e32 v152, 16, v121
	v_pk_mul_f32 v[120:121], v[32:33], v[152:153]
	v_pk_fma_f32 v[176:177], v[2:3], v[118:119], v[176:177]
	v_pk_fma_f32 v[120:121], v[20:21], v[174:175], v[120:121]
	v_lshlrev_b32_e32 v118, 16, v124
	v_pk_fma_f32 v[120:121], v[24:25], v[128:129], v[120:121]
	v_and_b32_e32 v119, 0xffff0000, v124
	v_pk_add_f32 v[174:175], v[120:121], v[28:29]
	v_pk_fma_f32 v[176:177], v[10:11], v[118:119], v[176:177]
	v_mul_f32_e32 v116, 0x3d372713, v174
	v_mul_f32_e32 v116, v174, v116
	v_fma_f32 v116, v174, v116, v174
	v_mul_f32_e32 v116, 0x3f4c422a, v116
	v_add_f32_e32 v116, v116, v116
	v_mul_f32_e32 v116, 0xbfb8aa3b, v116
	v_exp_f32_e32 v116, v116
	v_pk_add_f32 v[176:177], v[176:177], v[14:15]
	v_lshlrev_b32_e32 v120, 16, v117
	v_and_b32_e32 v121, 0xffff0000, v117
	v_add_f32_e32 v116, 1.0, v116
	v_pk_mul_f32 v[172:173], v[176:177], v[172:173]
	v_rcp_f32_e32 v124, v116
	v_lshlrev_b32_e32 v176, 16, v171
	v_and_b32_e32 v177, 0xffff0000, v171
	v_pk_mul_f32 v[116:117], v[8:9], v[120:121]
	s_nop 0
	v_pk_fma_f32 v[176:177], v[4:5], v[176:177], v[116:117]
	v_lshlrev_b32_e32 v116, 16, v125
	v_and_b32_e32 v117, 0xffff0000, v125
	v_mul_f32_e32 v125, 0x3d372713, v175
	v_mul_f32_e32 v125, v175, v125
; __device__ __forceinline__ unsigned cvtpk(float lo, float hi) { f32x2 v = {lo, hi}; bf16x2_t b = __builtin_convertvector(v, bf16x2_t); return __builtin_bit_cast(unsigned, b); }
; __device__ __forceinline__ float gelu_tanh(float x) { const float u = 0.7978845608028654f * (x + 0.044715f * x * x * x); return x * sigmoidf_(2.0f * u); }
; __device__ __forceinline__ void st16_wt(void* p, u32x4 v) { asm volatile("global_store_dwordx4 %0, %1, off sc1\n\ts_nop 2" :: "v"(p), "v"(v) : "memory"); }
; __device__ __forceinline__ float bfe(const u32x4& w, int e) { return (e & 1) ? __builtin_bit_cast(float, w[e >> 1] & 0xffff0000u) : __builtin_bit_cast(float, w[e >> 1] << 16); }
; __device__ __forceinline__ void conv_pass(const bf16_t* __restrict__ U, const float* __restrict__ cw, const float* __restrict__ cb, bf16_t* __restrict__ GA, int tg, int wv) {
;     ...
; #pragma unroll
;         for (int i = 0; i < RUN; ++i) {
;             float o[8];
; #pragma unroll
;             for (int e = 0; e < 8; ++e) {
;                 const float ua = bfe(ra[i], e) * wa[0][e >> 2][e & 3] + bfe(ra[i + 1], e) * wa[1][e >> 2][e & 3] + bfe(ra[i + 2], e) * wa[2][e >> 2][e & 3] + ba[e >> 2][e & 3];
;                 const float ub = bfe(rb[i], e) * wb[0][e >> 2][e & 3] + bfe(rb[i + 1], e) * wb[1][e >> 2][e & 3] + bfe(rb[i + 2], e) * wb[2][e >> 2][e & 3] + bb[e >> 2][e & 3];
;                 o[e] = gelu_tanh(ua) * ub;
;             }
;             u32x4 w; w.x = cvtpk(o[0], o[1]); w.y = cvtpk(o[2], o[3]); w.z = cvtpk(o[4], o[5]); w.w = cvtpk(o[6], o[7]);
;             st16_wt(GA + (size_t)(t0 + i) * DFF + c0, w);
	v_fma_f32 v125, v175, v125, v175
	v_mul_f32_e32 v125, 0x3f4c422a, v125
	v_add_f32_e32 v125, v125, v125
	v_mul_f32_e32 v125, 0xbfb8aa3b, v125
	v_exp_f32_e32 v125, v125
	v_pk_fma_f32 v[176:177], v[12:13], v[116:117], v[176:177]
	v_add_f32_e32 v125, 1.0, v125
	v_rcp_f32_e32 v125, v125
	v_pk_add_f32 v[176:177], v[176:177], v[16:17]
	v_pk_mul_f32 v[124:125], v[174:175], v[124:125]
	s_nop 0
	v_pk_mul_f32 v[174:175], v[176:177], v[124:125]
	v_cvt_pk_bf16_f32 v124, v148, v149
	v_cvt_pk_bf16_f32 v125, v126, v127
	v_cvt_pk_bf16_f32 v126, v172, v173
	v_cvt_pk_bf16_f32 v127, v174, v175
	v_mad_i64_i32 v[148:149], s[0:1], v170, s91, v[130:131]
	global_store_dwordx4 v[148:149], v[124:127], off sc1 nt
	s_nop 2
	v_pk_mul_f32 v[124:125], v[50:51], v[134:135]
	v_lshlrev_b32_e32 v148, 16, v110
	v_pk_fma_f32 v[124:125], v[38:39], v[146:147], v[124:125]
	v_and_b32_e32 v149, 0xffff0000, v110
	v_pk_fma_f32 v[124:125], v[58:59], v[148:149], v[124:125]
	v_pk_mul_f32 v[126:127], v[42:43], v[132:133]
	v_pk_add_f32 v[124:125], v[124:125], v[62:63]
	v_pk_fma_f32 v[140:141], v[34:35], v[140:141], v[126:127]
	v_mul_f32_e32 v110, 0x3d372713, v124
	v_lshlrev_b32_e32 v126, 16, v106
	v_and_b32_e32 v127, 0xffff0000, v106
	v_mul_f32_e32 v106, 0x3d372713, v125
	v_mul_f32_e32 v110, v124, v110
	v_mul_f32_e32 v106, v125, v106
	v_fma_f32 v110, v124, v110, v124
	v_fma_f32 v106, v125, v106, v125
	v_mul_f32_e32 v110, 0x3f4c422a, v110
	v_mul_f32_e32 v106, 0x3f4c422a, v106
	v_add_f32_e32 v110, v110, v110
	v_add_f32_e32 v106, v106, v106
	v_mul_f32_e32 v110, 0xbfb8aa3b, v110
	v_mul_f32_e32 v106, 0xbfb8aa3b, v106
	v_exp_f32_e32 v110, v110
	v_exp_f32_e32 v106, v106
	v_pk_fma_f32 v[140:141], v[46:47], v[126:127], v[140:141]
	v_add_f32_e32 v110, 1.0, v110
	v_add_f32_e32 v106, 1.0, v106
	v_rcp_f32_e32 v146, v110
	v_rcp_f32_e32 v147, v106
	v_pk_add_f32 v[140:141], v[140:141], v[54:55]
	v_pk_mul_f32 v[124:125], v[124:125], v[146:147]
	s_nop 0
	v_pk_mul_f32 v[146:147], v[140:141], v[124:125]
	v_pk_mul_f32 v[124:125], v[52:53], v[136:137]
	s_nop 0
	v_pk_fma_f32 v[124:125], v[40:41], v[144:145], v[124:125]
	v_lshlrev_b32_e32 v144, 16, v111
	v_and_b32_e32 v145, 0xffff0000, v111
	v_pk_fma_f32 v[110:111], v[60:61], v[144:145], v[124:125]
	v_pk_mul_f32 v[124:125], v[44:45], v[114:115]
	v_pk_add_f32 v[110:111], v[110:111], v[64:65]
	v_pk_fma_f32 v[140:141], v[36:37], v[142:143], v[124:125]
	v_mul_f32_e32 v106, 0x3d372713, v110
	v_lshlrev_b32_e32 v124, 16, v107
	v_and_b32_e32 v125, 0xffff0000, v107
	v_mul_f32_e32 v107, 0x3d372713, v111
	v_mul_f32_e32 v106, v110, v106
	v_mul_f32_e32 v107, v111, v107
	v_fma_f32 v106, v110, v106, v110
	v_fma_f32 v107, v111, v107, v111
	v_mul_f32_e32 v106, 0x3f4c422a, v106
	v_mul_f32_e32 v107, 0x3f4c422a, v107
	v_add_f32_e32 v106, v106, v106
	v_add_f32_e32 v107, v107, v107
	v_mul_f32_e32 v106, 0xbfb8aa3b, v106
	v_mul_f32_e32 v107, 0xbfb8aa3b, v107
	v_exp_f32_e32 v106, v106
	v_exp_f32_e32 v107, v107
	v_pk_fma_f32 v[140:141], v[48:49], v[124:125], v[140:141]
	v_lshlrev_b32_e32 v142, 16, v112
	v_add_f32_e32 v106, 1.0, v106
	v_add_f32_e32 v107, 1.0, v107
	v_rcp_f32_e32 v106, v106
	v_rcp_f32_e32 v107, v107
	v_pk_add_f32 v[140:141], v[140:141], v[56:57]
	v_and_b32_e32 v143, 0xffff0000, v112
	v_pk_mul_f32 v[106:107], v[110:111], v[106:107]
	s_nop 0
	v_pk_mul_f32 v[110:111], v[140:141], v[106:107]
	v_pk_mul_f32 v[106:107], v[30:31], v[138:139]
	s_nop 0
	v_pk_fma_f32 v[106:107], v[18:19], v[150:151], v[106:107]
	v_pk_mul_f32 v[150:151], v[6:7], v[118:119]
	v_pk_fma_f32 v[106:107], v[22:23], v[142:143], v[106:107]
	v_pk_fma_f32 v[150:151], v[2:3], v[122:123], v[150:151]
	v_pk_add_f32 v[106:107], v[106:107], v[26:27]
	v_lshlrev_b32_e32 v122, 16, v108
	v_mul_f32_e32 v112, 0x3d372713, v106
	v_and_b32_e32 v123, 0xffff0000, v108
	v_mul_f32_e32 v108, 0x3d372713, v107
	v_mul_f32_e32 v112, v106, v112
	v_mul_f32_e32 v108, v107, v108
	v_fma_f32 v112, v106, v112, v106
	v_fma_f32 v108, v107, v108, v107
	v_mul_f32_e32 v112, 0x3f4c422a, v112
	v_mul_f32_e32 v108, 0x3f4c422a, v108
	v_add_f32_e32 v112, v112, v112
	v_add_f32_e32 v108, v108, v108
	v_mul_f32_e32 v112, 0xbfb8aa3b, v112
	v_mul_f32_e32 v108, 0xbfb8aa3b, v108
	v_exp_f32_e32 v112, v112
	v_exp_f32_e32 v108, v108
	v_pk_fma_f32 v[150:151], v[10:11], v[122:123], v[150:151]
	v_add_f32_e32 v112, 1.0, v112
	v_add_f32_e32 v108, 1.0, v108
	v_rcp_f32_e32 v140, v112
	v_rcp_f32_e32 v141, v108
	v_pk_add_f32 v[150:151], v[150:151], v[14:15]
	v_pk_mul_f32 v[106:107], v[106:107], v[140:141]
	s_nop 0
	v_pk_mul_f32 v[150:151], v[150:151], v[106:107]
	v_pk_mul_f32 v[106:107], v[32:33], v[128:129]
	v_lshlrev_b32_e32 v140, 16, v113
	v_pk_fma_f32 v[106:107], v[20:21], v[152:153], v[106:107]
	v_and_b32_e32 v141, 0xffff0000, v113
	v_pk_fma_f32 v[106:107], v[24:25], v[140:141], v[106:107]
	v_pk_mul_f32 v[112:113], v[8:9], v[116:117]
	v_pk_add_f32 v[106:107], v[106:107], v[28:29]
	v_pk_fma_f32 v[112:113], v[4:5], v[120:121], v[112:113]
	v_mul_f32_e32 v108, 0x3d372713, v106
	v_lshlrev_b32_e32 v120, 16, v109
	v_and_b32_e32 v121, 0xffff0000, v109
	v_mul_f32_e32 v109, 0x3d372713, v107
	v_mul_f32_e32 v108, v106, v108
	v_mul_f32_e32 v109, v107, v109
	v_fma_f32 v108, v106, v108, v106
	v_fma_f32 v109, v107, v109, v107
	v_mul_f32_e32 v108, 0x3f4c422a, v108
	v_mul_f32_e32 v109, 0x3f4c422a, v109
	v_add_f32_e32 v108, v108, v108
	v_add_f32_e32 v109, v109, v109
	v_mul_f32_e32 v108, 0xbfb8aa3b, v108
	v_mul_f32_e32 v109, 0xbfb8aa3b, v109
	v_exp_f32_e32 v108, v108
	v_exp_f32_e32 v109, v109
	v_pk_fma_f32 v[112:113], v[12:13], v[120:121], v[112:113]
	v_add_f32_e32 v108, 1.0, v108
	v_add_f32_e32 v109, 1.0, v109
	v_rcp_f32_e32 v108, v108
	v_rcp_f32_e32 v109, v109
; __device__ __forceinline__ unsigned cvtpk(float lo, float hi) { f32x2 v = {lo, hi}; bf16x2_t b = __builtin_convertvector(v, bf16x2_t); return __builtin_bit_cast(unsigned, b); }
; __device__ __forceinline__ float gelu_tanh(float x) { const float u = 0.7978845608028654f * (x + 0.044715f * x * x * x); return x * sigmoidf_(2.0f * u); }
; __device__ __forceinline__ void st16_wt(void* p, u32x4 v) { asm volatile("global_store_dwordx4 %0, %1, off sc1\n\ts_nop 2" :: "v"(p), "v"(v) : "memory"); }
; __device__ __forceinline__ float bfe(const u32x4& w, int e) { return (e & 1) ? __builtin_bit_cast(float, w[e >> 1] & 0xffff0000u) : __builtin_bit_cast(float, w[e >> 1] << 16); }
; __device__ __forceinline__ void conv_pass(const bf16_t* __restrict__ U, const float* __restrict__ cw, const float* __restrict__ cb, bf16_t* __restrict__ GA, int tg, int wv) {
;     ...
; #pragma unroll
;         for (int i = 0; i < RUN; ++i) {
;             float o[8];
; #pragma unroll
;             for (int e = 0; e < 8; ++e) {
;                 const float ua = bfe(ra[i], e) * wa[0][e >> 2][e & 3] + bfe(ra[i + 1], e) * wa[1][e >> 2][e & 3] + bfe(ra[i + 2], e) * wa[2][e >> 2][e & 3] + ba[e >> 2][e & 3];
;                 const float ub = bfe(rb[i], e) * wb[0][e >> 2][e & 3] + bfe(rb[i + 1], e) * wb[1][e >> 2][e & 3] + bfe(rb[i + 2], e) * wb[2][e >> 2][e & 3] + bb[e >> 2][e & 3];
;                 o[e] = gelu_tanh(ua) * ub;
;             }
;             u32x4 w; w.x = cvtpk(o[0], o[1]); w.y = cvtpk(o[2], o[3]); w.z = cvtpk(o[4], o[5]); w.w = cvtpk(o[6], o[7]);
;             st16_wt(GA + (size_t)(t0 + i) * DFF + c0, w);
	v_pk_add_f32 v[112:113], v[112:113], v[16:17]
	v_pk_mul_f32 v[106:107], v[106:107], v[108:109]
	s_nop 0
	v_pk_mul_f32 v[112:113], v[112:113], v[106:107]
	v_cvt_pk_bf16_f32 v106, v146, v147
	v_cvt_pk_bf16_f32 v107, v110, v111
	v_cvt_pk_bf16_f32 v108, v150, v151
	v_cvt_pk_bf16_f32 v109, v112, v113
	v_mad_i64_i32 v[110:111], s[0:1], v169, s91, v[130:131]
	global_store_dwordx4 v[110:111], v[106:109], off sc1 nt
	s_nop 2
	v_pk_mul_f32 v[106:107], v[50:51], v[148:149]
	v_lshlrev_b32_e32 v146, 16, v102
	v_pk_fma_f32 v[106:107], v[38:39], v[134:135], v[106:107]
	v_and_b32_e32 v147, 0xffff0000, v102
	v_pk_fma_f32 v[106:107], v[58:59], v[146:147], v[106:107]
	v_lshlrev_b32_e32 v112, 16, v98
	v_pk_add_f32 v[106:107], v[106:107], v[62:63]
	v_and_b32_e32 v113, 0xffff0000, v98
	v_mul_f32_e32 v102, 0x3d372713, v106
	v_mul_f32_e32 v98, 0x3d372713, v107
	v_mul_f32_e32 v102, v106, v102
	v_mul_f32_e32 v98, v107, v98
	v_fma_f32 v102, v106, v102, v106
	v_fma_f32 v98, v107, v98, v107
	v_mul_f32_e32 v102, 0x3f4c422a, v102
	v_mul_f32_e32 v98, 0x3f4c422a, v98
	v_add_f32_e32 v102, v102, v102
	v_add_f32_e32 v98, v98, v98
	v_mul_f32_e32 v102, 0xbfb8aa3b, v102
	v_mul_f32_e32 v98, 0xbfb8aa3b, v98
	v_exp_f32_e32 v102, v102
	v_exp_f32_e32 v98, v98
	v_lshlrev_b32_e32 v134, 16, v103
	v_and_b32_e32 v135, 0xffff0000, v103
	v_add_f32_e32 v102, 1.0, v102
	v_add_f32_e32 v98, 1.0, v98
	v_rcp_f32_e32 v108, v102
	v_rcp_f32_e32 v109, v98
	v_pk_mul_f32 v[110:111], v[42:43], v[126:127]
	v_pk_mul_f32 v[106:107], v[106:107], v[108:109]
	v_pk_mul_f32 v[108:109], v[52:53], v[144:145]
	v_pk_fma_f32 v[110:111], v[34:35], v[132:133], v[110:111]
	v_pk_fma_f32 v[108:109], v[40:41], v[136:137], v[108:109]
	v_pk_fma_f32 v[110:111], v[46:47], v[112:113], v[110:111]
	v_pk_fma_f32 v[102:103], v[60:61], v[134:135], v[108:109]
	v_pk_add_f32 v[110:111], v[110:111], v[54:55]
	v_pk_add_f32 v[102:103], v[102:103], v[64:65]
	v_pk_mul_f32 v[106:107], v[110:111], v[106:107]
	v_mul_f32_e32 v98, 0x3d372713, v102
	v_mul_f32_e32 v109, 0x3d372713, v103
	v_mul_f32_e32 v98, v102, v98
	v_mul_f32_e32 v109, v103, v109
	v_fma_f32 v98, v102, v98, v102
	v_fma_f32 v109, v103, v109, v103
	v_mul_f32_e32 v98, 0x3f4c422a, v98
	v_mul_f32_e32 v109, 0x3f4c422a, v109
	v_add_f32_e32 v98, v98, v98
	v_add_f32_e32 v109, v109, v109
	v_mul_f32_e32 v98, 0xbfb8aa3b, v98
	v_mul_f32_e32 v109, 0xbfb8aa3b, v109
	v_exp_f32_e32 v98, v98
	v_exp_f32_e32 v109, v109
	v_pk_mul_f32 v[110:111], v[44:45], v[124:125]
	v_lshlrev_b32_e32 v132, 16, v104
	v_add_f32_e32 v98, 1.0, v98
	v_add_f32_e32 v109, 1.0, v109
	v_rcp_f32_e32 v108, v98
	v_rcp_f32_e32 v109, v109
	v_pk_fma_f32 v[110:111], v[36:37], v[114:115], v[110:111]
	v_lshlrev_b32_e32 v98, 16, v99
	v_and_b32_e32 v99, 0xffff0000, v99
	v_pk_mul_f32 v[102:103], v[102:103], v[108:109]
	v_pk_mul_f32 v[108:109], v[30:31], v[142:143]
	v_pk_fma_f32 v[110:111], v[48:49], v[98:99], v[110:111]
	v_pk_fma_f32 v[108:109], v[18:19], v[138:139], v[108:109]
	v_and_b32_e32 v133, 0xffff0000, v104
	v_pk_add_f32 v[110:111], v[110:111], v[56:57]
	v_pk_fma_f32 v[108:109], v[22:23], v[132:133], v[108:109]
	v_pk_mul_f32 v[102:103], v[110:111], v[102:103]
	v_pk_add_f32 v[108:109], v[108:109], v[26:27]
	v_pk_mul_f32 v[110:111], v[6:7], v[122:123]
	v_mul_f32_e32 v104, 0x3d372713, v108
	v_pk_fma_f32 v[118:119], v[2:3], v[118:119], v[110:111]
	v_lshlrev_b32_e32 v110, 16, v100
	v_and_b32_e32 v111, 0xffff0000, v100
	v_mul_f32_e32 v100, 0x3d372713, v109
	v_mul_f32_e32 v104, v108, v104
	v_mul_f32_e32 v100, v109, v100
	v_fma_f32 v104, v108, v104, v108
	v_fma_f32 v100, v109, v100, v109
	v_mul_f32_e32 v104, 0x3f4c422a, v104
	v_mul_f32_e32 v100, 0x3f4c422a, v100
	v_add_f32_e32 v104, v104, v104
	v_add_f32_e32 v100, v100, v100
	v_mul_f32_e32 v104, 0xbfb8aa3b, v104
	v_mul_f32_e32 v100, 0xbfb8aa3b, v100
	v_exp_f32_e32 v104, v104
	v_exp_f32_e32 v100, v100
	v_pk_fma_f32 v[118:119], v[10:11], v[110:111], v[118:119]
	v_lshlrev_b32_e32 v136, 16, v94
	v_add_f32_e32 v104, 1.0, v104
	v_add_f32_e32 v100, 1.0, v100
	v_rcp_f32_e32 v114, v104
	v_rcp_f32_e32 v115, v100
	v_pk_add_f32 v[118:119], v[118:119], v[14:15]
	v_and_b32_e32 v137, 0xffff0000, v94
	v_pk_mul_f32 v[108:109], v[108:109], v[114:115]
	s_nop 0
	v_pk_mul_f32 v[114:115], v[118:119], v[108:109]
	v_pk_mul_f32 v[108:109], v[32:33], v[140:141]
	v_lshlrev_b32_e32 v118, 16, v96
	v_pk_fma_f32 v[108:109], v[20:21], v[128:129], v[108:109]
	v_lshlrev_b32_e32 v128, 16, v105
	v_and_b32_e32 v129, 0xffff0000, v105
	v_pk_fma_f32 v[104:105], v[24:25], v[128:129], v[108:109]
	v_pk_mul_f32 v[108:109], v[8:9], v[120:121]
	v_pk_add_f32 v[104:105], v[104:105], v[28:29]
	v_pk_fma_f32 v[116:117], v[4:5], v[116:117], v[108:109]
	v_mul_f32_e32 v100, 0x3d372713, v104
	v_lshlrev_b32_e32 v108, 16, v101
	v_and_b32_e32 v109, 0xffff0000, v101
	v_mul_f32_e32 v101, 0x3d372713, v105
	v_mul_f32_e32 v100, v104, v100
	v_mul_f32_e32 v101, v105, v101
	v_fma_f32 v100, v104, v100, v104
	v_fma_f32 v101, v105, v101, v105
	v_mul_f32_e32 v100, 0x3f4c422a, v100
	v_mul_f32_e32 v101, 0x3f4c422a, v101
	v_add_f32_e32 v100, v100, v100
	v_add_f32_e32 v101, v101, v101
	v_mul_f32_e32 v100, 0xbfb8aa3b, v100
	v_mul_f32_e32 v101, 0xbfb8aa3b, v101
	v_exp_f32_e32 v100, v100
	v_exp_f32_e32 v101, v101
	v_pk_fma_f32 v[116:117], v[12:13], v[108:109], v[116:117]
	v_and_b32_e32 v119, 0xffff0000, v96
	v_add_f32_e32 v100, 1.0, v100
	v_add_f32_e32 v101, 1.0, v101
	v_rcp_f32_e32 v100, v100
	v_rcp_f32_e32 v101, v101
	v_pk_add_f32 v[116:117], v[116:117], v[16:17]
	v_pk_mul_f32 v[100:101], v[104:105], v[100:101]
	s_nop 0
	v_pk_mul_f32 v[104:105], v[116:117], v[100:101]
	v_cvt_pk_bf16_f32 v100, v106, v107
	v_cvt_pk_bf16_f32 v101, v102, v103
; __device__ __forceinline__ unsigned cvtpk(float lo, float hi) { f32x2 v = {lo, hi}; bf16x2_t b = __builtin_convertvector(v, bf16x2_t); return __builtin_bit_cast(unsigned, b); }
; __device__ __forceinline__ float gelu_tanh(float x) { const float u = 0.7978845608028654f * (x + 0.044715f * x * x * x); return x * sigmoidf_(2.0f * u); }
; __device__ __forceinline__ void st16_wt(void* p, u32x4 v) { asm volatile("global_store_dwordx4 %0, %1, off sc1\n\ts_nop 2" :: "v"(p), "v"(v) : "memory"); }
; __device__ __forceinline__ float bfe(const u32x4& w, int e) { return (e & 1) ? __builtin_bit_cast(float, w[e >> 1] & 0xffff0000u) : __builtin_bit_cast(float, w[e >> 1] << 16); }
; __device__ __forceinline__ void conv_pass(const bf16_t* __restrict__ U, const float* __restrict__ cw, const float* __restrict__ cb, bf16_t* __restrict__ GA, int tg, int wv) {
;     ...
; #pragma unroll
;         for (int i = 0; i < RUN; ++i) {
;             float o[8];
; #pragma unroll
;             for (int e = 0; e < 8; ++e) {
;                 const float ua = bfe(ra[i], e) * wa[0][e >> 2][e & 3] + bfe(ra[i + 1], e) * wa[1][e >> 2][e & 3] + bfe(ra[i + 2], e) * wa[2][e >> 2][e & 3] + ba[e >> 2][e & 3];
;                 const float ub = bfe(rb[i], e) * wb[0][e >> 2][e & 3] + bfe(rb[i + 1], e) * wb[1][e >> 2][e & 3] + bfe(rb[i + 2], e) * wb[2][e >> 2][e & 3] + bb[e >> 2][e & 3];
;                 o[e] = gelu_tanh(ua) * ub;
;             }
;             u32x4 w; w.x = cvtpk(o[0], o[1]); w.y = cvtpk(o[2], o[3]); w.z = cvtpk(o[4], o[5]); w.w = cvtpk(o[6], o[7]);
;             st16_wt(GA + (size_t)(t0 + i) * DFF + c0, w);
	v_cvt_pk_bf16_f32 v102, v114, v115
	v_cvt_pk_bf16_f32 v103, v104, v105
	v_mad_i64_i32 v[104:105], s[0:1], v168, s91, v[130:131]
	global_store_dwordx4 v[104:105], v[100:103], off sc1 nt
	s_nop 2
	v_pk_mul_f32 v[100:101], v[50:51], v[146:147]
	v_lshlrev_b32_e32 v106, 16, v90
	v_pk_fma_f32 v[100:101], v[38:39], v[148:149], v[100:101]
	v_and_b32_e32 v107, 0xffff0000, v90
	v_pk_fma_f32 v[100:101], v[58:59], v[136:137], v[100:101]
	v_pk_mul_f32 v[104:105], v[42:43], v[112:113]
	v_pk_add_f32 v[100:101], v[100:101], v[62:63]
	v_pk_fma_f32 v[104:105], v[34:35], v[126:127], v[104:105]
	v_mul_f32_e32 v94, 0x3d372713, v100
	v_mul_f32_e32 v90, 0x3d372713, v101
	v_mul_f32_e32 v94, v100, v94
	v_mul_f32_e32 v90, v101, v90
	v_fma_f32 v94, v100, v94, v100
	v_fma_f32 v90, v101, v90, v101
	v_mul_f32_e32 v94, 0x3f4c422a, v94
	v_mul_f32_e32 v90, 0x3f4c422a, v90
	v_add_f32_e32 v94, v94, v94
	v_add_f32_e32 v90, v90, v90
	v_mul_f32_e32 v94, 0xbfb8aa3b, v94
	v_mul_f32_e32 v90, 0xbfb8aa3b, v90
	v_exp_f32_e32 v94, v94
	v_exp_f32_e32 v90, v90
	v_lshlrev_b32_e32 v126, 16, v95
	v_and_b32_e32 v127, 0xffff0000, v95
	v_add_f32_e32 v94, 1.0, v94
	v_add_f32_e32 v90, 1.0, v90
	v_rcp_f32_e32 v102, v94
	v_rcp_f32_e32 v103, v90
	v_pk_fma_f32 v[104:105], v[46:47], v[106:107], v[104:105]
	v_pk_mul_f32 v[100:101], v[100:101], v[102:103]
	v_pk_mul_f32 v[102:103], v[52:53], v[134:135]
	v_pk_add_f32 v[104:105], v[104:105], v[54:55]
	v_pk_fma_f32 v[102:103], v[40:41], v[144:145], v[102:103]
	v_pk_mul_f32 v[100:101], v[104:105], v[100:101]
	v_pk_fma_f32 v[94:95], v[60:61], v[126:127], v[102:103]
	v_lshlrev_b32_e32 v104, 16, v91
	v_pk_add_f32 v[94:95], v[94:95], v[64:65]
	v_and_b32_e32 v105, 0xffff0000, v91
	v_mul_f32_e32 v90, 0x3d372713, v94
	v_mul_f32_e32 v91, 0x3d372713, v95
	v_mul_f32_e32 v90, v94, v90
	v_mul_f32_e32 v91, v95, v91
	v_fma_f32 v90, v94, v90, v94
	v_fma_f32 v91, v95, v91, v95
	v_mul_f32_e32 v90, 0x3f4c422a, v90
	v_mul_f32_e32 v91, 0x3f4c422a, v91
	v_add_f32_e32 v90, v90, v90
	v_add_f32_e32 v91, v91, v91
	v_mul_f32_e32 v90, 0xbfb8aa3b, v90
	v_mul_f32_e32 v91, 0xbfb8aa3b, v91
	v_exp_f32_e32 v90, v90
	v_exp_f32_e32 v91, v91
	v_pk_mul_f32 v[102:103], v[44:45], v[98:99]
	v_add_f32_e32 v90, 1.0, v90
	v_add_f32_e32 v91, 1.0, v91
	v_rcp_f32_e32 v90, v90
	v_rcp_f32_e32 v91, v91
	v_pk_fma_f32 v[102:103], v[36:37], v[124:125], v[102:103]
	v_pk_mul_f32 v[90:91], v[94:95], v[90:91]
	v_pk_fma_f32 v[102:103], v[48:49], v[104:105], v[102:103]
	s_nop 0
	v_pk_add_f32 v[102:103], v[102:103], v[56:57]
	s_nop 0
	v_pk_mul_f32 v[94:95], v[102:103], v[90:91]
	v_pk_mul_f32 v[90:91], v[30:31], v[132:133]
	s_nop 0
	v_pk_fma_f32 v[90:91], v[18:19], v[142:143], v[90:91]
	s_nop 0
	v_pk_fma_f32 v[90:91], v[22:23], v[118:119], v[90:91]
	s_nop 0
	v_pk_add_f32 v[102:103], v[90:91], v[26:27]
	s_nop 0
	v_mul_f32_e32 v90, 0x3d372713, v102
	v_mul_f32_e32 v90, v102, v90
	v_fma_f32 v90, v102, v90, v102
	v_mul_f32_e32 v90, 0x3f4c422a, v90
	v_add_f32_e32 v90, v90, v90
	v_mul_f32_e32 v90, 0xbfb8aa3b, v90
	v_exp_f32_e32 v90, v90
	s_nop 0
	v_add_f32_e32 v90, 1.0, v90
	v_rcp_f32_e32 v114, v90
	v_pk_mul_f32 v[90:91], v[6:7], v[110:111]
	s_nop 0
	v_pk_fma_f32 v[116:117], v[2:3], v[122:123], v[90:91]
	v_lshlrev_b32_e32 v90, 16, v92
	v_and_b32_e32 v91, 0xffff0000, v92
	v_mul_f32_e32 v92, 0x3d372713, v103
	v_mul_f32_e32 v92, v103, v92
	v_fma_f32 v92, v103, v92, v103
	v_mul_f32_e32 v92, 0x3f4c422a, v92
	v_add_f32_e32 v92, v92, v92
	v_mul_f32_e32 v92, 0xbfb8aa3b, v92
	v_exp_f32_e32 v92, v92
	v_pk_fma_f32 v[116:117], v[10:11], v[90:91], v[116:117]
	v_add_f32_e32 v92, 1.0, v92
	v_rcp_f32_e32 v115, v92
	v_pk_add_f32 v[116:117], v[116:117], v[14:15]
	v_pk_mul_f32 v[102:103], v[102:103], v[114:115]
	s_nop 0
	v_pk_mul_f32 v[114:115], v[116:117], v[102:103]
	v_pk_mul_f32 v[102:103], v[32:33], v[128:129]
	v_lshlrev_b32_e32 v116, 16, v97
	v_pk_fma_f32 v[102:103], v[20:21], v[140:141], v[102:103]
	v_and_b32_e32 v117, 0xffff0000, v97
	v_pk_fma_f32 v[96:97], v[24:25], v[116:117], v[102:103]
	v_pk_mul_f32 v[102:103], v[8:9], v[108:109]
	v_pk_add_f32 v[96:97], v[96:97], v[28:29]
	v_pk_fma_f32 v[120:121], v[4:5], v[120:121], v[102:103]
	v_mul_f32_e32 v92, 0x3d372713, v96
	v_lshlrev_b32_e32 v102, 16, v93
	v_and_b32_e32 v103, 0xffff0000, v93
	v_mul_f32_e32 v93, 0x3d372713, v97
	v_mul_f32_e32 v92, v96, v92
	v_mul_f32_e32 v93, v97, v93
	v_fma_f32 v92, v96, v92, v96
	v_fma_f32 v93, v97, v93, v97
	v_mul_f32_e32 v92, 0x3f4c422a, v92
	v_mul_f32_e32 v93, 0x3f4c422a, v93
	v_add_f32_e32 v92, v92, v92
	v_add_f32_e32 v93, v93, v93
	v_mul_f32_e32 v92, 0xbfb8aa3b, v92
	v_mul_f32_e32 v93, 0xbfb8aa3b, v93
	v_exp_f32_e32 v92, v92
	v_exp_f32_e32 v93, v93
	v_pk_fma_f32 v[120:121], v[12:13], v[102:103], v[120:121]
	v_add_f32_e32 v92, 1.0, v92
	v_add_f32_e32 v93, 1.0, v93
	v_rcp_f32_e32 v92, v92
	v_rcp_f32_e32 v93, v93
	v_pk_add_f32 v[120:121], v[120:121], v[16:17]
	v_pk_mul_f32 v[92:93], v[96:97], v[92:93]
	s_nop 0
	v_pk_mul_f32 v[96:97], v[120:121], v[92:93]
	v_cvt_pk_bf16_f32 v92, v100, v101
	v_cvt_pk_bf16_f32 v93, v94, v95
	v_cvt_pk_bf16_f32 v94, v114, v115
	v_cvt_pk_bf16_f32 v95, v96, v97
	v_mad_i64_i32 v[96:97], s[0:1], v167, s91, v[130:131]
	global_store_dwordx4 v[96:97], v[92:95], off sc1 nt
	s_nop 2
	v_pk_mul_f32 v[92:93], v[50:51], v[136:137]
	v_lshlrev_b32_e32 v120, 16, v86
	v_pk_fma_f32 v[92:93], v[38:39], v[146:147], v[92:93]
	v_and_b32_e32 v121, 0xffff0000, v86
	v_pk_fma_f32 v[92:93], v[58:59], v[120:121], v[92:93]
	v_lshlrev_b32_e32 v100, 16, v82
	v_pk_add_f32 v[92:93], v[92:93], v[62:63]
	v_and_b32_e32 v101, 0xffff0000, v82
	v_mul_f32_e32 v86, 0x3d372713, v92
	v_mul_f32_e32 v82, 0x3d372713, v93
	v_mul_f32_e32 v86, v92, v86
; __device__ __forceinline__ unsigned cvtpk(float lo, float hi) { f32x2 v = {lo, hi}; bf16x2_t b = __builtin_convertvector(v, bf16x2_t); return __builtin_bit_cast(unsigned, b); }
; __device__ __forceinline__ float gelu_tanh(float x) { const float u = 0.7978845608028654f * (x + 0.044715f * x * x * x); return x * sigmoidf_(2.0f * u); }
; __device__ __forceinline__ void st16_wt(void* p, u32x4 v) { asm volatile("global_store_dwordx4 %0, %1, off sc1\n\ts_nop 2" :: "v"(p), "v"(v) : "memory"); }
; __device__ __forceinline__ float bfe(const u32x4& w, int e) { return (e & 1) ? __builtin_bit_cast(float, w[e >> 1] & 0xffff0000u) : __builtin_bit_cast(float, w[e >> 1] << 16); }
; __device__ __forceinline__ void conv_pass(const bf16_t* __restrict__ U, const float* __restrict__ cw, const float* __restrict__ cb, bf16_t* __restrict__ GA, int tg, int wv) {
;     ...
; #pragma unroll
;         for (int i = 0; i < RUN; ++i) {
;             float o[8];
; #pragma unroll
;             for (int e = 0; e < 8; ++e) {
;                 const float ua = bfe(ra[i], e) * wa[0][e >> 2][e & 3] + bfe(ra[i + 1], e) * wa[1][e >> 2][e & 3] + bfe(ra[i + 2], e) * wa[2][e >> 2][e & 3] + ba[e >> 2][e & 3];
;                 const float ub = bfe(rb[i], e) * wb[0][e >> 2][e & 3] + bfe(rb[i + 1], e) * wb[1][e >> 2][e & 3] + bfe(rb[i + 2], e) * wb[2][e >> 2][e & 3] + bb[e >> 2][e & 3];
;                 o[e] = gelu_tanh(ua) * ub;
;             }
;             u32x4 w; w.x = cvtpk(o[0], o[1]); w.y = cvtpk(o[2], o[3]); w.z = cvtpk(o[4], o[5]); w.w = cvtpk(o[6], o[7]);
;             st16_wt(GA + (size_t)(t0 + i) * DFF + c0, w);
	v_mul_f32_e32 v82, v93, v82
	v_fma_f32 v86, v92, v86, v92
	v_fma_f32 v82, v93, v82, v93
	v_mul_f32_e32 v86, 0x3f4c422a, v86
	v_mul_f32_e32 v82, 0x3f4c422a, v82
	v_add_f32_e32 v86, v86, v86
	v_add_f32_e32 v82, v82, v82
	v_mul_f32_e32 v86, 0xbfb8aa3b, v86
	v_mul_f32_e32 v82, 0xbfb8aa3b, v82
	v_exp_f32_e32 v86, v86
	v_exp_f32_e32 v82, v82
	v_lshlrev_b32_e32 v114, 16, v87
	v_and_b32_e32 v115, 0xffff0000, v87
	v_add_f32_e32 v86, 1.0, v86
	v_add_f32_e32 v82, 1.0, v82
	v_rcp_f32_e32 v94, v86
	v_rcp_f32_e32 v95, v82
	v_pk_mul_f32 v[96:97], v[42:43], v[106:107]
	v_pk_mul_f32 v[92:93], v[92:93], v[94:95]
	v_pk_mul_f32 v[94:95], v[52:53], v[126:127]
	v_pk_fma_f32 v[96:97], v[34:35], v[112:113], v[96:97]
	v_pk_fma_f32 v[94:95], v[40:41], v[134:135], v[94:95]
	v_pk_fma_f32 v[96:97], v[46:47], v[100:101], v[96:97]
	v_pk_fma_f32 v[86:87], v[60:61], v[114:115], v[94:95]
	v_pk_mul_f32 v[94:95], v[44:45], v[104:105]
	v_pk_add_f32 v[86:87], v[86:87], v[64:65]
	v_pk_fma_f32 v[94:95], v[36:37], v[98:99], v[94:95]
	v_mul_f32_e32 v82, 0x3d372713, v86
	v_lshlrev_b32_e32 v98, 16, v83
	v_and_b32_e32 v99, 0xffff0000, v83
	v_mul_f32_e32 v83, 0x3d372713, v87
	v_mul_f32_e32 v82, v86, v82
	v_mul_f32_e32 v83, v87, v83
	v_fma_f32 v82, v86, v82, v86
	v_fma_f32 v83, v87, v83, v87
	v_mul_f32_e32 v82, 0x3f4c422a, v82
	v_mul_f32_e32 v83, 0x3f4c422a, v83
	v_add_f32_e32 v82, v82, v82
	v_add_f32_e32 v83, v83, v83
	v_mul_f32_e32 v82, 0xbfb8aa3b, v82
	v_mul_f32_e32 v83, 0xbfb8aa3b, v83
	v_exp_f32_e32 v82, v82
	v_exp_f32_e32 v83, v83
	v_pk_fma_f32 v[94:95], v[48:49], v[98:99], v[94:95]
	v_lshlrev_b32_e32 v112, 16, v88
	v_add_f32_e32 v82, 1.0, v82
	v_add_f32_e32 v83, 1.0, v83
	v_rcp_f32_e32 v82, v82
	v_rcp_f32_e32 v83, v83
	v_pk_add_f32 v[94:95], v[94:95], v[56:57]
	v_and_b32_e32 v113, 0xffff0000, v88
	v_pk_add_f32 v[96:97], v[96:97], v[54:55]
	v_pk_mul_f32 v[82:83], v[86:87], v[82:83]
	v_pk_mul_f32 v[92:93], v[96:97], v[92:93]
	v_pk_mul_f32 v[86:87], v[94:95], v[82:83]
	v_pk_mul_f32 v[82:83], v[30:31], v[118:119]
	v_pk_mul_f32 v[96:97], v[6:7], v[90:91]
	v_pk_fma_f32 v[82:83], v[18:19], v[132:133], v[82:83]
	v_pk_fma_f32 v[110:111], v[2:3], v[110:111], v[96:97]
	v_pk_fma_f32 v[82:83], v[22:23], v[112:113], v[82:83]
	v_lshlrev_b32_e32 v96, 16, v84
	v_pk_add_f32 v[82:83], v[82:83], v[26:27]
	v_and_b32_e32 v97, 0xffff0000, v84
	v_mul_f32_e32 v88, 0x3d372713, v82
	v_mul_f32_e32 v84, 0x3d372713, v83
	v_mul_f32_e32 v88, v82, v88
	v_mul_f32_e32 v84, v83, v84
	v_fma_f32 v88, v82, v88, v82
	v_fma_f32 v84, v83, v84, v83
	v_mul_f32_e32 v88, 0x3f4c422a, v88
	v_mul_f32_e32 v84, 0x3f4c422a, v84
	v_add_f32_e32 v88, v88, v88
	v_add_f32_e32 v84, v84, v84
	v_mul_f32_e32 v88, 0xbfb8aa3b, v88
	v_mul_f32_e32 v84, 0xbfb8aa3b, v84
	v_exp_f32_e32 v88, v88
	v_exp_f32_e32 v84, v84
	v_pk_fma_f32 v[110:111], v[10:11], v[96:97], v[110:111]
	v_add_f32_e32 v88, 1.0, v88
	v_add_f32_e32 v84, 1.0, v84
	v_rcp_f32_e32 v94, v88
	v_rcp_f32_e32 v95, v84
	v_pk_add_f32 v[110:111], v[110:111], v[14:15]
	v_pk_mul_f32 v[82:83], v[82:83], v[94:95]
	s_nop 0
	v_pk_mul_f32 v[122:123], v[110:111], v[82:83]
	v_pk_mul_f32 v[82:83], v[32:33], v[116:117]
	v_lshlrev_b32_e32 v110, 16, v89
	v_pk_fma_f32 v[82:83], v[20:21], v[128:129], v[82:83]
	v_and_b32_e32 v111, 0xffff0000, v89
	v_pk_fma_f32 v[82:83], v[24:25], v[110:111], v[82:83]
	v_lshlrev_b32_e32 v94, 16, v85
	v_pk_add_f32 v[82:83], v[82:83], v[28:29]
	v_and_b32_e32 v95, 0xffff0000, v85
	v_mul_f32_e32 v84, 0x3d372713, v82
	v_mul_f32_e32 v85, 0x3d372713, v83
	v_mul_f32_e32 v84, v82, v84
	v_mul_f32_e32 v85, v83, v85
	v_fma_f32 v84, v82, v84, v82
	v_fma_f32 v85, v83, v85, v83
	v_mul_f32_e32 v84, 0x3f4c422a, v84
	v_mul_f32_e32 v85, 0x3f4c422a, v85
	v_add_f32_e32 v84, v84, v84
	v_add_f32_e32 v85, v85, v85
	v_mul_f32_e32 v84, 0xbfb8aa3b, v84
	v_mul_f32_e32 v85, 0xbfb8aa3b, v85
	v_exp_f32_e32 v84, v84
	v_exp_f32_e32 v85, v85
	v_pk_mul_f32 v[88:89], v[8:9], v[102:103]
	v_add_f32_e32 v84, 1.0, v84
	v_add_f32_e32 v85, 1.0, v85
	v_rcp_f32_e32 v84, v84
	v_rcp_f32_e32 v85, v85
	v_pk_fma_f32 v[88:89], v[4:5], v[108:109], v[88:89]
	v_pk_mul_f32 v[108:109], v[6:7], v[96:97]
	v_pk_fma_f32 v[88:89], v[12:13], v[94:95], v[88:89]
	v_pk_mul_f32 v[82:83], v[82:83], v[84:85]
	v_pk_add_f32 v[88:89], v[88:89], v[16:17]
	v_cvt_pk_bf16_f32 v84, v122, v123
	v_pk_mul_f32 v[88:89], v[88:89], v[82:83]
	v_cvt_pk_bf16_f32 v82, v92, v93
	v_cvt_pk_bf16_f32 v83, v86, v87
	v_cvt_pk_bf16_f32 v85, v88, v89
	v_mad_i64_i32 v[86:87], s[0:1], v166, s91, v[130:131]
	global_store_dwordx4 v[86:87], v[82:85], off sc1 nt
	s_nop 2
	v_pk_mul_f32 v[82:83], v[50:51], v[120:121]
	v_lshlrev_b32_e32 v86, 16, v78
	v_pk_fma_f32 v[82:83], v[38:39], v[136:137], v[82:83]
	v_and_b32_e32 v87, 0xffff0000, v78
	v_pk_fma_f32 v[82:83], v[58:59], v[86:87], v[82:83]
	v_pk_fma_f32 v[108:109], v[2:3], v[90:91], v[108:109]
	v_pk_add_f32 v[84:85], v[82:83], v[62:63]
	v_pk_mul_f32 v[82:83], v[42:43], v[100:101]
	v_mul_f32_e32 v78, 0x3d372713, v84
	v_pk_fma_f32 v[92:93], v[34:35], v[106:107], v[82:83]
	v_lshlrev_b32_e32 v82, 16, v74
	v_and_b32_e32 v83, 0xffff0000, v74
	v_mul_f32_e32 v74, 0x3d372713, v85
	v_mul_f32_e32 v78, v84, v78
	v_mul_f32_e32 v74, v85, v74
	v_fma_f32 v78, v84, v78, v84
	v_fma_f32 v74, v85, v74, v85
	v_mul_f32_e32 v78, 0x3f4c422a, v78
	v_mul_f32_e32 v74, 0x3f4c422a, v74
	v_add_f32_e32 v78, v78, v78
	v_add_f32_e32 v74, v74, v74
	v_mul_f32_e32 v78, 0xbfb8aa3b, v78
	v_mul_f32_e32 v74, 0xbfb8aa3b, v74
	v_exp_f32_e32 v78, v78
	v_exp_f32_e32 v74, v74
	v_pk_fma_f32 v[92:93], v[46:47], v[82:83], v[92:93]
	v_lshlrev_b32_e32 v90, 16, v76
	v_add_f32_e32 v78, 1.0, v78
	v_add_f32_e32 v74, 1.0, v74
	v_rcp_f32_e32 v88, v78
	v_rcp_f32_e32 v89, v74
; __device__ __forceinline__ unsigned cvtpk(float lo, float hi) { f32x2 v = {lo, hi}; bf16x2_t b = __builtin_convertvector(v, bf16x2_t); return __builtin_bit_cast(unsigned, b); }
; __device__ __forceinline__ float gelu_tanh(float x) { const float u = 0.7978845608028654f * (x + 0.044715f * x * x * x); return x * sigmoidf_(2.0f * u); }
; __device__ __forceinline__ void st16_wt(void* p, u32x4 v) { asm volatile("global_store_dwordx4 %0, %1, off sc1\n\ts_nop 2" :: "v"(p), "v"(v) : "memory"); }
; __device__ __forceinline__ float bfe(const u32x4& w, int e) { return (e & 1) ? __builtin_bit_cast(float, w[e >> 1] & 0xffff0000u) : __builtin_bit_cast(float, w[e >> 1] << 16); }
; __device__ __forceinline__ void conv_pass(const bf16_t* __restrict__ U, const float* __restrict__ cw, const float* __restrict__ cb, bf16_t* __restrict__ GA, int tg, int wv) {
;     ...
; #pragma unroll
;         for (int i = 0; i < RUN; ++i) {
;             float o[8];
; #pragma unroll
;             for (int e = 0; e < 8; ++e) {
;                 const float ua = bfe(ra[i], e) * wa[0][e >> 2][e & 3] + bfe(ra[i + 1], e) * wa[1][e >> 2][e & 3] + bfe(ra[i + 2], e) * wa[2][e >> 2][e & 3] + ba[e >> 2][e & 3];
;                 const float ub = bfe(rb[i], e) * wb[0][e >> 2][e & 3] + bfe(rb[i + 1], e) * wb[1][e >> 2][e & 3] + bfe(rb[i + 2], e) * wb[2][e >> 2][e & 3] + bb[e >> 2][e & 3];
;                 o[e] = gelu_tanh(ua) * ub;
;             }
;             u32x4 w; w.x = cvtpk(o[0], o[1]); w.y = cvtpk(o[2], o[3]); w.z = cvtpk(o[4], o[5]); w.w = cvtpk(o[6], o[7]);
;             st16_wt(GA + (size_t)(t0 + i) * DFF + c0, w);
	v_pk_add_f32 v[92:93], v[92:93], v[54:55]
	v_and_b32_e32 v91, 0xffff0000, v76
	v_pk_fma_f32 v[108:109], v[10:11], v[90:91], v[108:109]
	v_pk_mul_f32 v[84:85], v[84:85], v[88:89]
	v_lshlrev_b32_e32 v88, 16, v79
	v_pk_mul_f32 v[106:107], v[92:93], v[84:85]
	v_pk_mul_f32 v[84:85], v[52:53], v[114:115]
	v_and_b32_e32 v89, 0xffff0000, v79
	v_pk_fma_f32 v[84:85], v[40:41], v[126:127], v[84:85]
	v_pk_add_f32 v[108:109], v[108:109], v[14:15]
	v_pk_fma_f32 v[78:79], v[60:61], v[88:89], v[84:85]
	v_pk_mul_f32 v[84:85], v[44:45], v[98:99]
	v_pk_add_f32 v[78:79], v[78:79], v[64:65]
	v_pk_fma_f32 v[92:93], v[36:37], v[104:105], v[84:85]
	v_mul_f32_e32 v74, 0x3d372713, v78
	v_lshlrev_b32_e32 v84, 16, v75
	v_and_b32_e32 v85, 0xffff0000, v75
	v_mul_f32_e32 v75, 0x3d372713, v79
	v_mul_f32_e32 v74, v78, v74
	v_mul_f32_e32 v75, v79, v75
	v_fma_f32 v74, v78, v74, v78
	v_fma_f32 v75, v79, v75, v79
	v_mul_f32_e32 v74, 0x3f4c422a, v74
	v_mul_f32_e32 v75, 0x3f4c422a, v75
	v_add_f32_e32 v74, v74, v74
	v_add_f32_e32 v75, v75, v75
	v_mul_f32_e32 v74, 0xbfb8aa3b, v74
	v_mul_f32_e32 v75, 0xbfb8aa3b, v75
	v_exp_f32_e32 v74, v74
	v_exp_f32_e32 v75, v75
	v_pk_fma_f32 v[92:93], v[48:49], v[84:85], v[92:93]
	v_add_f32_e32 v74, 1.0, v74
	v_add_f32_e32 v75, 1.0, v75
	v_rcp_f32_e32 v74, v74
	v_rcp_f32_e32 v75, v75
	v_pk_add_f32 v[92:93], v[92:93], v[56:57]
	v_pk_mul_f32 v[74:75], v[78:79], v[74:75]
	s_nop 0
	v_pk_mul_f32 v[104:105], v[92:93], v[74:75]
	v_pk_mul_f32 v[74:75], v[30:31], v[112:113]
	v_lshlrev_b32_e32 v92, 16, v80
	v_pk_fma_f32 v[74:75], v[18:19], v[118:119], v[74:75]
	v_and_b32_e32 v93, 0xffff0000, v80
	v_pk_fma_f32 v[74:75], v[22:23], v[92:93], v[74:75]
	s_nop 0
	v_pk_add_f32 v[74:75], v[74:75], v[26:27]
	s_nop 0
	v_mul_f32_e32 v78, 0x3d372713, v74
	v_mul_f32_e32 v76, 0x3d372713, v75
	v_mul_f32_e32 v78, v74, v78
	v_mul_f32_e32 v76, v75, v76
	v_fma_f32 v78, v74, v78, v74
	v_fma_f32 v76, v75, v76, v75
	v_mul_f32_e32 v78, 0x3f4c422a, v78
	v_mul_f32_e32 v76, 0x3f4c422a, v76
	v_add_f32_e32 v78, v78, v78
	v_add_f32_e32 v76, v76, v76
	v_mul_f32_e32 v78, 0xbfb8aa3b, v78
	v_mul_f32_e32 v76, 0xbfb8aa3b, v76
	v_exp_f32_e32 v78, v78
	v_exp_f32_e32 v76, v76
	v_add_f32_e32 v78, 1.0, v78
	v_add_f32_e32 v76, 1.0, v76
	v_rcp_f32_e32 v78, v78
	v_rcp_f32_e32 v79, v76
	s_nop 0
	v_pk_mul_f32 v[74:75], v[74:75], v[78:79]
	s_nop 0
	v_pk_mul_f32 v[108:109], v[108:109], v[74:75]
	v_pk_mul_f32 v[74:75], v[32:33], v[110:111]
	v_lshlrev_b32_e32 v78, 16, v81
	v_pk_fma_f32 v[74:75], v[20:21], v[116:117], v[74:75]
	v_and_b32_e32 v79, 0xffff0000, v81
	v_pk_fma_f32 v[74:75], v[24:25], v[78:79], v[74:75]
	s_nop 0
	v_pk_add_f32 v[80:81], v[74:75], v[28:29]
	s_nop 0
	v_mul_f32_e32 v74, 0x3d372713, v80
	v_mul_f32_e32 v74, v80, v74
	v_fma_f32 v74, v80, v74, v80
	v_mul_f32_e32 v74, 0x3f4c422a, v74
	v_add_f32_e32 v74, v74, v74
	v_mul_f32_e32 v74, 0xbfb8aa3b, v74
	v_exp_f32_e32 v74, v74
	s_nop 0
	v_add_f32_e32 v74, 1.0, v74
	v_rcp_f32_e32 v76, v74
	v_pk_mul_f32 v[74:75], v[8:9], v[94:95]
	s_nop 0
	v_pk_fma_f32 v[102:103], v[4:5], v[102:103], v[74:75]
	v_lshlrev_b32_e32 v74, 16, v77
	v_and_b32_e32 v75, 0xffff0000, v77
	v_mul_f32_e32 v77, 0x3d372713, v81
	v_mul_f32_e32 v77, v81, v77
	v_fma_f32 v77, v81, v77, v81
	v_mul_f32_e32 v77, 0x3f4c422a, v77
	v_add_f32_e32 v77, v77, v77
	v_mul_f32_e32 v77, 0xbfb8aa3b, v77
	v_exp_f32_e32 v77, v77
	v_pk_fma_f32 v[102:103], v[12:13], v[74:75], v[102:103]
	v_add_f32_e32 v77, 1.0, v77
	v_rcp_f32_e32 v77, v77
	v_pk_add_f32 v[102:103], v[102:103], v[16:17]
	v_pk_mul_f32 v[76:77], v[80:81], v[76:77]
	s_nop 0
	v_pk_mul_f32 v[76:77], v[102:103], v[76:77]
	v_cvt_pk_bf16_f32 v103, v104, v105
	v_cvt_pk_bf16_f32 v105, v76, v77
	v_mad_i64_i32 v[76:77], s[0:1], v165, s91, v[130:131]
	v_cvt_pk_bf16_f32 v102, v106, v107
	v_cvt_pk_bf16_f32 v104, v108, v109
	global_store_dwordx4 v[76:77], v[102:105], off sc1 nt
	s_nop 2
	v_pk_mul_f32 v[76:77], v[50:51], v[86:87]
	v_lshlrev_b32_e32 v80, 16, v70
	v_pk_fma_f32 v[76:77], v[38:39], v[120:121], v[76:77]
	v_and_b32_e32 v81, 0xffff0000, v70
	v_pk_fma_f32 v[76:77], v[58:59], v[80:81], v[76:77]
	v_pk_mul_f32 v[106:107], v[44:45], v[84:85]
	v_pk_add_f32 v[102:103], v[76:77], v[62:63]
	v_pk_mul_f32 v[76:77], v[42:43], v[82:83]
	v_mul_f32_e32 v70, 0x3d372713, v102
	v_pk_fma_f32 v[100:101], v[34:35], v[100:101], v[76:77]
	v_lshlrev_b32_e32 v76, 16, v66
	v_and_b32_e32 v77, 0xffff0000, v66
	v_mul_f32_e32 v66, 0x3d372713, v103
	v_mul_f32_e32 v70, v102, v70
	v_mul_f32_e32 v66, v103, v66
	v_fma_f32 v70, v102, v70, v102
	v_fma_f32 v66, v103, v66, v103
	v_mul_f32_e32 v70, 0x3f4c422a, v70
	v_mul_f32_e32 v66, 0x3f4c422a, v66
	v_add_f32_e32 v70, v70, v70
	v_add_f32_e32 v66, v66, v66
	v_mul_f32_e32 v70, 0xbfb8aa3b, v70
	v_mul_f32_e32 v66, 0xbfb8aa3b, v66
	v_exp_f32_e32 v70, v70
	v_exp_f32_e32 v66, v66
	v_pk_fma_f32 v[100:101], v[46:47], v[76:77], v[100:101]
	v_pk_fma_f32 v[98:99], v[36:37], v[98:99], v[106:107]
	v_add_f32_e32 v70, 1.0, v70
	v_add_f32_e32 v66, 1.0, v66
	v_rcp_f32_e32 v104, v70
	v_rcp_f32_e32 v105, v66
	v_pk_add_f32 v[100:101], v[100:101], v[54:55]
	v_pk_mul_f32 v[108:109], v[6:7], v[90:91]
	v_pk_mul_f32 v[50:51], v[50:51], v[80:81]
	v_pk_mul_f32 v[102:103], v[102:103], v[104:105]
	v_pk_fma_f32 v[108:109], v[2:3], v[96:97], v[108:109]
	v_pk_mul_f32 v[102:103], v[100:101], v[102:103]
	v_pk_mul_f32 v[100:101], v[52:53], v[88:89]
	v_lshlrev_b32_e32 v96, 16, v68
	v_pk_fma_f32 v[104:105], v[40:41], v[114:115], v[100:101]
	v_lshlrev_b32_e32 v100, 16, v71
	v_and_b32_e32 v101, 0xffff0000, v71
	v_pk_fma_f32 v[70:71], v[60:61], v[100:101], v[104:105]
	v_and_b32_e32 v97, 0xffff0000, v68
	v_pk_add_f32 v[70:71], v[70:71], v[64:65]
; __device__ __forceinline__ float gelu_tanh(float x) { const float u = 0.7978845608028654f * (x + 0.044715f * x * x * x); return x * sigmoidf_(2.0f * u); }
; __device__ __forceinline__ float bfe(const u32x4& w, int e) { return (e & 1) ? __builtin_bit_cast(float, w[e >> 1] & 0xffff0000u) : __builtin_bit_cast(float, w[e >> 1] << 16); }
; __device__ __forceinline__ void conv_pass(const bf16_t* __restrict__ U, const float* __restrict__ cw, const float* __restrict__ cb, bf16_t* __restrict__ GA, int tg, int wv) {
;     ...
; #pragma unroll
;         for (int i = 0; i < RUN; ++i) {
;             float o[8];
; #pragma unroll
;             for (int e = 0; e < 8; ++e) {
;                 const float ua = bfe(ra[i], e) * wa[0][e >> 2][e & 3] + bfe(ra[i + 1], e) * wa[1][e >> 2][e & 3] + bfe(ra[i + 2], e) * wa[2][e >> 2][e & 3] + ba[e >> 2][e & 3];
;                 const float ub = bfe(rb[i], e) * wb[0][e >> 2][e & 3] + bfe(rb[i + 1], e) * wb[1][e >> 2][e & 3] + bfe(rb[i + 2], e) * wb[2][e >> 2][e & 3] + bb[e >> 2][e & 3];
;                 o[e] = gelu_tanh(ua) * ub;
	v_pk_fma_f32 v[38:39], v[38:39], v[86:87], v[50:51]
	v_mul_f32_e32 v66, 0x3d372713, v70
	v_mul_f32_e32 v105, 0x3d372713, v71
	v_mul_f32_e32 v66, v70, v66
	v_mul_f32_e32 v105, v71, v105
	v_fma_f32 v66, v70, v66, v70
	v_fma_f32 v105, v71, v105, v71
	v_mul_f32_e32 v66, 0x3f4c422a, v66
	v_mul_f32_e32 v105, 0x3f4c422a, v105
	v_add_f32_e32 v66, v66, v66
	v_add_f32_e32 v105, v105, v105
	v_mul_f32_e32 v66, 0xbfb8aa3b, v66
	v_mul_f32_e32 v105, 0xbfb8aa3b, v105
	v_exp_f32_e32 v66, v66
	v_exp_f32_e32 v105, v105
	v_lshlrev_b32_e32 v50, 16, v164
	v_and_b32_e32 v51, 0xffff0000, v164
	v_add_f32_e32 v66, 1.0, v66
	v_add_f32_e32 v105, 1.0, v105
	v_rcp_f32_e32 v104, v66
	v_rcp_f32_e32 v105, v105
	v_lshlrev_b32_e32 v66, 16, v67
	v_and_b32_e32 v67, 0xffff0000, v67
	v_pk_fma_f32 v[98:99], v[48:49], v[66:67], v[98:99]
	v_pk_mul_f32 v[70:71], v[70:71], v[104:105]
	v_pk_add_f32 v[98:99], v[98:99], v[56:57]
	v_pk_fma_f32 v[38:39], v[58:59], v[50:51], v[38:39]
	v_pk_mul_f32 v[104:105], v[98:99], v[70:71]
	v_pk_mul_f32 v[70:71], v[30:31], v[92:93]
	v_lshlrev_b32_e32 v98, 16, v72
	v_pk_fma_f32 v[70:71], v[18:19], v[112:113], v[70:71]
	v_and_b32_e32 v99, 0xffff0000, v72
	v_pk_fma_f32 v[70:71], v[22:23], v[98:99], v[70:71]
	v_pk_mul_f32 v[30:31], v[30:31], v[98:99]
	v_pk_add_f32 v[70:71], v[70:71], v[26:27]
	v_pk_fma_f32 v[18:19], v[18:19], v[92:93], v[30:31]
	v_mul_f32_e32 v72, 0x3d372713, v70
	v_mul_f32_e32 v68, 0x3d372713, v71
	v_mul_f32_e32 v72, v70, v72
	v_mul_f32_e32 v68, v71, v68
	v_fma_f32 v72, v70, v72, v70
	v_fma_f32 v68, v71, v68, v71
	v_mul_f32_e32 v72, 0x3f4c422a, v72
	v_mul_f32_e32 v68, 0x3f4c422a, v68
	v_add_f32_e32 v72, v72, v72
	v_add_f32_e32 v68, v68, v68
	v_mul_f32_e32 v72, 0xbfb8aa3b, v72
	v_mul_f32_e32 v68, 0xbfb8aa3b, v68
	v_exp_f32_e32 v72, v72
	v_exp_f32_e32 v68, v68
	v_lshlrev_b32_e32 v30, 16, v159
	v_and_b32_e32 v31, 0xffff0000, v159
	v_add_f32_e32 v72, 1.0, v72
	v_add_f32_e32 v68, 1.0, v68
	v_rcp_f32_e32 v106, v72
	v_rcp_f32_e32 v107, v68
	v_pk_mul_f32 v[42:43], v[42:43], v[76:77]
	v_pk_fma_f32 v[18:19], v[22:23], v[30:31], v[18:19]
	v_pk_mul_f32 v[6:7], v[6:7], v[96:97]
	v_pk_add_f32 v[38:39], v[38:39], v[62:63]
	v_pk_fma_f32 v[34:35], v[34:35], v[82:83], v[42:43]
	v_lshlrev_b32_e32 v42, 16, v162
	v_and_b32_e32 v43, 0xffff0000, v162
	v_pk_add_f32 v[18:19], v[18:19], v[26:27]
	v_pk_fma_f32 v[2:3], v[2:3], v[90:91], v[6:7]
	v_lshlrev_b32_e32 v6, 16, v158
	v_and_b32_e32 v7, 0xffff0000, v158
	v_pk_fma_f32 v[108:109], v[10:11], v[96:97], v[108:109]
	v_mul_f32_e32 v50, 0x3d372713, v38
	v_pk_fma_f32 v[34:35], v[46:47], v[42:43], v[34:35]
	v_mul_f32_e32 v42, 0x3d372713, v39
	v_mul_f32_e32 v22, 0x3d372713, v18
	v_pk_fma_f32 v[2:3], v[10:11], v[6:7], v[2:3]
	v_mul_f32_e32 v6, 0x3d372713, v19
	v_pk_add_f32 v[108:109], v[108:109], v[14:15]
	v_pk_mul_f32 v[70:71], v[70:71], v[106:107]
	v_mul_f32_e32 v50, v38, v50
	v_mul_f32_e32 v42, v39, v42
	v_mul_f32_e32 v22, v18, v22
	v_mul_f32_e32 v6, v19, v6
	v_pk_mul_f32 v[106:107], v[108:109], v[70:71]
	v_pk_mul_f32 v[70:71], v[32:33], v[78:79]
	v_fma_f32 v50, v38, v50, v38
	v_fma_f32 v42, v39, v42, v39
	v_fma_f32 v22, v18, v22, v18
	v_fma_f32 v6, v19, v6, v19
	v_pk_fma_f32 v[108:109], v[20:21], v[110:111], v[70:71]
	v_lshlrev_b32_e32 v70, 16, v73
	v_and_b32_e32 v71, 0xffff0000, v73
	v_mul_f32_e32 v50, 0x3f4c422a, v50
	v_mul_f32_e32 v42, 0x3f4c422a, v42
	v_mul_f32_e32 v22, 0x3f4c422a, v22
	v_mul_f32_e32 v6, 0x3f4c422a, v6
	v_pk_fma_f32 v[72:73], v[24:25], v[70:71], v[108:109]
	v_add_f32_e32 v50, v50, v50
	v_add_f32_e32 v42, v42, v42
	v_add_f32_e32 v22, v22, v22
	v_add_f32_e32 v6, v6, v6
	v_pk_add_f32 v[72:73], v[72:73], v[28:29]
	v_mul_f32_e32 v50, 0xbfb8aa3b, v50
	v_mul_f32_e32 v42, 0xbfb8aa3b, v42
	v_mul_f32_e32 v22, 0xbfb8aa3b, v22
	v_mul_f32_e32 v6, 0xbfb8aa3b, v6
	v_mul_f32_e32 v68, 0x3d372713, v72
	v_exp_f32_e32 v50, v50
	v_exp_f32_e32 v42, v42
	v_exp_f32_e32 v22, v22
	v_exp_f32_e32 v6, v6
	v_mul_f32_e32 v68, v72, v68
	v_fma_f32 v68, v72, v68, v72
	v_mul_f32_e32 v68, 0x3f4c422a, v68
	v_add_f32_e32 v68, v68, v68
; __device__ __forceinline__ unsigned cvtpk(float lo, float hi) { f32x2 v = {lo, hi}; bf16x2_t b = __builtin_convertvector(v, bf16x2_t); return __builtin_bit_cast(unsigned, b); }
; __device__ __forceinline__ float gelu_tanh(float x) { const float u = 0.7978845608028654f * (x + 0.044715f * x * x * x); return x * sigmoidf_(2.0f * u); }
; __device__ __forceinline__ void st16_wt(void* p, u32x4 v) { asm volatile("global_store_dwordx4 %0, %1, off sc1\n\ts_nop 2" :: "v"(p), "v"(v) : "memory"); }
; __device__ __forceinline__ float bfe(const u32x4& w, int e) { return (e & 1) ? __builtin_bit_cast(float, w[e >> 1] & 0xffff0000u) : __builtin_bit_cast(float, w[e >> 1] << 16); }
; __device__ __forceinline__ void conv_pass(const bf16_t* __restrict__ U, const float* __restrict__ cw, const float* __restrict__ cb, bf16_t* __restrict__ GA, int tg, int wv) {
;     ...
; #pragma unroll
;         for (int i = 0; i < RUN; ++i) {
;             float o[8];
; #pragma unroll
;             for (int e = 0; e < 8; ++e) {
;                 const float ua = bfe(ra[i], e) * wa[0][e >> 2][e & 3] + bfe(ra[i + 1], e) * wa[1][e >> 2][e & 3] + bfe(ra[i + 2], e) * wa[2][e >> 2][e & 3] + ba[e >> 2][e & 3];
;                 const float ub = bfe(rb[i], e) * wb[0][e >> 2][e & 3] + bfe(rb[i + 1], e) * wb[1][e >> 2][e & 3] + bfe(rb[i + 2], e) * wb[2][e >> 2][e & 3] + bb[e >> 2][e & 3];
;                 o[e] = gelu_tanh(ua) * ub;
;             }
;             u32x4 w; w.x = cvtpk(o[0], o[1]); w.y = cvtpk(o[2], o[3]); w.z = cvtpk(o[4], o[5]); w.w = cvtpk(o[6], o[7]);
;             st16_wt(GA + (size_t)(t0 + i) * DFF + c0, w);
;         }
;     }
; }
	v_add_f32_e32 v50, 1.0, v50
	v_add_f32_e32 v42, 1.0, v42
	v_add_f32_e32 v22, 1.0, v22
	v_add_f32_e32 v6, 1.0, v6
	v_mul_f32_e32 v68, 0xbfb8aa3b, v68
	v_rcp_f32_e32 v50, v50
	v_rcp_f32_e32 v51, v42
	v_rcp_f32_e32 v22, v22
	v_rcp_f32_e32 v23, v6
	v_exp_f32_e32 v68, v68
	v_pk_add_f32 v[34:35], v[34:35], v[54:55]
	v_pk_mul_f32 v[38:39], v[38:39], v[50:51]
	v_pk_add_f32 v[2:3], v[2:3], v[14:15]
	v_pk_mul_f32 v[6:7], v[18:19], v[22:23]
	v_add_f32_e32 v68, 1.0, v68
	v_pk_mul_f32 v[34:35], v[34:35], v[38:39]
	v_pk_mul_f32 v[38:39], v[52:53], v[100:101]
	v_pk_mul_f32 v[2:3], v[2:3], v[6:7]
	v_pk_mul_f32 v[6:7], v[32:33], v[70:71]
	v_rcp_f32_e32 v108, v68
	v_lshlrev_b32_e32 v68, 16, v69
	v_and_b32_e32 v69, 0xffff0000, v69
	v_pk_fma_f32 v[38:39], v[40:41], v[88:89], v[38:39]
	v_lshlrev_b32_e32 v40, 16, v161
	v_and_b32_e32 v41, 0xffff0000, v161
	v_pk_fma_f32 v[6:7], v[20:21], v[78:79], v[6:7]
	v_lshlrev_b32_e32 v10, 16, v157
	v_and_b32_e32 v11, 0xffff0000, v157
	v_pk_mul_f32 v[110:111], v[8:9], v[74:75]
	v_pk_fma_f32 v[38:39], v[60:61], v[40:41], v[38:39]
	v_pk_fma_f32 v[6:7], v[24:25], v[10:11], v[6:7]
	v_pk_mul_f32 v[8:9], v[8:9], v[68:69]
	v_pk_fma_f32 v[94:95], v[4:5], v[94:95], v[110:111]
	v_mul_f32_e32 v109, 0x3d372713, v73
	v_pk_add_f32 v[38:39], v[38:39], v[64:65]
	v_pk_add_f32 v[6:7], v[6:7], v[28:29]
	v_pk_fma_f32 v[4:5], v[4:5], v[74:75], v[8:9]
	v_lshlrev_b32_e32 v8, 16, v156
	v_and_b32_e32 v9, 0xffff0000, v156
	v_mul_f32_e32 v109, v73, v109
	v_mul_f32_e32 v40, 0x3d372713, v38
	v_mul_f32_e32 v41, 0x3d372713, v39
	v_mul_f32_e32 v10, 0x3d372713, v6
	v_pk_fma_f32 v[4:5], v[12:13], v[8:9], v[4:5]
	v_mul_f32_e32 v8, 0x3d372713, v7
	v_fma_f32 v109, v73, v109, v73
	v_mul_f32_e32 v40, v38, v40
	v_mul_f32_e32 v41, v39, v41
	v_mul_f32_e32 v10, v6, v10
	v_mul_f32_e32 v8, v7, v8
	v_mul_f32_e32 v109, 0x3f4c422a, v109
	v_fma_f32 v40, v38, v40, v38
	v_fma_f32 v41, v39, v41, v39
	v_fma_f32 v10, v6, v10, v6
	v_fma_f32 v8, v7, v8, v7
	v_add_f32_e32 v109, v109, v109
	v_mul_f32_e32 v40, 0x3f4c422a, v40
	v_mul_f32_e32 v41, 0x3f4c422a, v41
	v_mul_f32_e32 v10, 0x3f4c422a, v10
	v_mul_f32_e32 v8, 0x3f4c422a, v8
	v_mul_f32_e32 v109, 0xbfb8aa3b, v109
	v_add_f32_e32 v40, v40, v40
	v_add_f32_e32 v41, v41, v41
	v_add_f32_e32 v10, v10, v10
	v_add_f32_e32 v8, v8, v8
	v_exp_f32_e32 v109, v109
	v_mul_f32_e32 v40, 0xbfb8aa3b, v40
	v_mul_f32_e32 v41, 0xbfb8aa3b, v41
	v_mul_f32_e32 v10, 0xbfb8aa3b, v10
	v_mul_f32_e32 v8, 0xbfb8aa3b, v8
	v_exp_f32_e32 v40, v40
	v_exp_f32_e32 v41, v41
	v_exp_f32_e32 v10, v10
	v_exp_f32_e32 v8, v8
	v_add_f32_e32 v109, 1.0, v109
	v_rcp_f32_e32 v109, v109
	v_add_f32_e32 v40, 1.0, v40
	v_add_f32_e32 v41, 1.0, v41
	v_add_f32_e32 v10, 1.0, v10
	v_add_f32_e32 v8, 1.0, v8
	v_rcp_f32_e32 v40, v40
	v_rcp_f32_e32 v41, v41
	v_rcp_f32_e32 v10, v10
	v_rcp_f32_e32 v11, v8
	v_pk_mul_f32 v[42:43], v[44:45], v[66:67]
	v_pk_fma_f32 v[94:95], v[12:13], v[68:69], v[94:95]
	v_pk_fma_f32 v[36:37], v[36:37], v[84:85], v[42:43]
	v_lshlrev_b32_e32 v42, 16, v160
	v_and_b32_e32 v43, 0xffff0000, v160
	v_pk_add_f32 v[94:95], v[94:95], v[16:17]
	v_pk_mul_f32 v[72:73], v[72:73], v[108:109]
	v_pk_fma_f32 v[36:37], v[48:49], v[42:43], v[36:37]
	v_pk_mul_f32 v[72:73], v[94:95], v[72:73]
	v_pk_add_f32 v[36:37], v[36:37], v[56:57]
	v_pk_mul_f32 v[38:39], v[38:39], v[40:41]
	v_pk_add_f32 v[4:5], v[4:5], v[16:17]
	v_pk_mul_f32 v[6:7], v[6:7], v[10:11]
	v_cvt_pk_bf16_f32 v102, v102, v103
	v_cvt_pk_bf16_f32 v103, v104, v105
	v_cvt_pk_bf16_f32 v104, v106, v107
	v_cvt_pk_bf16_f32 v105, v72, v73
	v_mad_i64_i32 v[72:73], s[0:1], v163, s91, v[130:131]
	global_store_dwordx4 v[72:73], v[102:105], off sc1 nt
	s_nop 2
	v_pk_mul_f32 v[36:37], v[36:37], v[38:39]
	v_pk_mul_f32 v[8:9], v[4:5], v[6:7]
	v_cvt_pk_bf16_f32 v4, v34, v35
	v_cvt_pk_bf16_f32 v5, v36, v37
	v_cvt_pk_bf16_f32 v6, v2, v3
	v_cvt_pk_bf16_f32 v7, v8, v9
	v_mad_i64_i32 v[2:3], s[0:1], v155, s91, v[130:131]
	global_store_dwordx4 v[2:3], v[4:7], off sc1 nt
	s_nop 2
	s_andn2_b64 exec, exec, s[82:83]
	s_cbranch_execnz .LBB0_189

; __device__ __forceinline__ float shx(float v, int o, int lane) { return __builtin_bit_cast(float, __builtin_amdgcn_ds_bpermute((lane ^ o) << 2, __builtin_bit_cast(int, v))); }
; __device__ __forceinline__ int ltid(int wv) { unsigned z = 0u; asm volatile("" : "+v"(z)); return wv * 64 + (int)__builtin_amdgcn_mbcnt_hi(~0u, __builtin_amdgcn_mbcnt_lo(~0u, z)); }
; #define EPI_LOOP_ROWS for (int ai = 0; ai < 2; ++ai) _Pragma("unroll") for (int m = 0; m < 4; ++m)
; __device__ __forceinline__ float row_part(const float* RS, int row, int fq) { const f32x4 a = ((const f32x4*)(RS + (size_t)row * 16))[fq]; return (a.x + a.y) + (a.z + a.w); }
; __device__ __forceinline__ float row_rstd_fin(float s, int lane) { s += shx(s, 16, lane); s += shx(s, 32, lane); return rsqrtf(s * (1.0f / 1024.0f) + EPS); }
;     __device__ __forceinline__ void operator()(const f32x4 (&acc)[2][2][4][2], const Unit& u, int wv) const {
;         const int t_ = ltid(wv), wid_ = __builtin_amdgcn_readfirstlane(t_ >> 6), wr = wid_ >> 2, wc = wid_ & 3, fr = t_ & 15, fq = (t_ & 63) >> 4;
;         const bool gate = u.pn >= split_pn;
;         bf16_t* base = gate ? O1 : O0;
;         const int col0 = (gate ? (u.pn - split_pn) : u.pn) * BM + wc * 32 + 8 * fq;
;         const int row0 = u.pm * BM + wr * 64 + fr;
;         float rs[2][4];
; #pragma unroll
;         EPI_LOOP_ROWS rs[ai][m] = RS ? row_part(RS, row0 + ai * HALF + m * 16, fq) : 0.f;
; #pragma unroll
;         EPI_LOOP_ROWS rs[ai][m] = RS ? row_rstd_fin(rs[ai][m], t_ & 63) : 1.0f;
.LBB0_204:
	v_mov_b32_e32 v0, v1
	s_nop 0
	v_mbcnt_lo_u32_b32 v0, -1, v0
	v_mbcnt_hi_u32_b32 v0, -1, v0
	v_add_u32_e32 v142, s33, v0
	v_and_b32_e32 v160, 63, v0
	v_readfirstlane_b32 s0, v142
	s_lshr_b32 s1, s0, 1
	s_ashr_i32 s0, s0, 2
	s_and_b32 s10, s1, 0x60
	s_lshl_b32 s1, s4, 8
	s_andn2_b32 s0, s0, 63
	s_add_i32 s0, s0, s1
	v_and_or_b32 v158, v0, 15, s0
	v_lshrrev_b32_e32 v176, 1, v0
	v_and_b32_e32 v0, 48, v0
	v_ashrrev_i32_e32 v159, 31, v158
	v_lshl_add_u64 v[162:163], s[64:65], 0, v[0:1]
	v_lshlrev_b64 v[188:189], 6, v[158:159]
	v_lshl_add_u64 v[188:189], v[162:163], 0, v[188:189]
	global_load_dwordx4 v[196:199], v[188:189], off
	v_or_b32_e32 v154, 16, v158
	v_ashrrev_i32_e32 v155, 31, v154
	v_lshlrev_b64 v[188:189], 6, v[154:155]
	v_lshl_add_u64 v[188:189], v[162:163], 0, v[188:189]
	global_load_dwordx4 v[200:203], v[188:189], off
	v_or_b32_e32 v152, 32, v158
	v_ashrrev_i32_e32 v153, 31, v152
	v_lshlrev_b64 v[188:189], 6, v[152:153]
	v_lshl_add_u64 v[188:189], v[162:163], 0, v[188:189]
	global_load_dwordx4 v[204:207], v[188:189], off
	v_or_b32_e32 v150, 48, v158
	v_ashrrev_i32_e32 v151, 31, v150
	v_lshlrev_b64 v[188:189], 6, v[150:151]
	v_lshl_add_u64 v[188:189], v[162:163], 0, v[188:189]
	global_load_dwordx4 v[208:211], v[188:189], off
	v_add_u32_e32 v148, 0x80, v158
	v_ashrrev_i32_e32 v149, 31, v148
	v_lshlrev_b64 v[188:189], 6, v[148:149]
	v_lshl_add_u64 v[188:189], v[162:163], 0, v[188:189]
	global_load_dwordx4 v[212:215], v[188:189], off
	v_add_u32_e32 v146, 0x90, v158
	v_ashrrev_i32_e32 v147, 31, v146
	v_lshlrev_b64 v[188:189], 6, v[146:147]
	v_lshl_add_u64 v[188:189], v[162:163], 0, v[188:189]
	global_load_dwordx4 v[216:219], v[188:189], off
	v_add_u32_e32 v144, 0xa0, v158
	v_ashrrev_i32_e32 v145, 31, v144
	v_lshlrev_b64 v[188:189], 6, v[144:145]
	v_lshl_add_u64 v[188:189], v[162:163], 0, v[188:189]
	global_load_dwordx4 v[220:223], v[188:189], off
	v_add_u32_e32 v142, 0xb0, v158
	v_ashrrev_i32_e32 v143, 31, v142
	v_lshlrev_b64 v[188:189], 6, v[142:143]
	v_lshl_add_u64 v[188:189], v[162:163], 0, v[188:189]
	global_load_dwordx4 v[224:227], v[188:189], off
	v_lshlrev_b32_e32 v0, 2, v160
	s_lshl_b32 s0, s5, 8
	s_or_b32 s10, s10, s0
	s_mov_b32 s0, 0x358637bd
	s_waitcnt vmcnt(0)
	v_add_f32_e32 v156, v197, v196
	v_add_f32_e32 v157, v198, v199
	v_add_f32_e32 v182, v201, v200
	v_add_f32_e32 v183, v202, v203
	v_add_f32_e32 v184, v205, v204
	v_add_f32_e32 v185, v206, v207
	v_add_f32_e32 v170, v209, v208
	v_add_f32_e32 v171, v210, v211
	v_add_f32_e32 v172, v213, v212
	v_add_f32_e32 v173, v214, v215
	v_add_f32_e32 v164, v217, v216
	v_add_f32_e32 v165, v218, v219
	v_xor_b32_e32 v145, 64, v0
	v_add_f32_e32 v168, v221, v220
	v_add_f32_e32 v169, v222, v223
	v_mov_b32_e32 v166, v184
	v_mov_b32_e32 v167, v182
	v_mov_b32_e32 v182, v185
	v_pk_add_f32 v[166:167], v[166:167], v[182:183]
	v_xor_b32_e32 v143, 0x80, v0
	v_add_f32_e32 v162, v225, v224
	v_add_f32_e32 v163, v226, v227
	ds_bpermute_b32 v179, v145, v167
	ds_bpermute_b32 v178, v145, v166
	v_mov_b32_e32 v177, v162
	v_mov_b32_e32 v162, v157
	s_waitcnt lgkmcnt(0)
	v_pk_add_f32 v[166:167], v[166:167], v[178:179]
	ds_bpermute_b32 v179, v143, v167
	ds_bpermute_b32 v178, v143, v166
	s_waitcnt lgkmcnt(0)
	v_pk_add_f32 v[178:179], v[166:167], v[178:179]
	v_mov_b64_e32 v[166:167], s[0:1]
	v_pk_fma_f32 v[178:179], v[178:179], s[92:93], v[166:167] op_sel_hi:[1,0,0]
	s_nop 0
	v_mul_f32_e32 v0, 0x4b800000, v179
	v_cmp_gt_f32_e64 s[4:5], s97, v179
	v_cmp_gt_f32_e32 vcc, s97, v178
	s_nop 0
	v_cndmask_b32_e64 v0, v179, v0, s[4:5]
	v_rsq_f32_e32 v0, v0
	v_mov_b32_e32 v179, v170
	v_mov_b32_e32 v170, v173
	v_mul_f32_e32 v147, 0x45800000, v0
	v_cndmask_b32_e64 v160, v0, v147, s[4:5]
	v_mul_f32_e32 v0, 0x4b800000, v178
	v_cndmask_b32_e32 v0, v178, v0, vcc
	v_mov_b32_e32 v178, v172
	v_pk_add_f32 v[170:171], v[178:179], v[170:171]
	ds_bpermute_b32 v173, v145, v171
	ds_bpermute_b32 v172, v145, v170
	v_rsq_f32_e32 v0, v0
	v_mov_b32_e32 v178, v168
	v_mov_b32_e32 v179, v164
	v_mov_b32_e32 v164, v169
	s_waitcnt lgkmcnt(0)
	v_pk_add_f32 v[170:171], v[170:171], v[172:173]
	ds_bpermute_b32 v173, v143, v171
	ds_bpermute_b32 v172, v143, v170
	v_mul_f32_e32 v147, 0x45800000, v0
	v_cndmask_b32_e32 v0, v0, v147, vcc
	v_pk_add_f32 v[164:165], v[178:179], v[164:165]
	ds_bpermute_b32 v169, v145, v165
	s_waitcnt lgkmcnt(1)
	v_pk_add_f32 v[170:171], v[170:171], v[172:173]
	ds_bpermute_b32 v168, v145, v164
	v_pk_fma_f32 v[170:171], v[170:171], s[92:93], v[166:167] op_sel_hi:[1,0,0]
	v_pk_mul_f32 v[96:97], v[96:97], v[160:161] op_sel_hi:[1,0]
	v_mul_f32_e32 v147, 0x4b800000, v171
	v_cmp_gt_f32_e64 s[4:5], s97, v171
	s_waitcnt lgkmcnt(0)
	v_pk_add_f32 v[164:165], v[164:165], v[168:169]
	v_cmp_gt_f32_e32 vcc, s97, v170
	v_cndmask_b32_e64 v147, v171, v147, s[4:5]
	v_rsq_f32_e32 v147, v147
	ds_bpermute_b32 v169, v143, v165
	ds_bpermute_b32 v168, v143, v164
	v_pk_mul_f32 v[80:81], v[80:81], v[0:1] op_sel_hi:[1,0]
	v_mul_f32_e32 v149, 0x45800000, v147
	v_cndmask_b32_e64 v172, v147, v149, s[4:5]
	v_mul_f32_e32 v147, 0x4b800000, v170
	v_cndmask_b32_e32 v147, v170, v147, vcc
	v_rsq_f32_e32 v147, v147
	s_waitcnt lgkmcnt(0)
; __device__ __forceinline__ unsigned cvtpk(float lo, float hi) { f32x2 v = {lo, hi}; bf16x2_t b = __builtin_convertvector(v, bf16x2_t); return __builtin_bit_cast(unsigned, b); }
; __device__ __forceinline__ float sigmoidf_(float v) { return __builtin_amdgcn_rcpf(1.0f + __expf(-v)); }
; __device__ __forceinline__ void st16_wt(void* p, u32x4 v) { asm volatile("global_store_dwordx4 %0, %1, off sc1\n\ts_nop 2" :: "v"(p), "v"(v) : "memory"); }
; #define EPI_LOOP_ROWS for (int ai = 0; ai < 2; ++ai) _Pragma("unroll") for (int m = 0; m < 4; ++m)
;     __device__ __forceinline__ void operator()(const f32x4 (&acc)[2][2][4][2], const Unit& u, int wv) const {
;     ...
;         EPI_LOOP_ROWS { bf16_t* rowp = base + (size_t)(row0 + ai * HALF + m * 16) * ldc + col0;
;             const float rstd = rs[ai][m];
;             float ssm = 0.f;
; #pragma unroll
;             for (int bj = 0; bj < 2; ++bj) { f32x4 v0 = acc[ai][bj][m][0] * rstd, v1 = acc[ai][bj][m][1] * rstd;
;                 if (RSM && (u.pn == 0 || (u.pn == 1 && bj == 0))) ssm += ((v0[0] * v0[0] + v0[1] * v0[1]) + (v0[2] * v0[2] + v0[3] * v0[3])) + ((v1[0] * v1[0] + v1[1] * v1[1]) + (v1[2] * v1[2] + v1[3] * v1[3]));
;                 if (gate) {
; #pragma unroll
;                     for (int e = 0; e < 4; ++e) { v0[e] = sigmoidf_(v0[e]); v1[e] = sigmoidf_(v1[e]); } }
;                 u32x4 w; w.x = cvtpk(v0[0], v0[1]); w.y = cvtpk(v0[2], v0[3]); w.z = cvtpk(v1[0], v1[1]); w.w = cvtpk(v1[2], v1[3]);
;                 st16_wt(rowp + bj * HALF, w); }
	v_pk_add_f32 v[164:165], v[164:165], v[168:169]
	v_pk_mul_f32 v[72:73], v[72:73], v[172:173] op_sel_hi:[1,0]
	v_pk_fma_f32 v[164:165], v[164:165], s[92:93], v[166:167] op_sel_hi:[1,0,0]
	v_mul_f32_e32 v149, 0x45800000, v147
	v_cndmask_b32_e32 v170, v147, v149, vcc
	v_mul_f32_e32 v147, 0x4b800000, v165
	v_cmp_gt_f32_e64 s[4:5], s97, v165
	v_cmp_gt_f32_e32 vcc, s97, v164
	v_pk_mul_f32 v[64:65], v[64:65], v[170:171] op_sel_hi:[1,0]
	v_cndmask_b32_e64 v147, v165, v147, s[4:5]
	v_rsq_f32_e32 v147, v147
	v_pk_mul_f32 v[48:49], v[48:49], v[170:171] op_sel_hi:[1,0]
	v_mul_f32_e32 v149, 0x45800000, v147
	v_cndmask_b32_e64 v174, v147, v149, s[4:5]
	v_mul_f32_e32 v147, 0x4b800000, v164
	v_cndmask_b32_e32 v147, v164, v147, vcc
	v_and_or_b32 v164, v176, 24, s10
	v_mov_b32_e32 v176, v156
	v_pk_add_f32 v[156:157], v[176:177], v[162:163]
	ds_bpermute_b32 v162, v145, v156
	ds_bpermute_b32 v163, v145, v157
	v_rsq_f32_e32 v147, v147
	v_ashrrev_i32_e32 v165, 31, v164
	v_lshl_add_u64 v[164:165], v[164:165], 1, s[12:13]
	v_mad_i64_i32 v[158:159], s[0:1], v158, s95, v[164:165]
	s_waitcnt lgkmcnt(0)
	v_pk_add_f32 v[156:157], v[156:157], v[162:163]
	ds_bpermute_b32 v162, v143, v156
	ds_bpermute_b32 v163, v143, v157
	v_mul_f32_e32 v149, 0x45800000, v147
	v_cndmask_b32_e32 v168, v147, v149, vcc
	v_pk_mul_f32 v[32:33], v[32:33], v[174:175] op_sel_hi:[1,0]
	v_pk_mul_f32 v[16:17], v[16:17], v[168:169] op_sel_hi:[1,0]
	s_waitcnt lgkmcnt(0)
	v_pk_add_f32 v[156:157], v[156:157], v[162:163]
	s_nop 0
	v_pk_fma_f32 v[162:163], v[156:157], s[92:93], v[166:167] op_sel_hi:[1,0,0]
	s_nop 0
	v_mul_f32_e32 v143, 0x4b800000, v163
	v_cmp_gt_f32_e64 s[4:5], s97, v163
	v_cmp_gt_f32_e32 vcc, s97, v162
	s_nop 0
	v_cndmask_b32_e64 v143, v163, v143, s[4:5]
	v_rsq_f32_e32 v143, v143
	s_nop 0
	v_mul_f32_e32 v145, 0x45800000, v143
	v_cndmask_b32_e64 v156, v143, v145, s[4:5]
	v_mul_f32_e32 v143, 0x4b800000, v162
	v_cndmask_b32_e32 v143, v162, v143, vcc
	v_rsq_f32_e32 v143, v143
	s_mov_b64 s[4:5], 0x100
	v_pk_mul_f32 v[8:9], v[8:9], v[156:157] op_sel_hi:[1,0]
	v_mul_f32_e32 v145, 0x45800000, v143
	v_cndmask_b32_e32 v162, v143, v145, vcc
	v_pk_mul_f32 v[166:167], v[124:125], v[162:163] op_sel_hi:[1,0]
	v_pk_mul_f32 v[124:125], v[122:123], v[162:163] op_sel_hi:[1,0]
	v_pk_mul_f32 v[128:129], v[128:129], v[162:163] op_sel_hi:[1,0]
	v_pk_mul_f32 v[122:123], v[126:127], v[162:163] op_sel_hi:[1,0]
	v_cvt_pk_bf16_f32 v124, v124, v125
	v_cvt_pk_bf16_f32 v122, v122, v123
	v_cvt_pk_bf16_f32 v123, v128, v129
	v_cvt_pk_bf16_f32 v125, v166, v167
	global_store_dwordx4 v[158:159], v[122:125], off sc1 nt
	s_nop 2
	v_pk_mul_f32 v[122:123], v[108:109], v[162:163] op_sel_hi:[1,0]
	v_pk_mul_f32 v[108:109], v[106:107], v[162:163] op_sel_hi:[1,0]
	v_pk_mul_f32 v[112:113], v[112:113], v[162:163] op_sel_hi:[1,0]
	v_pk_mul_f32 v[106:107], v[110:111], v[162:163] op_sel_hi:[1,0]
	v_cvt_pk_bf16_f32 v108, v108, v109
	v_cvt_pk_bf16_f32 v106, v106, v107
	v_cvt_pk_bf16_f32 v107, v112, v113
	v_cvt_pk_bf16_f32 v109, v122, v123
	v_lshl_add_u64 v[110:111], v[158:159], 0, s[4:5]
	global_store_dwordx4 v[110:111], v[106:109], off sc1 nt
	s_nop 2
	v_pk_mul_f32 v[108:109], v[114:115], v[160:161] op_sel_hi:[1,0]
	v_pk_mul_f32 v[114:115], v[120:121], v[160:161] op_sel_hi:[1,0]
	v_pk_mul_f32 v[106:107], v[118:119], v[160:161] op_sel_hi:[1,0]
	v_pk_mul_f32 v[112:113], v[116:117], v[160:161] op_sel_hi:[1,0]
	v_cvt_pk_bf16_f32 v106, v106, v107
	v_cvt_pk_bf16_f32 v107, v114, v115
	v_mad_i64_i32 v[110:111], s[0:1], v154, s95, v[164:165]
	v_cvt_pk_bf16_f32 v108, v108, v109
	v_cvt_pk_bf16_f32 v109, v112, v113
	global_store_dwordx4 v[110:111], v[106:109], off sc1 nt
	s_nop 2
	v_pk_mul_f32 v[106:107], v[92:93], v[160:161] op_sel_hi:[1,0]
	v_pk_mul_f32 v[92:93], v[90:91], v[160:161] op_sel_hi:[1,0]
	v_pk_mul_f32 v[90:91], v[94:95], v[160:161] op_sel_hi:[1,0]
	v_cvt_pk_bf16_f32 v92, v92, v93
	v_cvt_pk_bf16_f32 v90, v90, v91
	v_cvt_pk_bf16_f32 v91, v96, v97
	v_cvt_pk_bf16_f32 v93, v106, v107
	v_lshl_add_u64 v[94:95], v[110:111], 0, s[4:5]
	global_store_dwordx4 v[94:95], v[90:93], off sc1 nt
	s_nop 2
	v_pk_mul_f32 v[92:93], v[98:99], v[0:1] op_sel_hi:[1,0]
	v_pk_mul_f32 v[98:99], v[104:105], v[0:1] op_sel_hi:[1,0]
	v_pk_mul_f32 v[90:91], v[102:103], v[0:1] op_sel_hi:[1,0]
	v_pk_mul_f32 v[96:97], v[100:101], v[0:1] op_sel_hi:[1,0]
	v_cvt_pk_bf16_f32 v90, v90, v91
	v_cvt_pk_bf16_f32 v91, v98, v99
	v_mad_i64_i32 v[94:95], s[0:1], v152, s95, v[164:165]
	v_cvt_pk_bf16_f32 v92, v92, v93
	v_cvt_pk_bf16_f32 v93, v96, v97
	global_store_dwordx4 v[94:95], v[90:93], off sc1 nt
	s_nop 2
	v_pk_mul_f32 v[90:91], v[76:77], v[0:1] op_sel_hi:[1,0]
	v_pk_mul_f32 v[76:77], v[74:75], v[0:1] op_sel_hi:[1,0]
	v_pk_mul_f32 v[74:75], v[78:79], v[0:1] op_sel_hi:[1,0]
	v_cvt_pk_bf16_f32 v76, v76, v77
	v_cvt_pk_bf16_f32 v74, v74, v75
	v_cvt_pk_bf16_f32 v75, v80, v81
; __device__ __forceinline__ unsigned cvtpk(float lo, float hi) { f32x2 v = {lo, hi}; bf16x2_t b = __builtin_convertvector(v, bf16x2_t); return __builtin_bit_cast(unsigned, b); }
; __device__ __forceinline__ float sigmoidf_(float v) { return __builtin_amdgcn_rcpf(1.0f + __expf(-v)); }
; __device__ __forceinline__ void st16_wt(void* p, u32x4 v) { asm volatile("global_store_dwordx4 %0, %1, off sc1\n\ts_nop 2" :: "v"(p), "v"(v) : "memory"); }
; #define EPI_LOOP_ROWS for (int ai = 0; ai < 2; ++ai) _Pragma("unroll") for (int m = 0; m < 4; ++m)
;     __device__ __forceinline__ void operator()(const f32x4 (&acc)[2][2][4][2], const Unit& u, int wv) const {
;     ...
;         EPI_LOOP_ROWS { bf16_t* rowp = base + (size_t)(row0 + ai * HALF + m * 16) * ldc + col0;
;             const float rstd = rs[ai][m];
;             float ssm = 0.f;
; #pragma unroll
;             for (int bj = 0; bj < 2; ++bj) { f32x4 v0 = acc[ai][bj][m][0] * rstd, v1 = acc[ai][bj][m][1] * rstd;
;                 if (RSM && (u.pn == 0 || (u.pn == 1 && bj == 0))) ssm += ((v0[0] * v0[0] + v0[1] * v0[1]) + (v0[2] * v0[2] + v0[3] * v0[3])) + ((v1[0] * v1[0] + v1[1] * v1[1]) + (v1[2] * v1[2] + v1[3] * v1[3]));
;                 if (gate) {
; #pragma unroll
;                     for (int e = 0; e < 4; ++e) { v0[e] = sigmoidf_(v0[e]); v1[e] = sigmoidf_(v1[e]); } }
;                 u32x4 w; w.x = cvtpk(v0[0], v0[1]); w.y = cvtpk(v0[2], v0[3]); w.z = cvtpk(v1[0], v1[1]); w.w = cvtpk(v1[2], v1[3]);
;                 st16_wt(rowp + bj * HALF, w); }
	v_cvt_pk_bf16_f32 v77, v90, v91
	v_lshl_add_u64 v[78:79], v[94:95], 0, s[4:5]
	global_store_dwordx4 v[78:79], v[74:77], off sc1 nt
	s_nop 2
	v_pk_mul_f32 v[76:77], v[82:83], v[172:173] op_sel_hi:[1,0]
	v_pk_mul_f32 v[82:83], v[88:89], v[172:173] op_sel_hi:[1,0]
	v_pk_mul_f32 v[74:75], v[86:87], v[172:173] op_sel_hi:[1,0]
	v_pk_mul_f32 v[80:81], v[84:85], v[172:173] op_sel_hi:[1,0]
	v_cvt_pk_bf16_f32 v74, v74, v75
	v_cvt_pk_bf16_f32 v75, v82, v83
	v_mad_i64_i32 v[78:79], s[0:1], v150, s95, v[164:165]
	v_cvt_pk_bf16_f32 v76, v76, v77
	v_cvt_pk_bf16_f32 v77, v80, v81
	global_store_dwordx4 v[78:79], v[74:77], off sc1 nt
	s_nop 2
	v_pk_mul_f32 v[74:75], v[68:69], v[172:173] op_sel_hi:[1,0]
	v_pk_mul_f32 v[68:69], v[66:67], v[172:173] op_sel_hi:[1,0]
	v_pk_mul_f32 v[66:67], v[70:71], v[172:173] op_sel_hi:[1,0]
	v_cvt_pk_bf16_f32 v68, v68, v69
	v_cvt_pk_bf16_f32 v69, v74, v75
	v_cvt_pk_bf16_f32 v66, v66, v67
	v_cvt_pk_bf16_f32 v67, v72, v73
	v_lshl_add_u64 v[70:71], v[78:79], 0, s[4:5]
	global_store_dwordx4 v[70:71], v[66:69], off sc1 nt
	s_nop 2
	v_pk_mul_f32 v[68:69], v[60:61], v[170:171] op_sel_hi:[1,0]
	v_pk_mul_f32 v[60:61], v[58:59], v[170:171] op_sel_hi:[1,0]
	v_pk_mul_f32 v[58:59], v[62:63], v[170:171] op_sel_hi:[1,0]
	v_mad_i64_i32 v[66:67], s[0:1], v148, s95, v[164:165]
	v_cvt_pk_bf16_f32 v58, v58, v59
	v_cvt_pk_bf16_f32 v59, v64, v65
	v_cvt_pk_bf16_f32 v60, v60, v61
	v_cvt_pk_bf16_f32 v61, v68, v69
	global_store_dwordx4 v[66:67], v[58:61], off sc1 nt
	s_nop 2
	v_pk_mul_f32 v[58:59], v[44:45], v[170:171] op_sel_hi:[1,0]
	v_pk_mul_f32 v[44:45], v[42:43], v[170:171] op_sel_hi:[1,0]
	v_pk_mul_f32 v[42:43], v[46:47], v[170:171] op_sel_hi:[1,0]
	v_cvt_pk_bf16_f32 v44, v44, v45
	v_cvt_pk_bf16_f32 v42, v42, v43
	v_cvt_pk_bf16_f32 v43, v48, v49
	v_cvt_pk_bf16_f32 v45, v58, v59
	v_lshl_add_u64 v[46:47], v[66:67], 0, s[4:5]
	global_store_dwordx4 v[46:47], v[42:45], off sc1 nt
	s_nop 2
	v_pk_mul_f32 v[44:45], v[50:51], v[174:175] op_sel_hi:[1,0]
	v_pk_mul_f32 v[50:51], v[56:57], v[174:175] op_sel_hi:[1,0]
	v_pk_mul_f32 v[42:43], v[54:55], v[174:175] op_sel_hi:[1,0]
	v_pk_mul_f32 v[48:49], v[52:53], v[174:175] op_sel_hi:[1,0]
	v_cvt_pk_bf16_f32 v42, v42, v43
	v_cvt_pk_bf16_f32 v43, v50, v51
	v_mad_i64_i32 v[46:47], s[0:1], v146, s95, v[164:165]
	v_cvt_pk_bf16_f32 v44, v44, v45
	v_cvt_pk_bf16_f32 v45, v48, v49
	global_store_dwordx4 v[46:47], v[42:45], off sc1 nt
	s_nop 2
	v_pk_mul_f32 v[42:43], v[28:29], v[174:175] op_sel_hi:[1,0]
	v_pk_mul_f32 v[28:29], v[26:27], v[174:175] op_sel_hi:[1,0]
	v_pk_mul_f32 v[26:27], v[30:31], v[174:175] op_sel_hi:[1,0]
	v_cvt_pk_bf16_f32 v28, v28, v29
	v_cvt_pk_bf16_f32 v26, v26, v27
	v_cvt_pk_bf16_f32 v27, v32, v33
	v_cvt_pk_bf16_f32 v29, v42, v43
	v_lshl_add_u64 v[30:31], v[46:47], 0, s[4:5]
	global_store_dwordx4 v[30:31], v[26:29], off sc1 nt
	s_nop 2
	v_pk_mul_f32 v[28:29], v[34:35], v[168:169] op_sel_hi:[1,0]
	v_pk_mul_f32 v[34:35], v[40:41], v[168:169] op_sel_hi:[1,0]
	v_pk_mul_f32 v[26:27], v[38:39], v[168:169] op_sel_hi:[1,0]
	v_pk_mul_f32 v[32:33], v[36:37], v[168:169] op_sel_hi:[1,0]
	v_cvt_pk_bf16_f32 v26, v26, v27
	v_cvt_pk_bf16_f32 v27, v34, v35
	v_mad_i64_i32 v[30:31], s[0:1], v144, s95, v[164:165]
	v_cvt_pk_bf16_f32 v28, v28, v29
	v_cvt_pk_bf16_f32 v29, v32, v33
	global_store_dwordx4 v[30:31], v[26:29], off sc1 nt
	s_nop 2
	v_pk_mul_f32 v[26:27], v[12:13], v[168:169] op_sel_hi:[1,0]
	v_pk_mul_f32 v[12:13], v[10:11], v[168:169] op_sel_hi:[1,0]
	v_pk_mul_f32 v[10:11], v[14:15], v[168:169] op_sel_hi:[1,0]
	v_cvt_pk_bf16_f32 v12, v12, v13
	v_cvt_pk_bf16_f32 v10, v10, v11
	v_cvt_pk_bf16_f32 v11, v16, v17
	v_cvt_pk_bf16_f32 v13, v26, v27
	v_lshl_add_u64 v[14:15], v[30:31], 0, s[4:5]
	global_store_dwordx4 v[14:15], v[10:13], off sc1 nt
	s_nop 2
	v_pk_mul_f32 v[12:13], v[18:19], v[156:157] op_sel_hi:[1,0]
	v_pk_mul_f32 v[18:19], v[24:25], v[156:157] op_sel_hi:[1,0]
	v_pk_mul_f32 v[10:11], v[22:23], v[156:157] op_sel_hi:[1,0]
	v_pk_mul_f32 v[16:17], v[20:21], v[156:157] op_sel_hi:[1,0]
	v_cvt_pk_bf16_f32 v10, v10, v11
	v_cvt_pk_bf16_f32 v11, v18, v19
	v_mad_i64_i32 v[14:15], s[0:1], v142, s95, v[164:165]
	v_cvt_pk_bf16_f32 v12, v12, v13
	v_cvt_pk_bf16_f32 v13, v16, v17
	global_store_dwordx4 v[14:15], v[10:13], off sc1 nt
	s_nop 2
	v_pk_mul_f32 v[10:11], v[4:5], v[156:157] op_sel_hi:[1,0]
	v_pk_mul_f32 v[4:5], v[2:3], v[156:157] op_sel_hi:[1,0]
	v_pk_mul_f32 v[2:3], v[6:7], v[156:157] op_sel_hi:[1,0]
	v_cvt_pk_bf16_f32 v4, v4, v5
	v_cvt_pk_bf16_f32 v2, v2, v3
	v_cvt_pk_bf16_f32 v3, v8, v9
	v_cvt_pk_bf16_f32 v5, v10, v11
	v_lshl_add_u64 v[6:7], v[14:15], 0, s[4:5]
	global_store_dwordx4 v[6:7], v[2:5], off sc1 nt
	s_nop 2
	s_mov_b64 s[4:5], -1
	s_andn2_b64 vcc, exec, s[2:3]
	s_cbranch_vccnz .LBB0_197
	s_andn2_b64 vcc, exec, s[8:9]
	s_cbranch_vccnz .LBB0_196
	s_barrier
	s_branch .LBB0_196

; __device__ __forceinline__ unsigned cvtpk(float lo, float hi) { f32x2 v = {lo, hi}; bf16x2_t b = __builtin_convertvector(v, bf16x2_t); return __builtin_bit_cast(unsigned, b); }
; __device__ __forceinline__ float sigmoidf_(float v) { return __builtin_amdgcn_rcpf(1.0f + __expf(-v)); }
; __device__ __forceinline__ void st16_wt(void* p, u32x4 v) { asm volatile("global_store_dwordx4 %0, %1, off sc1\n\ts_nop 2" :: "v"(p), "v"(v) : "memory"); }
; #define EPI_LOOP_ROWS for (int ai = 0; ai < 2; ++ai) _Pragma("unroll") for (int m = 0; m < 4; ++m)
;     __device__ __forceinline__ void operator()(const f32x4 (&acc)[2][2][4][2], const Unit& u, int wv) const {
;     ...
;         EPI_LOOP_ROWS { bf16_t* rowp = base + (size_t)(row0 + ai * HALF + m * 16) * ldc + col0;
;             const float rstd = rs[ai][m];
;             float ssm = 0.f;
; #pragma unroll
;             for (int bj = 0; bj < 2; ++bj) { f32x4 v0 = acc[ai][bj][m][0] * rstd, v1 = acc[ai][bj][m][1] * rstd;
;                 if (RSM && (u.pn == 0 || (u.pn == 1 && bj == 0))) ssm += ((v0[0] * v0[0] + v0[1] * v0[1]) + (v0[2] * v0[2] + v0[3] * v0[3])) + ((v1[0] * v1[0] + v1[1] * v1[1]) + (v1[2] * v1[2] + v1[3] * v1[3]));
;                 if (gate) {
; #pragma unroll
;                     for (int e = 0; e < 4; ++e) { v0[e] = sigmoidf_(v0[e]); v1[e] = sigmoidf_(v1[e]); } }
;                 u32x4 w; w.x = cvtpk(v0[0], v0[1]); w.y = cvtpk(v0[2], v0[3]); w.z = cvtpk(v1[0], v1[1]); w.w = cvtpk(v1[2], v1[3]);
;                 st16_wt(rowp + bj * HALF, w); }
.LBB0_228:
	v_mov_b32_e32 v138, v1
	v_readlane_b32 s0, v255, 1
	v_mbcnt_lo_u32_b32 v138, -1, v138
	v_mbcnt_hi_u32_b32 v138, -1, v138
	v_add_u32_e32 v139, s0, v138
	s_lshl_b32 s20, s66, 8
	v_readfirstlane_b32 s0, v139
	s_lshr_b32 s1, s0, 1
	s_ashr_i32 s0, s0, 2
	s_andn2_b32 s0, s0, 63
	s_add_i32 s0, s0, s20
	s_and_b32 s1, s1, 0x60
	v_lshrrev_b32_e32 v139, 1, v138
	v_and_or_b32 v138, v138, 15, s0
	s_lshl_b32 s0, s64, 8
	s_or_b32 s0, s1, s0
	v_and_or_b32 v140, v139, 24, s0
	v_ashrrev_i32_e32 v141, 31, v140
	v_ashrrev_i32_e32 v139, 31, v138
	v_lshl_add_u64 v[140:141], v[140:141], 1, s[8:9]
	v_lshlrev_b64 v[142:143], 11, v[138:139]
	v_lshl_add_u64 v[142:143], v[140:141], 0, v[142:143]
	s_mov_b64 s[0:1], 0x100
	v_cvt_pk_bf16_f32 v126, v126, v127
	v_cvt_pk_bf16_f32 v127, v128, v129
	v_cvt_pk_bf16_f32 v128, v122, v123
	v_cvt_pk_bf16_f32 v129, v124, v125
	global_store_dwordx4 v[142:143], v[126:129], off sc1 nt
	s_nop 2
	v_cvt_pk_bf16_f32 v110, v110, v111
	v_cvt_pk_bf16_f32 v111, v112, v113
	v_cvt_pk_bf16_f32 v112, v106, v107
	v_lshl_add_u64 v[106:107], v[142:143], 0, s[0:1]
	v_cvt_pk_bf16_f32 v113, v108, v109
	global_store_dwordx4 v[106:107], v[110:113], off sc1 nt
	s_nop 2
	v_or_b32_e32 v106, 16, v138
	v_ashrrev_i32_e32 v107, 31, v106
	v_lshlrev_b64 v[106:107], 11, v[106:107]
	v_lshl_add_u64 v[110:111], v[140:141], 0, v[106:107]
	v_cvt_pk_bf16_f32 v106, v118, v119
	v_cvt_pk_bf16_f32 v107, v120, v121
	v_cvt_pk_bf16_f32 v108, v114, v115
	v_cvt_pk_bf16_f32 v109, v116, v117
	global_store_dwordx4 v[110:111], v[106:109], off sc1 nt
	s_nop 2
	v_cvt_pk_bf16_f32 v94, v94, v95
	v_cvt_pk_bf16_f32 v95, v96, v97
	v_cvt_pk_bf16_f32 v96, v90, v91
	v_lshl_add_u64 v[90:91], v[110:111], 0, s[0:1]
	v_cvt_pk_bf16_f32 v97, v92, v93
	global_store_dwordx4 v[90:91], v[94:97], off sc1 nt
	s_nop 2
	v_or_b32_e32 v90, 32, v138
	v_ashrrev_i32_e32 v91, 31, v90
	v_lshlrev_b64 v[90:91], 11, v[90:91]
	v_lshl_add_u64 v[94:95], v[140:141], 0, v[90:91]
	v_cvt_pk_bf16_f32 v90, v102, v103
	v_cvt_pk_bf16_f32 v91, v104, v105
	v_cvt_pk_bf16_f32 v92, v98, v99
	v_cvt_pk_bf16_f32 v93, v100, v101
	global_store_dwordx4 v[94:95], v[90:93], off sc1 nt
	s_nop 2
	v_cvt_pk_bf16_f32 v78, v78, v79
	v_cvt_pk_bf16_f32 v79, v80, v81
	v_cvt_pk_bf16_f32 v80, v74, v75
	v_lshl_add_u64 v[74:75], v[94:95], 0, s[0:1]
	v_cvt_pk_bf16_f32 v81, v76, v77
	global_store_dwordx4 v[74:75], v[78:81], off sc1 nt
	s_nop 2
	v_or_b32_e32 v74, 48, v138
	v_ashrrev_i32_e32 v75, 31, v74
	v_lshlrev_b64 v[74:75], 11, v[74:75]
	v_lshl_add_u64 v[78:79], v[140:141], 0, v[74:75]
	v_cvt_pk_bf16_f32 v74, v86, v87
	v_cvt_pk_bf16_f32 v75, v88, v89
	v_cvt_pk_bf16_f32 v76, v82, v83
	v_cvt_pk_bf16_f32 v77, v84, v85
	global_store_dwordx4 v[78:79], v[74:77], off sc1 nt
	s_nop 2
	v_cvt_pk_bf16_f32 v70, v70, v71
	v_cvt_pk_bf16_f32 v71, v72, v73
	v_cvt_pk_bf16_f32 v72, v66, v67
	v_cvt_pk_bf16_f32 v73, v68, v69
	v_lshl_add_u64 v[66:67], v[78:79], 0, s[0:1]
	global_store_dwordx4 v[66:67], v[70:73], off sc1 nt
	s_nop 2
	s_mov_b64 s[0:1], 0x40000
	v_lshl_add_u64 v[66:67], v[142:143], 0, s[0:1]
	v_cvt_pk_bf16_f32 v62, v62, v63
	v_cvt_pk_bf16_f32 v63, v64, v65
	v_cvt_pk_bf16_f32 v64, v58, v59
	v_cvt_pk_bf16_f32 v65, v60, v61
	global_store_dwordx4 v[66:67], v[62:65], off sc1 nt
	s_nop 2
	s_mov_b64 s[0:1], 0x40100
	v_cvt_pk_bf16_f32 v46, v46, v47
	v_cvt_pk_bf16_f32 v47, v48, v49
	v_cvt_pk_bf16_f32 v48, v42, v43
	v_cvt_pk_bf16_f32 v49, v44, v45
	v_lshl_add_u64 v[42:43], v[142:143], 0, s[0:1]
	global_store_dwordx4 v[42:43], v[46:49], off sc1 nt
	s_nop 2
	s_mov_b64 s[0:1], 0x48000
	v_lshl_add_u64 v[46:47], v[142:143], 0, s[0:1]
	v_cvt_pk_bf16_f32 v42, v54, v55
	v_cvt_pk_bf16_f32 v43, v56, v57
	v_cvt_pk_bf16_f32 v44, v50, v51
	v_cvt_pk_bf16_f32 v45, v52, v53
	global_store_dwordx4 v[46:47], v[42:45], off sc1 nt
	s_nop 2
	s_mov_b64 s[0:1], 0x48100
	v_cvt_pk_bf16_f32 v30, v30, v31
	v_cvt_pk_bf16_f32 v31, v32, v33
	v_cvt_pk_bf16_f32 v32, v26, v27
	v_cvt_pk_bf16_f32 v33, v28, v29
	v_lshl_add_u64 v[26:27], v[142:143], 0, s[0:1]
	global_store_dwordx4 v[26:27], v[30:33], off sc1 nt
	s_nop 2
	s_mov_b64 s[0:1], 0x50000
	v_lshl_add_u64 v[30:31], v[142:143], 0, s[0:1]
	v_cvt_pk_bf16_f32 v26, v38, v39
	v_cvt_pk_bf16_f32 v27, v40, v41
	v_cvt_pk_bf16_f32 v28, v34, v35
	v_cvt_pk_bf16_f32 v29, v36, v37
	global_store_dwordx4 v[30:31], v[26:29], off sc1 nt
	s_nop 2
	s_mov_b64 s[0:1], 0x50100
	v_cvt_pk_bf16_f32 v14, v14, v15
	v_cvt_pk_bf16_f32 v15, v16, v17
	v_cvt_pk_bf16_f32 v16, v10, v11
	v_cvt_pk_bf16_f32 v17, v12, v13
	v_lshl_add_u64 v[10:11], v[142:143], 0, s[0:1]
	global_store_dwordx4 v[10:11], v[14:17], off sc1 nt
	s_nop 2
	s_mov_b64 s[0:1], 0x58000
	v_lshl_add_u64 v[14:15], v[142:143], 0, s[0:1]
	v_cvt_pk_bf16_f32 v10, v22, v23
	v_cvt_pk_bf16_f32 v11, v24, v25
	v_cvt_pk_bf16_f32 v12, v18, v19
	v_cvt_pk_bf16_f32 v13, v20, v21
	global_store_dwordx4 v[14:15], v[10:13], off sc1 nt
	s_nop 2
	s_mov_b64 s[0:1], 0x58100
	v_cvt_pk_bf16_f32 v6, v6, v7
	v_cvt_pk_bf16_f32 v7, v8, v9
	v_cvt_pk_bf16_f32 v8, v2, v3
	v_cvt_pk_bf16_f32 v9, v4, v5
	v_lshl_add_u64 v[2:3], v[142:143], 0, s[0:1]
	global_store_dwordx4 v[2:3], v[6:9], off sc1 nt
	s_nop 2
	s_andn2_b64 vcc, exec, s[2:3]
	s_mov_b64 s[2:3], -1
	v_readlane_b32 s33, v255, 7
	s_mov_b32 s92, 0x3a800000
	s_movk_i32 s95, 0x2c00
	s_movk_i32 s93, 0x1000
	s_movk_i32 s91, 0x1600
	s_mov_b64 s[86:87], 0x300
	s_cbranch_vccnz .LBB0_217
	s_andn2_b64 vcc, exec, s[4:5]
	s_cbranch_vccnz .LBB0_216
	s_barrier
	s_branch .LBB0_216

; __device__ __forceinline__ unsigned cvtpk(float lo, float hi) { f32x2 v = {lo, hi}; bf16x2_t b = __builtin_convertvector(v, bf16x2_t); return __builtin_bit_cast(unsigned, b); }
; __device__ __forceinline__ float sigmoidf_(float v) { return __builtin_amdgcn_rcpf(1.0f + __expf(-v)); }
; __device__ __forceinline__ void st16_wt(void* p, u32x4 v) { asm volatile("global_store_dwordx4 %0, %1, off sc1\n\ts_nop 2" :: "v"(p), "v"(v) : "memory"); }
; #define EPI_LOOP_ROWS for (int ai = 0; ai < 2; ++ai) _Pragma("unroll") for (int m = 0; m < 4; ++m)
;     __device__ __forceinline__ void operator()(const f32x4 (&acc)[2][2][4][2], const Unit& u, int wv) const {
;     ...
;         EPI_LOOP_ROWS { bf16_t* rowp = base + (size_t)(row0 + ai * HALF + m * 16) * ldc + col0;
;             const float rstd = rs[ai][m];
;             float ssm = 0.f;
; #pragma unroll
;             for (int bj = 0; bj < 2; ++bj) { f32x4 v0 = acc[ai][bj][m][0] * rstd, v1 = acc[ai][bj][m][1] * rstd;
;                 if (RSM && (u.pn == 0 || (u.pn == 1 && bj == 0))) ssm += ((v0[0] * v0[0] + v0[1] * v0[1]) + (v0[2] * v0[2] + v0[3] * v0[3])) + ((v1[0] * v1[0] + v1[1] * v1[1]) + (v1[2] * v1[2] + v1[3] * v1[3]));
;                 if (gate) {
; #pragma unroll
;                     for (int e = 0; e < 4; ++e) { v0[e] = sigmoidf_(v0[e]); v1[e] = sigmoidf_(v1[e]); } }
;                 u32x4 w; w.x = cvtpk(v0[0], v0[1]); w.y = cvtpk(v0[2], v0[3]); w.z = cvtpk(v1[0], v1[1]); w.w = cvtpk(v1[2], v1[3]);
;                 st16_wt(rowp + bj * HALF, w); }
.LBB0_311:
	s_lshr_b32 s0, s10, 1
	s_and_b32 s0, s0, 0x60
	s_lshl_b32 s1, s76, 8
	v_bfe_u32 v0, v183, 4, 2
	s_or_b32 s0, s0, s1
	v_lshl_or_b32 v122, v0, 3, s0
	v_ashrrev_i32_e32 v123, 31, v122
	v_lshl_add_u64 v[156:157], v[122:123], 1, s[8:9]
	v_lshlrev_b64 v[122:123], 13, v[174:175]
	v_lshl_add_u64 v[174:175], v[156:157], 0, v[122:123]
	v_cvt_pk_bf16_f32 v122, v130, v131
	v_cvt_pk_bf16_f32 v123, v132, v133
	v_cvt_pk_bf16_f32 v124, v134, v135
	v_cvt_pk_bf16_f32 v125, v136, v137
	global_store_dwordx4 v[174:175], v[122:125], off sc1 nt
	s_nop 2
	v_mov_b32_e32 v183, v182
	v_mov_b32_e32 v122, v182
	v_mov_b32_e32 v123, v182
	v_pk_mul_f32 v[120:121], v[120:121], v[122:123]
	v_pk_mul_f32 v[118:119], v[118:119], v[182:183]
	v_pk_mul_f32 v[116:117], v[116:117], v[122:123]
	v_pk_mul_f32 v[114:115], v[114:115], v[182:183]
	s_mov_b64 s[76:77], -1
	s_and_b64 vcc, exec, s[74:75]
	s_cbranch_vccz .LBB0_313
	v_mul_f32_e32 v0, 0xbfb8aa3b, v118
	v_exp_f32_e32 v0, v0
	v_mul_f32_e32 v122, 0xbfb8aa3b, v114
	v_exp_f32_e32 v122, v122
	v_mul_f32_e32 v124, 0xbfb8aa3b, v115
	v_add_f32_e32 v0, 1.0, v0
	v_exp_f32_e32 v124, v124
	v_add_f32_e32 v123, 1.0, v122
	v_rcp_f32_e32 v122, v0
	v_mul_f32_e32 v0, 0xbfb8aa3b, v119
	v_exp_f32_e32 v0, v0
	v_rcp_f32_e32 v126, v123
	v_mul_f32_e32 v125, 0xbfb8aa3b, v116
	v_exp_f32_e32 v125, v125
	v_add_f32_e32 v0, 1.0, v0
	v_rcp_f32_e32 v123, v0
	v_add_f32_e32 v0, 1.0, v124
	v_mul_f32_e32 v124, 0xbfb8aa3b, v120
	v_exp_f32_e32 v124, v124
	v_rcp_f32_e32 v127, v0
	v_mul_f32_e32 v128, 0xbfb8aa3b, v117
	v_exp_f32_e32 v129, v128
	v_add_f32_e32 v0, 1.0, v124
	v_rcp_f32_e32 v124, v0
	v_add_f32_e32 v0, 1.0, v125
	v_mul_f32_e32 v125, 0xbfb8aa3b, v121
	v_exp_f32_e32 v125, v125
	v_rcp_f32_e32 v128, v0
	s_mov_b64 s[76:77], 0
	v_add_f32_e32 v0, 1.0, v125
	v_rcp_f32_e32 v125, v0
	v_add_f32_e32 v0, 1.0, v129
	v_rcp_f32_e32 v129, v0

; __device__ __forceinline__ unsigned cvtpk(float lo, float hi) { f32x2 v = {lo, hi}; bf16x2_t b = __builtin_convertvector(v, bf16x2_t); return __builtin_bit_cast(unsigned, b); }
; __device__ __forceinline__ float shx(float v, int o, int lane) { return __builtin_bit_cast(float, __builtin_amdgcn_ds_bpermute((lane ^ o) << 2, __builtin_bit_cast(int, v))); }
; __device__ __forceinline__ float sigmoidf_(float v) { return __builtin_amdgcn_rcpf(1.0f + __expf(-v)); }
; __device__ __forceinline__ void st16_wt(void* p, u32x4 v) { asm volatile("global_store_dwordx4 %0, %1, off sc1\n\ts_nop 2" :: "v"(p), "v"(v) : "memory"); }
; #define EPI_LOOP_ROWS for (int ai = 0; ai < 2; ++ai) _Pragma("unroll") for (int m = 0; m < 4; ++m)
; __device__ __forceinline__ float row_rstd_fin(float s, int lane) { s += shx(s, 16, lane); s += shx(s, 32, lane); return rsqrtf(s * (1.0f / 1024.0f) + EPS); }
;     __device__ __forceinline__ void operator()(const f32x4 (&acc)[2][2][4][2], const Unit& u, int wv) const {
;     ...
;         EPI_LOOP_ROWS { bf16_t* rowp = base + (size_t)(row0 + ai * HALF + m * 16) * ldc + col0;
;             const float rstd = rs[ai][m];
;             float ssm = 0.f;
; #pragma unroll
;             for (int bj = 0; bj < 2; ++bj) { f32x4 v0 = acc[ai][bj][m][0] * rstd, v1 = acc[ai][bj][m][1] * rstd;
;                 if (RSM && (u.pn == 0 || (u.pn == 1 && bj == 0))) ssm += ((v0[0] * v0[0] + v0[1] * v0[1]) + (v0[2] * v0[2] + v0[3] * v0[3])) + ((v1[0] * v1[0] + v1[1] * v1[1]) + (v1[2] * v1[2] + v1[3] * v1[3]));
;                 if (gate) {
; #pragma unroll
;                     for (int e = 0; e < 4; ++e) { v0[e] = sigmoidf_(v0[e]); v1[e] = sigmoidf_(v1[e]); } }
;                 u32x4 w; w.x = cvtpk(v0[0], v0[1]); w.y = cvtpk(v0[2], v0[3]); w.z = cvtpk(v1[0], v1[1]); w.w = cvtpk(v1[2], v1[3]);
;                 st16_wt(rowp + bj * HALF, w); }
.LBB0_315:
	v_mul_f32_e32 v0, 0x4b800000, v180
	v_cndmask_b32_e64 v0, v180, v0, s[4:5]
	v_rsq_f32_e32 v0, v0
	s_mov_b64 s[0:1], 0x100
	v_cvt_pk_bf16_f32 v114, v122, v123
	v_cvt_pk_bf16_f32 v115, v124, v125
	v_mul_f32_e32 v117, 0x45800000, v0
	v_cvt_pk_bf16_f32 v116, v126, v127
	v_cndmask_b32_e64 v124, v0, v117, s[4:5]
	v_cvt_pk_bf16_f32 v117, v128, v129
	v_lshl_add_u64 v[118:119], v[174:175], 0, s[0:1]
	global_store_dwordx4 v[118:119], v[114:117], off sc1 nt
	s_nop 2
	v_pk_mul_f32 v[112:113], v[112:113], v[124:125] op_sel_hi:[1,0]
	v_pk_mul_f32 v[110:111], v[110:111], v[124:125] op_sel_hi:[1,0]
	v_pk_mul_f32 v[108:109], v[108:109], v[124:125] op_sel_hi:[1,0]
	v_pk_mul_f32 v[106:107], v[106:107], v[124:125] op_sel_hi:[1,0]
	s_mov_b64 s[4:5], -1
	s_and_b64 vcc, exec, s[74:75]
	s_cbranch_vccz .LBB0_317
	v_mul_f32_e32 v0, 0xbfb8aa3b, v110
	v_exp_f32_e32 v0, v0
	v_mul_f32_e32 v114, 0xbfb8aa3b, v106
	v_exp_f32_e32 v114, v114
	v_mul_f32_e32 v116, 0xbfb8aa3b, v107
	v_add_f32_e32 v0, 1.0, v0
	v_exp_f32_e32 v116, v116
	v_add_f32_e32 v115, 1.0, v114
	v_rcp_f32_e32 v114, v0
	v_mul_f32_e32 v0, 0xbfb8aa3b, v111
	v_exp_f32_e32 v0, v0
	v_rcp_f32_e32 v118, v115
	v_mul_f32_e32 v117, 0xbfb8aa3b, v108
	v_exp_f32_e32 v117, v117
	v_add_f32_e32 v0, 1.0, v0
	v_rcp_f32_e32 v115, v0
	v_add_f32_e32 v0, 1.0, v116
	v_mul_f32_e32 v116, 0xbfb8aa3b, v112
	v_exp_f32_e32 v116, v116
	v_rcp_f32_e32 v119, v0
	v_mul_f32_e32 v120, 0xbfb8aa3b, v109
	v_exp_f32_e32 v121, v120
	v_add_f32_e32 v0, 1.0, v116
	v_rcp_f32_e32 v116, v0
	v_add_f32_e32 v0, 1.0, v117
	v_mul_f32_e32 v117, 0xbfb8aa3b, v113
	v_exp_f32_e32 v117, v117
	v_rcp_f32_e32 v120, v0
	s_mov_b64 s[4:5], 0
	v_add_f32_e32 v0, 1.0, v117
	v_rcp_f32_e32 v117, v0
	v_add_f32_e32 v0, 1.0, v121
	v_rcp_f32_e32 v121, v0

; __device__ __forceinline__ unsigned cvtpk(float lo, float hi) { f32x2 v = {lo, hi}; bf16x2_t b = __builtin_convertvector(v, bf16x2_t); return __builtin_bit_cast(unsigned, b); }
; __device__ __forceinline__ float sigmoidf_(float v) { return __builtin_amdgcn_rcpf(1.0f + __expf(-v)); }
; __device__ __forceinline__ void st16_wt(void* p, u32x4 v) { asm volatile("global_store_dwordx4 %0, %1, off sc1\n\ts_nop 2" :: "v"(p), "v"(v) : "memory"); }
; #define EPI_LOOP_ROWS for (int ai = 0; ai < 2; ++ai) _Pragma("unroll") for (int m = 0; m < 4; ++m)
;     __device__ __forceinline__ void operator()(const f32x4 (&acc)[2][2][4][2], const Unit& u, int wv) const {
;     ...
;         EPI_LOOP_ROWS { bf16_t* rowp = base + (size_t)(row0 + ai * HALF + m * 16) * ldc + col0;
;             const float rstd = rs[ai][m];
;             float ssm = 0.f;
; #pragma unroll
;             for (int bj = 0; bj < 2; ++bj) { f32x4 v0 = acc[ai][bj][m][0] * rstd, v1 = acc[ai][bj][m][1] * rstd;
;                 if (RSM && (u.pn == 0 || (u.pn == 1 && bj == 0))) ssm += ((v0[0] * v0[0] + v0[1] * v0[1]) + (v0[2] * v0[2] + v0[3] * v0[3])) + ((v1[0] * v1[0] + v1[1] * v1[1]) + (v1[2] * v1[2] + v1[3] * v1[3]));
;                 if (gate) {
; #pragma unroll
;                     for (int e = 0; e < 4; ++e) { v0[e] = sigmoidf_(v0[e]); v1[e] = sigmoidf_(v1[e]); } }
;                 u32x4 w; w.x = cvtpk(v0[0], v0[1]); w.y = cvtpk(v0[2], v0[3]); w.z = cvtpk(v1[0], v1[1]); w.w = cvtpk(v1[2], v1[3]);
;                 st16_wt(rowp + bj * HALF, w); }
.LBB0_319:
	v_lshlrev_b64 v[106:107], 13, v[172:173]
	v_lshl_add_u64 v[122:123], v[156:157], 0, v[106:107]
	v_cvt_pk_bf16_f32 v106, v114, v115
	v_cvt_pk_bf16_f32 v107, v116, v117
	v_cvt_pk_bf16_f32 v108, v118, v119
	v_cvt_pk_bf16_f32 v109, v120, v121
	global_store_dwordx4 v[122:123], v[106:109], off sc1 nt
	s_nop 2
	v_mov_b32_e32 v125, v124
	v_mov_b32_e32 v106, v124
	v_mov_b32_e32 v107, v124
	v_pk_mul_f32 v[104:105], v[104:105], v[106:107]
	v_pk_mul_f32 v[102:103], v[102:103], v[124:125]
	v_pk_mul_f32 v[100:101], v[100:101], v[106:107]
	v_pk_mul_f32 v[98:99], v[98:99], v[124:125]
	s_mov_b64 s[4:5], -1
	s_and_b64 vcc, exec, s[74:75]
	s_cbranch_vccz .LBB0_321
	v_mul_f32_e32 v0, 0xbfb8aa3b, v102
	v_exp_f32_e32 v0, v0
	v_mul_f32_e32 v106, 0xbfb8aa3b, v98
	v_exp_f32_e32 v106, v106
	v_mul_f32_e32 v108, 0xbfb8aa3b, v99
	v_add_f32_e32 v0, 1.0, v0
	v_exp_f32_e32 v108, v108
	v_add_f32_e32 v107, 1.0, v106
	v_rcp_f32_e32 v106, v0
	v_mul_f32_e32 v0, 0xbfb8aa3b, v103
	v_exp_f32_e32 v0, v0
	v_rcp_f32_e32 v110, v107
	v_mul_f32_e32 v109, 0xbfb8aa3b, v100
	v_exp_f32_e32 v109, v109
	v_add_f32_e32 v0, 1.0, v0
	v_rcp_f32_e32 v107, v0
	v_add_f32_e32 v0, 1.0, v108
	v_mul_f32_e32 v108, 0xbfb8aa3b, v104
	v_exp_f32_e32 v108, v108
	v_rcp_f32_e32 v111, v0
	v_mul_f32_e32 v112, 0xbfb8aa3b, v101
	v_exp_f32_e32 v113, v112
	v_add_f32_e32 v0, 1.0, v108
	v_rcp_f32_e32 v108, v0
	v_add_f32_e32 v0, 1.0, v109
	v_mul_f32_e32 v109, 0xbfb8aa3b, v105
	v_exp_f32_e32 v109, v109
	v_rcp_f32_e32 v112, v0
	s_mov_b64 s[4:5], 0
	v_add_f32_e32 v0, 1.0, v109
	v_rcp_f32_e32 v109, v0
	v_add_f32_e32 v0, 1.0, v113
	v_rcp_f32_e32 v113, v0

; __device__ __forceinline__ unsigned cvtpk(float lo, float hi) { f32x2 v = {lo, hi}; bf16x2_t b = __builtin_convertvector(v, bf16x2_t); return __builtin_bit_cast(unsigned, b); }
; __device__ __forceinline__ float shx(float v, int o, int lane) { return __builtin_bit_cast(float, __builtin_amdgcn_ds_bpermute((lane ^ o) << 2, __builtin_bit_cast(int, v))); }
; __device__ __forceinline__ float sigmoidf_(float v) { return __builtin_amdgcn_rcpf(1.0f + __expf(-v)); }
; __device__ __forceinline__ void st16_wt(void* p, u32x4 v) { asm volatile("global_store_dwordx4 %0, %1, off sc1\n\ts_nop 2" :: "v"(p), "v"(v) : "memory"); }
; #define EPI_LOOP_ROWS for (int ai = 0; ai < 2; ++ai) _Pragma("unroll") for (int m = 0; m < 4; ++m)
; __device__ __forceinline__ float row_rstd_fin(float s, int lane) { s += shx(s, 16, lane); s += shx(s, 32, lane); return rsqrtf(s * (1.0f / 1024.0f) + EPS); }
;     __device__ __forceinline__ void operator()(const f32x4 (&acc)[2][2][4][2], const Unit& u, int wv) const {
;     ...
;         EPI_LOOP_ROWS { bf16_t* rowp = base + (size_t)(row0 + ai * HALF + m * 16) * ldc + col0;
;             const float rstd = rs[ai][m];
;             float ssm = 0.f;
; #pragma unroll
;             for (int bj = 0; bj < 2; ++bj) { f32x4 v0 = acc[ai][bj][m][0] * rstd, v1 = acc[ai][bj][m][1] * rstd;
;                 if (RSM && (u.pn == 0 || (u.pn == 1 && bj == 0))) ssm += ((v0[0] * v0[0] + v0[1] * v0[1]) + (v0[2] * v0[2] + v0[3] * v0[3])) + ((v1[0] * v1[0] + v1[1] * v1[1]) + (v1[2] * v1[2] + v1[3] * v1[3]));
;                 if (gate) {
; #pragma unroll
;                     for (int e = 0; e < 4; ++e) { v0[e] = sigmoidf_(v0[e]); v1[e] = sigmoidf_(v1[e]); } }
;                 u32x4 w; w.x = cvtpk(v0[0], v0[1]); w.y = cvtpk(v0[2], v0[3]); w.z = cvtpk(v1[0], v1[1]); w.w = cvtpk(v1[2], v1[3]);
;                 st16_wt(rowp + bj * HALF, w); }
.LBB0_323:
	v_pk_add_f32 v[98:99], v[176:177], v[178:179]
	v_cvt_pk_bf16_f32 v100, v110, v111
	v_pk_fma_f32 v[114:115], v[98:99], s[92:93], v[194:195] op_sel_hi:[1,0,0]
	v_cvt_pk_bf16_f32 v98, v106, v107
	v_mul_f32_e32 v0, 0x4b800000, v115
	v_cmp_gt_f32_e32 vcc, s97, v115
	v_cvt_pk_bf16_f32 v101, v112, v113
	v_lshl_add_u64 v[102:103], v[122:123], 0, s[0:1]
	v_cndmask_b32_e32 v0, v115, v0, vcc
	v_rsq_f32_e32 v0, v0
	v_cmp_gt_f32_e64 s[4:5], s97, v114
	s_mov_b64 s[76:77], -1
	v_mul_f32_e32 v99, 0x45800000, v0
	v_cndmask_b32_e32 v106, v0, v99, vcc
	v_cvt_pk_bf16_f32 v99, v108, v109
	global_store_dwordx4 v[102:103], v[98:101], off sc1 nt
	s_nop 2
	v_pk_mul_f32 v[96:97], v[96:97], v[106:107] op_sel_hi:[1,0]
	v_pk_mul_f32 v[94:95], v[94:95], v[106:107] op_sel_hi:[1,0]
	v_pk_mul_f32 v[92:93], v[92:93], v[106:107] op_sel_hi:[1,0]
	v_pk_mul_f32 v[90:91], v[90:91], v[106:107] op_sel_hi:[1,0]
	s_and_b64 vcc, exec, s[74:75]
	s_cbranch_vccz .LBB0_325
	v_mul_f32_e32 v0, 0xbfb8aa3b, v94
	v_exp_f32_e32 v0, v0
	v_mul_f32_e32 v98, 0xbfb8aa3b, v90
	v_exp_f32_e32 v98, v98
	v_mul_f32_e32 v100, 0xbfb8aa3b, v91
	v_add_f32_e32 v0, 1.0, v0
	v_exp_f32_e32 v100, v100
	v_add_f32_e32 v99, 1.0, v98
	v_rcp_f32_e32 v98, v0
	v_mul_f32_e32 v0, 0xbfb8aa3b, v95
	v_exp_f32_e32 v0, v0
	v_rcp_f32_e32 v102, v99
	v_mul_f32_e32 v101, 0xbfb8aa3b, v92
	v_exp_f32_e32 v101, v101
	v_add_f32_e32 v0, 1.0, v0
	v_rcp_f32_e32 v99, v0
	v_add_f32_e32 v0, 1.0, v100
	v_mul_f32_e32 v100, 0xbfb8aa3b, v96
	v_exp_f32_e32 v100, v100
	v_rcp_f32_e32 v103, v0
	v_mul_f32_e32 v104, 0xbfb8aa3b, v93
	v_exp_f32_e32 v105, v104
	v_add_f32_e32 v0, 1.0, v100
	v_rcp_f32_e32 v100, v0
	v_add_f32_e32 v0, 1.0, v101
	v_mul_f32_e32 v101, 0xbfb8aa3b, v97
	v_exp_f32_e32 v101, v101
	v_rcp_f32_e32 v104, v0
	s_mov_b64 s[76:77], 0
	v_add_f32_e32 v0, 1.0, v101
	v_rcp_f32_e32 v101, v0
	v_add_f32_e32 v0, 1.0, v105
	v_rcp_f32_e32 v105, v0

; __device__ __forceinline__ unsigned cvtpk(float lo, float hi) { f32x2 v = {lo, hi}; bf16x2_t b = __builtin_convertvector(v, bf16x2_t); return __builtin_bit_cast(unsigned, b); }
; __device__ __forceinline__ float sigmoidf_(float v) { return __builtin_amdgcn_rcpf(1.0f + __expf(-v)); }
; __device__ __forceinline__ void st16_wt(void* p, u32x4 v) { asm volatile("global_store_dwordx4 %0, %1, off sc1\n\ts_nop 2" :: "v"(p), "v"(v) : "memory"); }
; #define EPI_LOOP_ROWS for (int ai = 0; ai < 2; ++ai) _Pragma("unroll") for (int m = 0; m < 4; ++m)
;     __device__ __forceinline__ void operator()(const f32x4 (&acc)[2][2][4][2], const Unit& u, int wv) const {
;     ...
;         EPI_LOOP_ROWS { bf16_t* rowp = base + (size_t)(row0 + ai * HALF + m * 16) * ldc + col0;
;             const float rstd = rs[ai][m];
;             float ssm = 0.f;
; #pragma unroll
;             for (int bj = 0; bj < 2; ++bj) { f32x4 v0 = acc[ai][bj][m][0] * rstd, v1 = acc[ai][bj][m][1] * rstd;
;                 if (RSM && (u.pn == 0 || (u.pn == 1 && bj == 0))) ssm += ((v0[0] * v0[0] + v0[1] * v0[1]) + (v0[2] * v0[2] + v0[3] * v0[3])) + ((v1[0] * v1[0] + v1[1] * v1[1]) + (v1[2] * v1[2] + v1[3] * v1[3]));
;                 if (gate) {
; #pragma unroll
;                     for (int e = 0; e < 4; ++e) { v0[e] = sigmoidf_(v0[e]); v1[e] = sigmoidf_(v1[e]); } }
;                 u32x4 w; w.x = cvtpk(v0[0], v0[1]); w.y = cvtpk(v0[2], v0[3]); w.z = cvtpk(v1[0], v1[1]); w.w = cvtpk(v1[2], v1[3]);
;                 st16_wt(rowp + bj * HALF, w); }
.LBB0_327:
	v_lshlrev_b64 v[90:91], 13, v[166:167]
	v_lshl_add_u64 v[108:109], v[156:157], 0, v[90:91]
	v_cvt_pk_bf16_f32 v90, v98, v99
	v_cvt_pk_bf16_f32 v91, v100, v101
	v_cvt_pk_bf16_f32 v92, v102, v103
	v_cvt_pk_bf16_f32 v93, v104, v105
	global_store_dwordx4 v[108:109], v[90:93], off sc1 nt
	s_nop 2
	v_mov_b32_e32 v107, v106
	v_mov_b32_e32 v90, v106
	v_mov_b32_e32 v91, v106
	v_pk_mul_f32 v[88:89], v[88:89], v[90:91]
	v_pk_mul_f32 v[86:87], v[86:87], v[106:107]
	v_pk_mul_f32 v[84:85], v[84:85], v[90:91]
	v_pk_mul_f32 v[82:83], v[82:83], v[106:107]
	s_mov_b64 s[76:77], -1
	s_and_b64 vcc, exec, s[74:75]
	s_cbranch_vccz .LBB0_329
	v_mul_f32_e32 v0, 0xbfb8aa3b, v86
	v_exp_f32_e32 v0, v0
	v_mul_f32_e32 v90, 0xbfb8aa3b, v82
	v_exp_f32_e32 v90, v90
	v_mul_f32_e32 v92, 0xbfb8aa3b, v83
	v_add_f32_e32 v0, 1.0, v0
	v_exp_f32_e32 v92, v92
	v_add_f32_e32 v91, 1.0, v90
	v_rcp_f32_e32 v90, v0
	v_mul_f32_e32 v0, 0xbfb8aa3b, v87
	v_exp_f32_e32 v0, v0
	v_rcp_f32_e32 v94, v91
	v_mul_f32_e32 v93, 0xbfb8aa3b, v84
	v_exp_f32_e32 v93, v93
	v_add_f32_e32 v0, 1.0, v0
	v_rcp_f32_e32 v91, v0
	v_add_f32_e32 v0, 1.0, v92
	v_mul_f32_e32 v92, 0xbfb8aa3b, v88
	v_exp_f32_e32 v92, v92
	v_rcp_f32_e32 v95, v0
	v_mul_f32_e32 v96, 0xbfb8aa3b, v85
	v_exp_f32_e32 v97, v96
	v_add_f32_e32 v0, 1.0, v92
	v_rcp_f32_e32 v92, v0
	v_add_f32_e32 v0, 1.0, v93
	v_mul_f32_e32 v93, 0xbfb8aa3b, v89
	v_exp_f32_e32 v93, v93
	v_rcp_f32_e32 v96, v0
	s_mov_b64 s[76:77], 0
	v_add_f32_e32 v0, 1.0, v93
	v_rcp_f32_e32 v93, v0
	v_add_f32_e32 v0, 1.0, v97
	v_rcp_f32_e32 v97, v0

; __device__ __forceinline__ unsigned cvtpk(float lo, float hi) { f32x2 v = {lo, hi}; bf16x2_t b = __builtin_convertvector(v, bf16x2_t); return __builtin_bit_cast(unsigned, b); }
; __device__ __forceinline__ float shx(float v, int o, int lane) { return __builtin_bit_cast(float, __builtin_amdgcn_ds_bpermute((lane ^ o) << 2, __builtin_bit_cast(int, v))); }
; __device__ __forceinline__ float sigmoidf_(float v) { return __builtin_amdgcn_rcpf(1.0f + __expf(-v)); }
; __device__ __forceinline__ void st16_wt(void* p, u32x4 v) { asm volatile("global_store_dwordx4 %0, %1, off sc1\n\ts_nop 2" :: "v"(p), "v"(v) : "memory"); }
; #define EPI_LOOP_ROWS for (int ai = 0; ai < 2; ++ai) _Pragma("unroll") for (int m = 0; m < 4; ++m)
; __device__ __forceinline__ float row_rstd_fin(float s, int lane) { s += shx(s, 16, lane); s += shx(s, 32, lane); return rsqrtf(s * (1.0f / 1024.0f) + EPS); }
;     __device__ __forceinline__ void operator()(const f32x4 (&acc)[2][2][4][2], const Unit& u, int wv) const {
;     ...
;         EPI_LOOP_ROWS { bf16_t* rowp = base + (size_t)(row0 + ai * HALF + m * 16) * ldc + col0;
;             const float rstd = rs[ai][m];
;             float ssm = 0.f;
; #pragma unroll
;             for (int bj = 0; bj < 2; ++bj) { f32x4 v0 = acc[ai][bj][m][0] * rstd, v1 = acc[ai][bj][m][1] * rstd;
;                 if (RSM && (u.pn == 0 || (u.pn == 1 && bj == 0))) ssm += ((v0[0] * v0[0] + v0[1] * v0[1]) + (v0[2] * v0[2] + v0[3] * v0[3])) + ((v1[0] * v1[0] + v1[1] * v1[1]) + (v1[2] * v1[2] + v1[3] * v1[3]));
;                 if (gate) {
; #pragma unroll
;                     for (int e = 0; e < 4; ++e) { v0[e] = sigmoidf_(v0[e]); v1[e] = sigmoidf_(v1[e]); } }
;                 u32x4 w; w.x = cvtpk(v0[0], v0[1]); w.y = cvtpk(v0[2], v0[3]); w.z = cvtpk(v1[0], v1[1]); w.w = cvtpk(v1[2], v1[3]);
;                 st16_wt(rowp + bj * HALF, w); }
.LBB0_331:
	v_mul_f32_e32 v0, 0x4b800000, v114
	v_cndmask_b32_e64 v0, v114, v0, s[4:5]
	v_rsq_f32_e32 v0, v0
	v_cvt_pk_bf16_f32 v82, v90, v91
	v_cvt_pk_bf16_f32 v83, v92, v93
	v_cvt_pk_bf16_f32 v84, v94, v95
	v_mul_f32_e32 v85, 0x45800000, v0
	v_cndmask_b32_e64 v92, v0, v85, s[4:5]
	v_cvt_pk_bf16_f32 v85, v96, v97
	v_lshl_add_u64 v[86:87], v[108:109], 0, s[0:1]
	global_store_dwordx4 v[86:87], v[82:85], off sc1 nt
	s_nop 2
	v_pk_mul_f32 v[80:81], v[80:81], v[92:93] op_sel_hi:[1,0]
	v_pk_mul_f32 v[78:79], v[78:79], v[92:93] op_sel_hi:[1,0]
	v_pk_mul_f32 v[76:77], v[76:77], v[92:93] op_sel_hi:[1,0]
	v_pk_mul_f32 v[74:75], v[74:75], v[92:93] op_sel_hi:[1,0]
	s_mov_b64 s[4:5], -1
	s_and_b64 vcc, exec, s[74:75]
	s_cbranch_vccz .LBB0_333
	v_mul_f32_e32 v0, 0xbfb8aa3b, v78
	v_exp_f32_e32 v0, v0
	v_mul_f32_e32 v82, 0xbfb8aa3b, v74
	v_exp_f32_e32 v82, v82
	v_mul_f32_e32 v84, 0xbfb8aa3b, v75
	v_add_f32_e32 v0, 1.0, v0
	v_exp_f32_e32 v84, v84
	v_add_f32_e32 v83, 1.0, v82
	v_rcp_f32_e32 v82, v0
	v_mul_f32_e32 v0, 0xbfb8aa3b, v79
	v_exp_f32_e32 v0, v0
	v_rcp_f32_e32 v86, v83
	v_mul_f32_e32 v85, 0xbfb8aa3b, v76
	v_exp_f32_e32 v85, v85
	v_add_f32_e32 v0, 1.0, v0
	v_rcp_f32_e32 v83, v0
	v_add_f32_e32 v0, 1.0, v84
	v_mul_f32_e32 v84, 0xbfb8aa3b, v80
	v_exp_f32_e32 v84, v84
	v_rcp_f32_e32 v87, v0
	v_mul_f32_e32 v88, 0xbfb8aa3b, v77
	v_exp_f32_e32 v89, v88
	v_add_f32_e32 v0, 1.0, v84
	v_rcp_f32_e32 v84, v0
	v_add_f32_e32 v0, 1.0, v85
	v_mul_f32_e32 v85, 0xbfb8aa3b, v81
	v_exp_f32_e32 v85, v85
	v_rcp_f32_e32 v88, v0
	s_mov_b64 s[4:5], 0
	v_add_f32_e32 v0, 1.0, v85
	v_rcp_f32_e32 v85, v0
	v_add_f32_e32 v0, 1.0, v89
	v_rcp_f32_e32 v89, v0

; __device__ __forceinline__ unsigned cvtpk(float lo, float hi) { f32x2 v = {lo, hi}; bf16x2_t b = __builtin_convertvector(v, bf16x2_t); return __builtin_bit_cast(unsigned, b); }
; __device__ __forceinline__ float sigmoidf_(float v) { return __builtin_amdgcn_rcpf(1.0f + __expf(-v)); }
; __device__ __forceinline__ void st16_wt(void* p, u32x4 v) { asm volatile("global_store_dwordx4 %0, %1, off sc1\n\ts_nop 2" :: "v"(p), "v"(v) : "memory"); }
; #define EPI_LOOP_ROWS for (int ai = 0; ai < 2; ++ai) _Pragma("unroll") for (int m = 0; m < 4; ++m)
;     __device__ __forceinline__ void operator()(const f32x4 (&acc)[2][2][4][2], const Unit& u, int wv) const {
;     ...
;         EPI_LOOP_ROWS { bf16_t* rowp = base + (size_t)(row0 + ai * HALF + m * 16) * ldc + col0;
;             const float rstd = rs[ai][m];
;             float ssm = 0.f;
; #pragma unroll
;             for (int bj = 0; bj < 2; ++bj) { f32x4 v0 = acc[ai][bj][m][0] * rstd, v1 = acc[ai][bj][m][1] * rstd;
;                 if (RSM && (u.pn == 0 || (u.pn == 1 && bj == 0))) ssm += ((v0[0] * v0[0] + v0[1] * v0[1]) + (v0[2] * v0[2] + v0[3] * v0[3])) + ((v1[0] * v1[0] + v1[1] * v1[1]) + (v1[2] * v1[2] + v1[3] * v1[3]));
;                 if (gate) {
; #pragma unroll
;                     for (int e = 0; e < 4; ++e) { v0[e] = sigmoidf_(v0[e]); v1[e] = sigmoidf_(v1[e]); } }
;                 u32x4 w; w.x = cvtpk(v0[0], v0[1]); w.y = cvtpk(v0[2], v0[3]); w.z = cvtpk(v1[0], v1[1]); w.w = cvtpk(v1[2], v1[3]);
;                 st16_wt(rowp + bj * HALF, w); }
.LBB0_335:
	v_lshlrev_b64 v[74:75], 13, v[164:165]
	v_lshl_add_u64 v[90:91], v[156:157], 0, v[74:75]
	v_cvt_pk_bf16_f32 v74, v82, v83
	v_cvt_pk_bf16_f32 v75, v84, v85
	v_cvt_pk_bf16_f32 v76, v86, v87
	v_cvt_pk_bf16_f32 v77, v88, v89
	global_store_dwordx4 v[90:91], v[74:77], off sc1 nt
	s_nop 2
	v_mov_b32_e32 v93, v92
	v_mov_b32_e32 v74, v92
	v_mov_b32_e32 v75, v92
	v_pk_mul_f32 v[72:73], v[72:73], v[74:75]
	v_pk_mul_f32 v[70:71], v[70:71], v[92:93]
	v_pk_mul_f32 v[68:69], v[68:69], v[74:75]
	v_pk_mul_f32 v[66:67], v[66:67], v[92:93]
	s_mov_b64 s[4:5], -1
	s_and_b64 vcc, exec, s[74:75]
	s_cbranch_vccz .LBB0_337
	v_mul_f32_e32 v0, 0xbfb8aa3b, v70
	v_exp_f32_e32 v0, v0
	v_mul_f32_e32 v74, 0xbfb8aa3b, v66
	v_exp_f32_e32 v74, v74
	v_mul_f32_e32 v76, 0xbfb8aa3b, v67
	v_add_f32_e32 v0, 1.0, v0
	v_exp_f32_e32 v76, v76
	v_add_f32_e32 v75, 1.0, v74
	v_rcp_f32_e32 v74, v0
	v_mul_f32_e32 v0, 0xbfb8aa3b, v71
	v_exp_f32_e32 v0, v0
	v_rcp_f32_e32 v78, v75
	v_mul_f32_e32 v77, 0xbfb8aa3b, v68
	v_exp_f32_e32 v77, v77
	v_add_f32_e32 v0, 1.0, v0
	v_rcp_f32_e32 v75, v0
	v_add_f32_e32 v0, 1.0, v76
	v_mul_f32_e32 v76, 0xbfb8aa3b, v72
	v_exp_f32_e32 v76, v76
	v_rcp_f32_e32 v79, v0
	v_mul_f32_e32 v80, 0xbfb8aa3b, v69
	v_exp_f32_e32 v81, v80
	v_add_f32_e32 v0, 1.0, v76
	v_rcp_f32_e32 v76, v0
	v_add_f32_e32 v0, 1.0, v77
	v_mul_f32_e32 v77, 0xbfb8aa3b, v73
	v_exp_f32_e32 v77, v77
	v_rcp_f32_e32 v80, v0
	s_mov_b64 s[4:5], 0
	v_add_f32_e32 v0, 1.0, v77
	v_rcp_f32_e32 v77, v0
	v_add_f32_e32 v0, 1.0, v81
	v_rcp_f32_e32 v81, v0

; __device__ __forceinline__ unsigned cvtpk(float lo, float hi) { f32x2 v = {lo, hi}; bf16x2_t b = __builtin_convertvector(v, bf16x2_t); return __builtin_bit_cast(unsigned, b); }
; __device__ __forceinline__ float shx(float v, int o, int lane) { return __builtin_bit_cast(float, __builtin_amdgcn_ds_bpermute((lane ^ o) << 2, __builtin_bit_cast(int, v))); }
; __device__ __forceinline__ float sigmoidf_(float v) { return __builtin_amdgcn_rcpf(1.0f + __expf(-v)); }
; __device__ __forceinline__ void st16_wt(void* p, u32x4 v) { asm volatile("global_store_dwordx4 %0, %1, off sc1\n\ts_nop 2" :: "v"(p), "v"(v) : "memory"); }
; #define EPI_LOOP_ROWS for (int ai = 0; ai < 2; ++ai) _Pragma("unroll") for (int m = 0; m < 4; ++m)
; __device__ __forceinline__ float row_rstd_fin(float s, int lane) { s += shx(s, 16, lane); s += shx(s, 32, lane); return rsqrtf(s * (1.0f / 1024.0f) + EPS); }
;     __device__ __forceinline__ void operator()(const f32x4 (&acc)[2][2][4][2], const Unit& u, int wv) const {
;     ...
;         EPI_LOOP_ROWS { bf16_t* rowp = base + (size_t)(row0 + ai * HALF + m * 16) * ldc + col0;
;             const float rstd = rs[ai][m];
;             float ssm = 0.f;
; #pragma unroll
;             for (int bj = 0; bj < 2; ++bj) { f32x4 v0 = acc[ai][bj][m][0] * rstd, v1 = acc[ai][bj][m][1] * rstd;
;                 if (RSM && (u.pn == 0 || (u.pn == 1 && bj == 0))) ssm += ((v0[0] * v0[0] + v0[1] * v0[1]) + (v0[2] * v0[2] + v0[3] * v0[3])) + ((v1[0] * v1[0] + v1[1] * v1[1]) + (v1[2] * v1[2] + v1[3] * v1[3]));
;                 if (gate) {
; #pragma unroll
;                     for (int e = 0; e < 4; ++e) { v0[e] = sigmoidf_(v0[e]); v1[e] = sigmoidf_(v1[e]); } }
;                 u32x4 w; w.x = cvtpk(v0[0], v0[1]); w.y = cvtpk(v0[2], v0[3]); w.z = cvtpk(v1[0], v1[1]); w.w = cvtpk(v1[2], v1[3]);
;                 st16_wt(rowp + bj * HALF, w); }
.LBB0_339:
	s_waitcnt lgkmcnt(2)
	v_pk_add_f32 v[66:67], v[168:169], v[170:171]
	v_cvt_pk_bf16_f32 v68, v78, v79
	v_pk_fma_f32 v[82:83], v[66:67], s[92:93], v[194:195] op_sel_hi:[1,0,0]
	v_cvt_pk_bf16_f32 v66, v74, v75
	v_mul_f32_e32 v0, 0x4b800000, v83
	v_cmp_gt_f32_e32 vcc, s97, v83
	v_cvt_pk_bf16_f32 v69, v80, v81
	v_lshl_add_u64 v[70:71], v[90:91], 0, s[0:1]
	v_cndmask_b32_e32 v0, v83, v0, vcc
	v_rsq_f32_e32 v0, v0
	v_cmp_gt_f32_e64 s[4:5], s97, v82
	s_mov_b64 s[76:77], -1
	v_mul_f32_e32 v67, 0x45800000, v0
	v_cndmask_b32_e32 v74, v0, v67, vcc
	v_cvt_pk_bf16_f32 v67, v76, v77
	global_store_dwordx4 v[70:71], v[66:69], off sc1 nt
	s_nop 2
	v_pk_mul_f32 v[64:65], v[64:65], v[74:75] op_sel_hi:[1,0]
	v_pk_mul_f32 v[62:63], v[62:63], v[74:75] op_sel_hi:[1,0]
	v_pk_mul_f32 v[60:61], v[60:61], v[74:75] op_sel_hi:[1,0]
	v_pk_mul_f32 v[58:59], v[58:59], v[74:75] op_sel_hi:[1,0]
	s_and_b64 vcc, exec, s[74:75]
	s_cbranch_vccz .LBB0_341
	v_mul_f32_e32 v0, 0xbfb8aa3b, v62
	v_exp_f32_e32 v0, v0
	v_mul_f32_e32 v66, 0xbfb8aa3b, v58
	v_exp_f32_e32 v66, v66
	v_mul_f32_e32 v68, 0xbfb8aa3b, v59
	v_add_f32_e32 v0, 1.0, v0
	v_exp_f32_e32 v68, v68
	v_add_f32_e32 v67, 1.0, v66
	v_rcp_f32_e32 v66, v0
	v_mul_f32_e32 v0, 0xbfb8aa3b, v63
	v_exp_f32_e32 v0, v0
	v_rcp_f32_e32 v70, v67
	v_mul_f32_e32 v69, 0xbfb8aa3b, v60
	v_exp_f32_e32 v69, v69
	v_add_f32_e32 v0, 1.0, v0
	v_rcp_f32_e32 v67, v0
	v_add_f32_e32 v0, 1.0, v68
	v_mul_f32_e32 v68, 0xbfb8aa3b, v64
	v_exp_f32_e32 v68, v68
	v_rcp_f32_e32 v71, v0
	v_mul_f32_e32 v72, 0xbfb8aa3b, v61
	v_exp_f32_e32 v73, v72
	v_add_f32_e32 v0, 1.0, v68
	v_rcp_f32_e32 v68, v0
	v_add_f32_e32 v0, 1.0, v69
	v_mul_f32_e32 v69, 0xbfb8aa3b, v65
	v_exp_f32_e32 v69, v69
	v_rcp_f32_e32 v72, v0
	s_mov_b64 s[76:77], 0
	v_add_f32_e32 v0, 1.0, v69
	v_rcp_f32_e32 v69, v0
	v_add_f32_e32 v0, 1.0, v73
	v_rcp_f32_e32 v73, v0

; __device__ __forceinline__ unsigned cvtpk(float lo, float hi) { f32x2 v = {lo, hi}; bf16x2_t b = __builtin_convertvector(v, bf16x2_t); return __builtin_bit_cast(unsigned, b); }
; __device__ __forceinline__ float sigmoidf_(float v) { return __builtin_amdgcn_rcpf(1.0f + __expf(-v)); }
; __device__ __forceinline__ void st16_wt(void* p, u32x4 v) { asm volatile("global_store_dwordx4 %0, %1, off sc1\n\ts_nop 2" :: "v"(p), "v"(v) : "memory"); }
; #define EPI_LOOP_ROWS for (int ai = 0; ai < 2; ++ai) _Pragma("unroll") for (int m = 0; m < 4; ++m)
;     __device__ __forceinline__ void operator()(const f32x4 (&acc)[2][2][4][2], const Unit& u, int wv) const {
;     ...
;         EPI_LOOP_ROWS { bf16_t* rowp = base + (size_t)(row0 + ai * HALF + m * 16) * ldc + col0;
;             const float rstd = rs[ai][m];
;             float ssm = 0.f;
; #pragma unroll
;             for (int bj = 0; bj < 2; ++bj) { f32x4 v0 = acc[ai][bj][m][0] * rstd, v1 = acc[ai][bj][m][1] * rstd;
;                 if (RSM && (u.pn == 0 || (u.pn == 1 && bj == 0))) ssm += ((v0[0] * v0[0] + v0[1] * v0[1]) + (v0[2] * v0[2] + v0[3] * v0[3])) + ((v1[0] * v1[0] + v1[1] * v1[1]) + (v1[2] * v1[2] + v1[3] * v1[3]));
;                 if (gate) {
; #pragma unroll
;                     for (int e = 0; e < 4; ++e) { v0[e] = sigmoidf_(v0[e]); v1[e] = sigmoidf_(v1[e]); } }
;                 u32x4 w; w.x = cvtpk(v0[0], v0[1]); w.y = cvtpk(v0[2], v0[3]); w.z = cvtpk(v1[0], v1[1]); w.w = cvtpk(v1[2], v1[3]);
;                 st16_wt(rowp + bj * HALF, w); }
.LBB0_343:
	v_lshlrev_b64 v[58:59], 13, v[158:159]
	v_lshl_add_u64 v[76:77], v[156:157], 0, v[58:59]
	v_cvt_pk_bf16_f32 v58, v66, v67
	v_cvt_pk_bf16_f32 v59, v68, v69
	v_cvt_pk_bf16_f32 v60, v70, v71
	v_cvt_pk_bf16_f32 v61, v72, v73
	global_store_dwordx4 v[76:77], v[58:61], off sc1 nt
	s_nop 2
	v_mov_b32_e32 v75, v74
	v_mov_b32_e32 v58, v74
	v_mov_b32_e32 v59, v74
	v_pk_mul_f32 v[56:57], v[56:57], v[58:59]
	v_pk_mul_f32 v[54:55], v[54:55], v[74:75]
	v_pk_mul_f32 v[52:53], v[52:53], v[58:59]
	v_pk_mul_f32 v[50:51], v[50:51], v[74:75]
	s_mov_b64 s[76:77], -1
	s_and_b64 vcc, exec, s[74:75]
	s_cbranch_vccz .LBB0_345
	v_mul_f32_e32 v0, 0xbfb8aa3b, v54
	v_exp_f32_e32 v0, v0
	v_mul_f32_e32 v58, 0xbfb8aa3b, v50
	v_exp_f32_e32 v58, v58
	v_mul_f32_e32 v60, 0xbfb8aa3b, v51
	v_add_f32_e32 v0, 1.0, v0
	v_exp_f32_e32 v60, v60
	v_add_f32_e32 v59, 1.0, v58
	v_rcp_f32_e32 v58, v0
	v_mul_f32_e32 v0, 0xbfb8aa3b, v55
	v_exp_f32_e32 v0, v0
	v_rcp_f32_e32 v62, v59
	v_mul_f32_e32 v61, 0xbfb8aa3b, v52
	v_exp_f32_e32 v61, v61
	v_add_f32_e32 v0, 1.0, v0
	v_rcp_f32_e32 v59, v0
	v_add_f32_e32 v0, 1.0, v60
	v_mul_f32_e32 v60, 0xbfb8aa3b, v56
	v_exp_f32_e32 v60, v60
	v_rcp_f32_e32 v63, v0
	v_mul_f32_e32 v64, 0xbfb8aa3b, v53
	v_exp_f32_e32 v65, v64
	v_add_f32_e32 v0, 1.0, v60
	v_rcp_f32_e32 v60, v0
	v_add_f32_e32 v0, 1.0, v61
	v_mul_f32_e32 v61, 0xbfb8aa3b, v57
	v_exp_f32_e32 v61, v61
	v_rcp_f32_e32 v64, v0
	s_mov_b64 s[76:77], 0
	v_add_f32_e32 v0, 1.0, v61
	v_rcp_f32_e32 v61, v0
	v_add_f32_e32 v0, 1.0, v65
	v_rcp_f32_e32 v65, v0

; __device__ __forceinline__ unsigned cvtpk(float lo, float hi) { f32x2 v = {lo, hi}; bf16x2_t b = __builtin_convertvector(v, bf16x2_t); return __builtin_bit_cast(unsigned, b); }
; __device__ __forceinline__ float shx(float v, int o, int lane) { return __builtin_bit_cast(float, __builtin_amdgcn_ds_bpermute((lane ^ o) << 2, __builtin_bit_cast(int, v))); }
; __device__ __forceinline__ float sigmoidf_(float v) { return __builtin_amdgcn_rcpf(1.0f + __expf(-v)); }
; __device__ __forceinline__ void st16_wt(void* p, u32x4 v) { asm volatile("global_store_dwordx4 %0, %1, off sc1\n\ts_nop 2" :: "v"(p), "v"(v) : "memory"); }
; #define EPI_LOOP_ROWS for (int ai = 0; ai < 2; ++ai) _Pragma("unroll") for (int m = 0; m < 4; ++m)
; __device__ __forceinline__ float row_rstd_fin(float s, int lane) { s += shx(s, 16, lane); s += shx(s, 32, lane); return rsqrtf(s * (1.0f / 1024.0f) + EPS); }
;     __device__ __forceinline__ void operator()(const f32x4 (&acc)[2][2][4][2], const Unit& u, int wv) const {
;     ...
;         EPI_LOOP_ROWS { bf16_t* rowp = base + (size_t)(row0 + ai * HALF + m * 16) * ldc + col0;
;             const float rstd = rs[ai][m];
;             float ssm = 0.f;
; #pragma unroll
;             for (int bj = 0; bj < 2; ++bj) { f32x4 v0 = acc[ai][bj][m][0] * rstd, v1 = acc[ai][bj][m][1] * rstd;
;                 if (RSM && (u.pn == 0 || (u.pn == 1 && bj == 0))) ssm += ((v0[0] * v0[0] + v0[1] * v0[1]) + (v0[2] * v0[2] + v0[3] * v0[3])) + ((v1[0] * v1[0] + v1[1] * v1[1]) + (v1[2] * v1[2] + v1[3] * v1[3]));
;                 if (gate) {
; #pragma unroll
;                     for (int e = 0; e < 4; ++e) { v0[e] = sigmoidf_(v0[e]); v1[e] = sigmoidf_(v1[e]); } }
;                 u32x4 w; w.x = cvtpk(v0[0], v0[1]); w.y = cvtpk(v0[2], v0[3]); w.z = cvtpk(v1[0], v1[1]); w.w = cvtpk(v1[2], v1[3]);
;                 st16_wt(rowp + bj * HALF, w); }
.LBB0_347:
	v_mul_f32_e32 v0, 0x4b800000, v82
	v_cndmask_b32_e64 v0, v82, v0, s[4:5]
	v_rsq_f32_e32 v0, v0
	v_cvt_pk_bf16_f32 v50, v58, v59
	v_cvt_pk_bf16_f32 v51, v60, v61
	v_cvt_pk_bf16_f32 v52, v62, v63
	v_mul_f32_e32 v53, 0x45800000, v0
	v_cndmask_b32_e64 v60, v0, v53, s[4:5]
	v_cvt_pk_bf16_f32 v53, v64, v65
	v_lshl_add_u64 v[54:55], v[76:77], 0, s[0:1]
	global_store_dwordx4 v[54:55], v[50:53], off sc1 nt
	s_nop 2
	v_pk_mul_f32 v[48:49], v[48:49], v[60:61] op_sel_hi:[1,0]
	v_pk_mul_f32 v[46:47], v[46:47], v[60:61] op_sel_hi:[1,0]
	v_pk_mul_f32 v[44:45], v[44:45], v[60:61] op_sel_hi:[1,0]
	v_pk_mul_f32 v[42:43], v[42:43], v[60:61] op_sel_hi:[1,0]
	s_mov_b64 s[4:5], -1
	s_and_b64 vcc, exec, s[74:75]
	s_cbranch_vccz .LBB0_349
	v_mul_f32_e32 v0, 0xbfb8aa3b, v46
	v_exp_f32_e32 v0, v0
	v_mul_f32_e32 v50, 0xbfb8aa3b, v42
	v_exp_f32_e32 v50, v50
	v_mul_f32_e32 v52, 0xbfb8aa3b, v43
	v_add_f32_e32 v0, 1.0, v0
	v_exp_f32_e32 v52, v52
	v_add_f32_e32 v51, 1.0, v50
	v_rcp_f32_e32 v50, v0
	v_mul_f32_e32 v0, 0xbfb8aa3b, v47
	v_exp_f32_e32 v0, v0
	v_rcp_f32_e32 v54, v51
	v_mul_f32_e32 v53, 0xbfb8aa3b, v44
	v_exp_f32_e32 v53, v53
	v_add_f32_e32 v0, 1.0, v0
	v_rcp_f32_e32 v51, v0
	v_add_f32_e32 v0, 1.0, v52
	v_mul_f32_e32 v52, 0xbfb8aa3b, v48
	v_exp_f32_e32 v52, v52
	v_rcp_f32_e32 v55, v0
	v_mul_f32_e32 v56, 0xbfb8aa3b, v45
	v_exp_f32_e32 v57, v56
	v_add_f32_e32 v0, 1.0, v52
	v_rcp_f32_e32 v52, v0
	v_add_f32_e32 v0, 1.0, v53
	v_mul_f32_e32 v53, 0xbfb8aa3b, v49
	v_exp_f32_e32 v53, v53
	v_rcp_f32_e32 v56, v0
	s_mov_b64 s[4:5], 0
	v_add_f32_e32 v0, 1.0, v53
	v_rcp_f32_e32 v53, v0
	v_add_f32_e32 v0, 1.0, v57
	v_rcp_f32_e32 v57, v0

; __device__ __forceinline__ unsigned cvtpk(float lo, float hi) { f32x2 v = {lo, hi}; bf16x2_t b = __builtin_convertvector(v, bf16x2_t); return __builtin_bit_cast(unsigned, b); }
; __device__ __forceinline__ float sigmoidf_(float v) { return __builtin_amdgcn_rcpf(1.0f + __expf(-v)); }
; __device__ __forceinline__ void st16_wt(void* p, u32x4 v) { asm volatile("global_store_dwordx4 %0, %1, off sc1\n\ts_nop 2" :: "v"(p), "v"(v) : "memory"); }
; #define EPI_LOOP_ROWS for (int ai = 0; ai < 2; ++ai) _Pragma("unroll") for (int m = 0; m < 4; ++m)
;     __device__ __forceinline__ void operator()(const f32x4 (&acc)[2][2][4][2], const Unit& u, int wv) const {
;     ...
;         EPI_LOOP_ROWS { bf16_t* rowp = base + (size_t)(row0 + ai * HALF + m * 16) * ldc + col0;
;             const float rstd = rs[ai][m];
;             float ssm = 0.f;
; #pragma unroll
;             for (int bj = 0; bj < 2; ++bj) { f32x4 v0 = acc[ai][bj][m][0] * rstd, v1 = acc[ai][bj][m][1] * rstd;
;                 if (RSM && (u.pn == 0 || (u.pn == 1 && bj == 0))) ssm += ((v0[0] * v0[0] + v0[1] * v0[1]) + (v0[2] * v0[2] + v0[3] * v0[3])) + ((v1[0] * v1[0] + v1[1] * v1[1]) + (v1[2] * v1[2] + v1[3] * v1[3]));
;                 if (gate) {
; #pragma unroll
;                     for (int e = 0; e < 4; ++e) { v0[e] = sigmoidf_(v0[e]); v1[e] = sigmoidf_(v1[e]); } }
;                 u32x4 w; w.x = cvtpk(v0[0], v0[1]); w.y = cvtpk(v0[2], v0[3]); w.z = cvtpk(v1[0], v1[1]); w.w = cvtpk(v1[2], v1[3]);
;                 st16_wt(rowp + bj * HALF, w); }
.LBB0_351:
	v_lshlrev_b64 v[42:43], 13, v[154:155]
	v_lshl_add_u64 v[58:59], v[156:157], 0, v[42:43]
	v_cvt_pk_bf16_f32 v42, v50, v51
	v_cvt_pk_bf16_f32 v43, v52, v53
	v_cvt_pk_bf16_f32 v44, v54, v55
	v_cvt_pk_bf16_f32 v45, v56, v57
	global_store_dwordx4 v[58:59], v[42:45], off sc1 nt
	s_nop 2
	v_mov_b32_e32 v61, v60
	v_mov_b32_e32 v42, v60
	v_mov_b32_e32 v43, v60
	v_pk_mul_f32 v[40:41], v[40:41], v[42:43]
	v_pk_mul_f32 v[38:39], v[38:39], v[60:61]
	v_pk_mul_f32 v[36:37], v[36:37], v[42:43]
	v_pk_mul_f32 v[34:35], v[34:35], v[60:61]
	s_mov_b64 s[4:5], -1
	s_and_b64 vcc, exec, s[74:75]
	s_cbranch_vccz .LBB0_353
	v_mul_f32_e32 v0, 0xbfb8aa3b, v38
	v_exp_f32_e32 v0, v0
	v_mul_f32_e32 v42, 0xbfb8aa3b, v34
	v_exp_f32_e32 v42, v42
	v_mul_f32_e32 v44, 0xbfb8aa3b, v35
	v_add_f32_e32 v0, 1.0, v0
	v_exp_f32_e32 v44, v44
	v_add_f32_e32 v43, 1.0, v42
	v_rcp_f32_e32 v42, v0
	v_mul_f32_e32 v0, 0xbfb8aa3b, v39
	v_exp_f32_e32 v0, v0
	v_rcp_f32_e32 v46, v43
	v_mul_f32_e32 v45, 0xbfb8aa3b, v36
	v_exp_f32_e32 v45, v45
	v_add_f32_e32 v0, 1.0, v0
	v_rcp_f32_e32 v43, v0
	v_add_f32_e32 v0, 1.0, v44
	v_mul_f32_e32 v44, 0xbfb8aa3b, v40
	v_exp_f32_e32 v44, v44
	v_rcp_f32_e32 v47, v0
	v_mul_f32_e32 v48, 0xbfb8aa3b, v37
	v_exp_f32_e32 v49, v48
	v_add_f32_e32 v0, 1.0, v44
	v_rcp_f32_e32 v44, v0
	v_add_f32_e32 v0, 1.0, v45
	v_mul_f32_e32 v45, 0xbfb8aa3b, v41
	v_exp_f32_e32 v45, v45
	v_rcp_f32_e32 v48, v0
	s_mov_b64 s[4:5], 0
	v_add_f32_e32 v0, 1.0, v45
	v_rcp_f32_e32 v45, v0
	v_add_f32_e32 v0, 1.0, v49
	v_rcp_f32_e32 v49, v0

; __device__ __forceinline__ unsigned cvtpk(float lo, float hi) { f32x2 v = {lo, hi}; bf16x2_t b = __builtin_convertvector(v, bf16x2_t); return __builtin_bit_cast(unsigned, b); }
; __device__ __forceinline__ float shx(float v, int o, int lane) { return __builtin_bit_cast(float, __builtin_amdgcn_ds_bpermute((lane ^ o) << 2, __builtin_bit_cast(int, v))); }
; __device__ __forceinline__ float sigmoidf_(float v) { return __builtin_amdgcn_rcpf(1.0f + __expf(-v)); }
; __device__ __forceinline__ void st16_wt(void* p, u32x4 v) { asm volatile("global_store_dwordx4 %0, %1, off sc1\n\ts_nop 2" :: "v"(p), "v"(v) : "memory"); }
; #define EPI_LOOP_ROWS for (int ai = 0; ai < 2; ++ai) _Pragma("unroll") for (int m = 0; m < 4; ++m)
; __device__ __forceinline__ float row_rstd_fin(float s, int lane) { s += shx(s, 16, lane); s += shx(s, 32, lane); return rsqrtf(s * (1.0f / 1024.0f) + EPS); }
;     __device__ __forceinline__ void operator()(const f32x4 (&acc)[2][2][4][2], const Unit& u, int wv) const {
;     ...
;         EPI_LOOP_ROWS { bf16_t* rowp = base + (size_t)(row0 + ai * HALF + m * 16) * ldc + col0;
;             const float rstd = rs[ai][m];
;             float ssm = 0.f;
; #pragma unroll
;             for (int bj = 0; bj < 2; ++bj) { f32x4 v0 = acc[ai][bj][m][0] * rstd, v1 = acc[ai][bj][m][1] * rstd;
;                 if (RSM && (u.pn == 0 || (u.pn == 1 && bj == 0))) ssm += ((v0[0] * v0[0] + v0[1] * v0[1]) + (v0[2] * v0[2] + v0[3] * v0[3])) + ((v1[0] * v1[0] + v1[1] * v1[1]) + (v1[2] * v1[2] + v1[3] * v1[3]));
;                 if (gate) {
; #pragma unroll
;                     for (int e = 0; e < 4; ++e) { v0[e] = sigmoidf_(v0[e]); v1[e] = sigmoidf_(v1[e]); } }
;                 u32x4 w; w.x = cvtpk(v0[0], v0[1]); w.y = cvtpk(v0[2], v0[3]); w.z = cvtpk(v1[0], v1[1]); w.w = cvtpk(v1[2], v1[3]);
;                 st16_wt(rowp + bj * HALF, w); }
.LBB0_355:
	s_waitcnt lgkmcnt(0)
	v_pk_add_f32 v[34:35], v[160:161], v[162:163]
	v_cvt_pk_bf16_f32 v36, v46, v47
	v_pk_fma_f32 v[50:51], v[34:35], s[92:93], v[194:195] op_sel_hi:[1,0,0]
	v_cvt_pk_bf16_f32 v34, v42, v43
	v_mul_f32_e32 v0, 0x4b800000, v51
	v_cmp_gt_f32_e32 vcc, s97, v51
	v_cvt_pk_bf16_f32 v37, v48, v49
	v_lshl_add_u64 v[38:39], v[58:59], 0, s[0:1]
	v_cndmask_b32_e32 v0, v51, v0, vcc
	v_rsq_f32_e32 v0, v0
	v_cmp_gt_f32_e64 s[4:5], s97, v50
	s_mov_b64 s[76:77], -1
	v_mul_f32_e32 v35, 0x45800000, v0
	v_cndmask_b32_e32 v42, v0, v35, vcc
	v_cvt_pk_bf16_f32 v35, v44, v45
	global_store_dwordx4 v[38:39], v[34:37], off sc1 nt
	s_nop 2
	v_pk_mul_f32 v[32:33], v[32:33], v[42:43] op_sel_hi:[1,0]
	v_pk_mul_f32 v[30:31], v[30:31], v[42:43] op_sel_hi:[1,0]
	v_pk_mul_f32 v[28:29], v[28:29], v[42:43] op_sel_hi:[1,0]
	v_pk_mul_f32 v[26:27], v[26:27], v[42:43] op_sel_hi:[1,0]
	s_and_b64 vcc, exec, s[74:75]
	s_cbranch_vccz .LBB0_357
	v_mul_f32_e32 v0, 0xbfb8aa3b, v30
	v_exp_f32_e32 v0, v0
	v_mul_f32_e32 v34, 0xbfb8aa3b, v26
	v_exp_f32_e32 v34, v34
	v_mul_f32_e32 v36, 0xbfb8aa3b, v27
	v_add_f32_e32 v0, 1.0, v0
	v_exp_f32_e32 v36, v36
	v_add_f32_e32 v35, 1.0, v34
	v_rcp_f32_e32 v34, v0
	v_mul_f32_e32 v0, 0xbfb8aa3b, v31
	v_exp_f32_e32 v0, v0
	v_rcp_f32_e32 v38, v35
	v_mul_f32_e32 v37, 0xbfb8aa3b, v28
	v_exp_f32_e32 v37, v37
	v_add_f32_e32 v0, 1.0, v0
	v_rcp_f32_e32 v35, v0
	v_add_f32_e32 v0, 1.0, v36
	v_mul_f32_e32 v36, 0xbfb8aa3b, v32
	v_exp_f32_e32 v36, v36
	v_rcp_f32_e32 v39, v0
	v_mul_f32_e32 v40, 0xbfb8aa3b, v29
	v_exp_f32_e32 v41, v40
	v_add_f32_e32 v0, 1.0, v36
	v_rcp_f32_e32 v36, v0
	v_add_f32_e32 v0, 1.0, v37
	v_mul_f32_e32 v37, 0xbfb8aa3b, v33
	v_exp_f32_e32 v37, v37
	v_rcp_f32_e32 v40, v0
	s_mov_b64 s[76:77], 0
	v_add_f32_e32 v0, 1.0, v37
	v_rcp_f32_e32 v37, v0
	v_add_f32_e32 v0, 1.0, v41
	v_rcp_f32_e32 v41, v0

; __device__ __forceinline__ unsigned cvtpk(float lo, float hi) { f32x2 v = {lo, hi}; bf16x2_t b = __builtin_convertvector(v, bf16x2_t); return __builtin_bit_cast(unsigned, b); }
; __device__ __forceinline__ float sigmoidf_(float v) { return __builtin_amdgcn_rcpf(1.0f + __expf(-v)); }
; __device__ __forceinline__ void st16_wt(void* p, u32x4 v) { asm volatile("global_store_dwordx4 %0, %1, off sc1\n\ts_nop 2" :: "v"(p), "v"(v) : "memory"); }
; #define EPI_LOOP_ROWS for (int ai = 0; ai < 2; ++ai) _Pragma("unroll") for (int m = 0; m < 4; ++m)
;     __device__ __forceinline__ void operator()(const f32x4 (&acc)[2][2][4][2], const Unit& u, int wv) const {
;     ...
;         EPI_LOOP_ROWS { bf16_t* rowp = base + (size_t)(row0 + ai * HALF + m * 16) * ldc + col0;
;             const float rstd = rs[ai][m];
;             float ssm = 0.f;
; #pragma unroll
;             for (int bj = 0; bj < 2; ++bj) { f32x4 v0 = acc[ai][bj][m][0] * rstd, v1 = acc[ai][bj][m][1] * rstd;
;                 if (RSM && (u.pn == 0 || (u.pn == 1 && bj == 0))) ssm += ((v0[0] * v0[0] + v0[1] * v0[1]) + (v0[2] * v0[2] + v0[3] * v0[3])) + ((v1[0] * v1[0] + v1[1] * v1[1]) + (v1[2] * v1[2] + v1[3] * v1[3]));
;                 if (gate) {
; #pragma unroll
;                     for (int e = 0; e < 4; ++e) { v0[e] = sigmoidf_(v0[e]); v1[e] = sigmoidf_(v1[e]); } }
;                 u32x4 w; w.x = cvtpk(v0[0], v0[1]); w.y = cvtpk(v0[2], v0[3]); w.z = cvtpk(v1[0], v1[1]); w.w = cvtpk(v1[2], v1[3]);
;                 st16_wt(rowp + bj * HALF, w); }
.LBB0_359:
	v_lshlrev_b64 v[26:27], 13, v[152:153]
	v_lshl_add_u64 v[44:45], v[156:157], 0, v[26:27]
	v_cvt_pk_bf16_f32 v26, v34, v35
	v_cvt_pk_bf16_f32 v27, v36, v37
	v_cvt_pk_bf16_f32 v28, v38, v39
	v_cvt_pk_bf16_f32 v29, v40, v41
	global_store_dwordx4 v[44:45], v[26:29], off sc1 nt
	s_nop 2
	v_mov_b32_e32 v43, v42
	v_mov_b32_e32 v26, v42
	v_mov_b32_e32 v27, v42
	v_pk_mul_f32 v[24:25], v[24:25], v[26:27]
	v_pk_mul_f32 v[22:23], v[22:23], v[42:43]
	v_pk_mul_f32 v[20:21], v[20:21], v[26:27]
	v_pk_mul_f32 v[18:19], v[18:19], v[42:43]
	s_mov_b64 s[76:77], -1
	s_and_b64 vcc, exec, s[74:75]
	s_cbranch_vccz .LBB0_361
	v_mul_f32_e32 v0, 0xbfb8aa3b, v22
	v_exp_f32_e32 v0, v0
	v_mul_f32_e32 v26, 0xbfb8aa3b, v18
	v_exp_f32_e32 v26, v26
	v_mul_f32_e32 v28, 0xbfb8aa3b, v19
	v_add_f32_e32 v0, 1.0, v0
	v_exp_f32_e32 v28, v28
	v_add_f32_e32 v27, 1.0, v26
	v_rcp_f32_e32 v26, v0
	v_mul_f32_e32 v0, 0xbfb8aa3b, v23
	v_exp_f32_e32 v0, v0
	v_rcp_f32_e32 v30, v27
	v_mul_f32_e32 v29, 0xbfb8aa3b, v20
	v_exp_f32_e32 v29, v29
	v_add_f32_e32 v0, 1.0, v0
	v_rcp_f32_e32 v27, v0
	v_add_f32_e32 v0, 1.0, v28
	v_mul_f32_e32 v28, 0xbfb8aa3b, v24
	v_exp_f32_e32 v28, v28
	v_rcp_f32_e32 v31, v0
	v_mul_f32_e32 v32, 0xbfb8aa3b, v21
	v_exp_f32_e32 v33, v32
	v_add_f32_e32 v0, 1.0, v28
	v_rcp_f32_e32 v28, v0
	v_add_f32_e32 v0, 1.0, v29
	v_mul_f32_e32 v29, 0xbfb8aa3b, v25
	v_exp_f32_e32 v29, v29
	v_rcp_f32_e32 v32, v0
	s_mov_b64 s[76:77], 0
	v_add_f32_e32 v0, 1.0, v29
	v_rcp_f32_e32 v29, v0
	v_add_f32_e32 v0, 1.0, v33
	v_rcp_f32_e32 v33, v0

; __device__ __forceinline__ unsigned cvtpk(float lo, float hi) { f32x2 v = {lo, hi}; bf16x2_t b = __builtin_convertvector(v, bf16x2_t); return __builtin_bit_cast(unsigned, b); }
; __device__ __forceinline__ float shx(float v, int o, int lane) { return __builtin_bit_cast(float, __builtin_amdgcn_ds_bpermute((lane ^ o) << 2, __builtin_bit_cast(int, v))); }
; __device__ __forceinline__ float sigmoidf_(float v) { return __builtin_amdgcn_rcpf(1.0f + __expf(-v)); }
; __device__ __forceinline__ void st16_wt(void* p, u32x4 v) { asm volatile("global_store_dwordx4 %0, %1, off sc1\n\ts_nop 2" :: "v"(p), "v"(v) : "memory"); }
; #define EPI_LOOP_ROWS for (int ai = 0; ai < 2; ++ai) _Pragma("unroll") for (int m = 0; m < 4; ++m)
; __device__ __forceinline__ float row_rstd_fin(float s, int lane) { s += shx(s, 16, lane); s += shx(s, 32, lane); return rsqrtf(s * (1.0f / 1024.0f) + EPS); }
;     __device__ __forceinline__ void operator()(const f32x4 (&acc)[2][2][4][2], const Unit& u, int wv) const {
;     ...
;         EPI_LOOP_ROWS { bf16_t* rowp = base + (size_t)(row0 + ai * HALF + m * 16) * ldc + col0;
;             const float rstd = rs[ai][m];
;             float ssm = 0.f;
; #pragma unroll
;             for (int bj = 0; bj < 2; ++bj) { f32x4 v0 = acc[ai][bj][m][0] * rstd, v1 = acc[ai][bj][m][1] * rstd;
;                 if (RSM && (u.pn == 0 || (u.pn == 1 && bj == 0))) ssm += ((v0[0] * v0[0] + v0[1] * v0[1]) + (v0[2] * v0[2] + v0[3] * v0[3])) + ((v1[0] * v1[0] + v1[1] * v1[1]) + (v1[2] * v1[2] + v1[3] * v1[3]));
;                 if (gate) {
; #pragma unroll
;                     for (int e = 0; e < 4; ++e) { v0[e] = sigmoidf_(v0[e]); v1[e] = sigmoidf_(v1[e]); } }
;                 u32x4 w; w.x = cvtpk(v0[0], v0[1]); w.y = cvtpk(v0[2], v0[3]); w.z = cvtpk(v1[0], v1[1]); w.w = cvtpk(v1[2], v1[3]);
;                 st16_wt(rowp + bj * HALF, w); }
.LBB0_363:
	v_mul_f32_e32 v0, 0x4b800000, v50
	v_cndmask_b32_e64 v0, v50, v0, s[4:5]
	v_rsq_f32_e32 v0, v0
	v_cvt_pk_bf16_f32 v18, v26, v27
	v_cvt_pk_bf16_f32 v19, v28, v29
	v_cvt_pk_bf16_f32 v20, v30, v31
	v_mul_f32_e32 v21, 0x45800000, v0
	v_cndmask_b32_e64 v26, v0, v21, s[4:5]
	v_cvt_pk_bf16_f32 v21, v32, v33
	v_lshl_add_u64 v[22:23], v[44:45], 0, s[0:1]
	global_store_dwordx4 v[22:23], v[18:21], off sc1 nt
	s_nop 2
	v_pk_mul_f32 v[16:17], v[16:17], v[26:27] op_sel_hi:[1,0]
	v_pk_mul_f32 v[14:15], v[14:15], v[26:27] op_sel_hi:[1,0]
	v_pk_mul_f32 v[12:13], v[12:13], v[26:27] op_sel_hi:[1,0]
	v_pk_mul_f32 v[10:11], v[10:11], v[26:27] op_sel_hi:[1,0]
	s_mov_b64 s[4:5], -1
	s_and_b64 vcc, exec, s[74:75]
	s_cbranch_vccz .LBB0_365
	v_mul_f32_e32 v0, 0xbfb8aa3b, v14
	v_exp_f32_e32 v0, v0
	v_mul_f32_e32 v18, 0xbfb8aa3b, v10
	v_exp_f32_e32 v18, v18
	v_mul_f32_e32 v20, 0xbfb8aa3b, v11
	v_add_f32_e32 v0, 1.0, v0
	v_exp_f32_e32 v20, v20
	v_add_f32_e32 v19, 1.0, v18
	v_rcp_f32_e32 v18, v0
	v_mul_f32_e32 v0, 0xbfb8aa3b, v15
	v_exp_f32_e32 v0, v0
	v_rcp_f32_e32 v22, v19
	v_mul_f32_e32 v21, 0xbfb8aa3b, v12
	v_exp_f32_e32 v21, v21
	v_add_f32_e32 v0, 1.0, v0
	v_rcp_f32_e32 v19, v0
	v_add_f32_e32 v0, 1.0, v20
	v_mul_f32_e32 v20, 0xbfb8aa3b, v16
	v_exp_f32_e32 v20, v20
	v_rcp_f32_e32 v23, v0
	v_mul_f32_e32 v24, 0xbfb8aa3b, v13
	v_exp_f32_e32 v25, v24
	v_add_f32_e32 v0, 1.0, v20
	v_rcp_f32_e32 v20, v0
	v_add_f32_e32 v0, 1.0, v21
	v_mul_f32_e32 v21, 0xbfb8aa3b, v17
	v_exp_f32_e32 v21, v21
	v_rcp_f32_e32 v24, v0
	s_mov_b64 s[4:5], 0
	v_add_f32_e32 v0, 1.0, v21
	v_rcp_f32_e32 v21, v0
	v_add_f32_e32 v0, 1.0, v25
	v_rcp_f32_e32 v25, v0

; __device__ __forceinline__ unsigned cvtpk(float lo, float hi) { f32x2 v = {lo, hi}; bf16x2_t b = __builtin_convertvector(v, bf16x2_t); return __builtin_bit_cast(unsigned, b); }
; __device__ __forceinline__ float sigmoidf_(float v) { return __builtin_amdgcn_rcpf(1.0f + __expf(-v)); }
; __device__ __forceinline__ void st16_wt(void* p, u32x4 v) { asm volatile("global_store_dwordx4 %0, %1, off sc1\n\ts_nop 2" :: "v"(p), "v"(v) : "memory"); }
; #define EPI_LOOP_ROWS for (int ai = 0; ai < 2; ++ai) _Pragma("unroll") for (int m = 0; m < 4; ++m)
;     __device__ __forceinline__ void operator()(const f32x4 (&acc)[2][2][4][2], const Unit& u, int wv) const {
;     ...
;         EPI_LOOP_ROWS { bf16_t* rowp = base + (size_t)(row0 + ai * HALF + m * 16) * ldc + col0;
;             const float rstd = rs[ai][m];
;             float ssm = 0.f;
; #pragma unroll
;             for (int bj = 0; bj < 2; ++bj) { f32x4 v0 = acc[ai][bj][m][0] * rstd, v1 = acc[ai][bj][m][1] * rstd;
;                 if (RSM && (u.pn == 0 || (u.pn == 1 && bj == 0))) ssm += ((v0[0] * v0[0] + v0[1] * v0[1]) + (v0[2] * v0[2] + v0[3] * v0[3])) + ((v1[0] * v1[0] + v1[1] * v1[1]) + (v1[2] * v1[2] + v1[3] * v1[3]));
;                 if (gate) {
; #pragma unroll
;                     for (int e = 0; e < 4; ++e) { v0[e] = sigmoidf_(v0[e]); v1[e] = sigmoidf_(v1[e]); } }
;                 u32x4 w; w.x = cvtpk(v0[0], v0[1]); w.y = cvtpk(v0[2], v0[3]); w.z = cvtpk(v1[0], v1[1]); w.w = cvtpk(v1[2], v1[3]);
;                 st16_wt(rowp + bj * HALF, w); }
.LBB0_367:
	v_lshlrev_b64 v[10:11], 13, v[150:151]
	v_lshl_add_u64 v[28:29], v[156:157], 0, v[10:11]
	v_cvt_pk_bf16_f32 v10, v18, v19
	v_cvt_pk_bf16_f32 v11, v20, v21
	v_cvt_pk_bf16_f32 v12, v22, v23
	v_cvt_pk_bf16_f32 v13, v24, v25
	global_store_dwordx4 v[28:29], v[10:13], off sc1 nt
	s_nop 2
	v_mov_b32_e32 v27, v26
	v_mov_b32_e32 v10, v26
	v_mov_b32_e32 v11, v26
	v_pk_mul_f32 v[8:9], v[8:9], v[10:11]
	v_pk_mul_f32 v[6:7], v[6:7], v[26:27]
	v_pk_mul_f32 v[4:5], v[4:5], v[10:11]
	v_pk_mul_f32 v[2:3], v[2:3], v[26:27]
	s_mov_b64 s[4:5], -1
	s_and_b64 vcc, exec, s[74:75]
	s_cbranch_vccz .LBB0_369
	v_mul_f32_e32 v0, 0xbfb8aa3b, v6
	v_exp_f32_e32 v0, v0
	v_mul_f32_e32 v10, 0xbfb8aa3b, v2
	v_exp_f32_e32 v10, v10
	v_mul_f32_e32 v12, 0xbfb8aa3b, v3
	v_add_f32_e32 v0, 1.0, v0
	v_exp_f32_e32 v12, v12
	v_add_f32_e32 v11, 1.0, v10
	v_rcp_f32_e32 v10, v0
	v_mul_f32_e32 v0, 0xbfb8aa3b, v7
	v_exp_f32_e32 v0, v0
	v_rcp_f32_e32 v14, v11
	v_mul_f32_e32 v13, 0xbfb8aa3b, v4
	v_exp_f32_e32 v13, v13
	v_add_f32_e32 v0, 1.0, v0
	v_rcp_f32_e32 v11, v0
	v_add_f32_e32 v0, 1.0, v12
	v_mul_f32_e32 v12, 0xbfb8aa3b, v8
	v_exp_f32_e32 v12, v12
	v_rcp_f32_e32 v15, v0
	v_mul_f32_e32 v16, 0xbfb8aa3b, v5
	v_exp_f32_e32 v17, v16
	v_add_f32_e32 v0, 1.0, v12
	v_rcp_f32_e32 v12, v0
	v_add_f32_e32 v0, 1.0, v13
	v_mul_f32_e32 v13, 0xbfb8aa3b, v9
	v_exp_f32_e32 v13, v13
	v_rcp_f32_e32 v16, v0
	s_mov_b64 s[4:5], 0
	v_add_f32_e32 v0, 1.0, v13
	v_rcp_f32_e32 v13, v0
	v_add_f32_e32 v0, 1.0, v17
	v_rcp_f32_e32 v17, v0

;     __device__ __forceinline__ void operator()(const f32x4 (&acc)[2][2][4][2], const Unit& u, int wv) const {
;     ...
;                 u32x4 w; w.x = cvtpk(v0[0], v0[1]); w.y = cvtpk(v0[2], v0[3]); w.z = cvtpk(v1[0], v1[1]); w.w = cvtpk(v1[2], v1[3]);
;                 st16_wt(rowp + bj * HALF, w); }
; template <class Epi, class Sched>
; __device__ __forceinline__ void gemm_phase(LAS unsigned char* lds, const Gemm g, const Sched& S, const Epi& E, int wv) {
;     ...
;     for (;;) {
;         const bool has_next = S.next(ui + 1, nxt);
;         const char* nA = has_next ? (const char*)g.A + (size_t)nxt.pm * tstepA + (size_t)nxt.ak * 2 : cA; const char* nB = has_next ? (const char*)g.Bt + (size_t)nxt.pn * tstepB : cB;
;         for (int t = 0; t < nt; t += 2) {
;             const bool last = (t == nt - 2);
;             const char* a1 = cA + (size_t)(t + 1) * kstep;
;             const char* a2 = last ? nA : cA + (size_t)(t + 2) * kstep; const char* b2 = last ? nB : cB + (size_t)(t + 2) * kstep;
;             const char* a3 = a2 + kstep; const char* b3 = b2 + kstep;
;             PG8_LDB(B0, 0, 0); PG8_LDB(B1, 0, 1); PG8_SCHED; PG8_LDA(At, 0, 0); PG8_STAGE(PG8_SA(1, 1), a1 + hstepA, voffA);
;             PG8_WAIT_V(8); PG8_WAIT_L(0); PG8_BAR; PG8_MMA(0, 0, At, B0); PG8_MMA(0, 1, At, B1); PG8_BAR; PG8_SCHED;
;             PG8_LDA(At, 0, 1); PG8_STAGE(PG8_SB(0, 0), b2, voffB); PG8_STAGE(PG8_SB(0, 1), b2 + hstepB, voffB); PG8_STAGE(PG8_SA(0, 0), a2, voffA);
;             PG8_WAIT_V(8); PG8_WAIT_L(0); PG8_BAR; PG8_MMA(1, 0, At, B0); PG8_MMA(1, 1, At, B1); PG8_BAR; PG8_SCHED;
;             PG8_LDB(B0, 1, 0); PG8_LDB(B1, 1, 1); PG8_SCHED; PG8_LDA(At, 1, 0); PG8_STAGE(PG8_SA(0, 1), a2 + hstepA, voffA);
;             PG8_WAIT_V(8); PG8_WAIT_L(0); PG8_BAR; PG8_MMA(0, 0, At, B0); PG8_MMA(0, 1, At, B1); PG8_BAR; PG8_SCHED;
;             PG8_LDA(At, 1, 1); PG8_STAGE(PG8_SB(1, 0), b3, voffB); PG8_STAGE(PG8_SB(1, 1), b3 + hstepB, voffB); PG8_STAGE(PG8_SA(1, 0), a3, voffA);
;             PG8_WAIT_V(8); PG8_WAIT_L(0); PG8_BAR; PG8_MMA(1, 0, At, B0); PG8_MMA(1, 1, At, B1); PG8_BAR; PG8_SCHED;
;         }
;         if (wr == 0) PG8_BAR;
;         E(acc, cur, wv);
;         if (!has_next) break;
; #pragma unroll
;         for (int a = 0; a < 2; ++a)
; #pragma unroll
;             for (int b = 0; b < 2; ++b)
; #pragma unroll
;                 for (int m = 0; m < 4; ++m)
; #pragma unroll
.LBB0_371:
	v_cvt_pk_bf16_f32 v2, v10, v11
	v_cvt_pk_bf16_f32 v3, v12, v13
	v_cvt_pk_bf16_f32 v4, v14, v15
	v_cvt_pk_bf16_f32 v5, v16, v17
	v_lshl_add_u64 v[6:7], v[28:29], 0, s[0:1]
	global_store_dwordx4 v[6:7], v[2:5], off sc1 nt
	s_nop 2
	s_andn2_b64 vcc, exec, s[2:3]
	s_mov_b64 s[2:3], -1
	s_cbranch_vccnz .LBB0_296
	s_andn2_b64 vcc, exec, s[6:7]
	s_cbranch_vccnz .LBB0_295
	s_barrier
	s_branch .LBB0_295

; __device__ __forceinline__ unsigned cvtpk(float lo, float hi) { f32x2 v = {lo, hi}; bf16x2_t b = __builtin_convertvector(v, bf16x2_t); return __builtin_bit_cast(unsigned, b); }
; __device__ __forceinline__ float sigmoidf_(float v) { return __builtin_amdgcn_rcpf(1.0f + __expf(-v)); }
; __device__ __forceinline__ void st16_wt(void* p, u32x4 v) { asm volatile("global_store_dwordx4 %0, %1, off sc1\n\ts_nop 2" :: "v"(p), "v"(v) : "memory"); }
; __device__ __forceinline__ int ltid(int wv) { unsigned z = 0u; asm volatile("" : "+v"(z)); return wv * 64 + (int)__builtin_amdgcn_mbcnt_hi(~0u, __builtin_amdgcn_mbcnt_lo(~0u, z)); }
; #define EPI_LOOP_ROWS for (int ai = 0; ai < 2; ++ai) _Pragma("unroll") for (int m = 0; m < 4; ++m)
;     __device__ __forceinline__ void operator()(const f32x4 (&acc)[2][2][4][2], const Unit& u, int wv) const {
;         const int t_ = ltid(wv), wid_ = __builtin_amdgcn_readfirstlane(t_ >> 6), wr = wid_ >> 2, wc = wid_ & 3, fr = t_ & 15, fq = (t_ & 63) >> 4;
;         const bool gate = u.pn >= split_pn;
;         bf16_t* base = gate ? O1 : O0;
;         const int col0 = (gate ? (u.pn - split_pn) : u.pn) * BM + wc * 32 + 8 * fq;
;         const int row0 = u.pm * BM + wr * 64 + fr;
;         float rs[2][4];
; #pragma unroll
;         EPI_LOOP_ROWS rs[ai][m] = RS ? row_part(RS, row0 + ai * HALF + m * 16, fq) : 0.f;
; #pragma unroll
;         EPI_LOOP_ROWS rs[ai][m] = RS ? row_rstd_fin(rs[ai][m], t_ & 63) : 1.0f;
; #pragma unroll
;         EPI_LOOP_ROWS { bf16_t* rowp = base + (size_t)(row0 + ai * HALF + m * 16) * ldc + col0;
;             const float rstd = rs[ai][m];
;             float ssm = 0.f;
; #pragma unroll
;             for (int bj = 0; bj < 2; ++bj) { f32x4 v0 = acc[ai][bj][m][0] * rstd, v1 = acc[ai][bj][m][1] * rstd;
;                 if (RSM && (u.pn == 0 || (u.pn == 1 && bj == 0))) ssm += ((v0[0] * v0[0] + v0[1] * v0[1]) + (v0[2] * v0[2] + v0[3] * v0[3])) + ((v1[0] * v1[0] + v1[1] * v1[1]) + (v1[2] * v1[2] + v1[3] * v1[3]));
;                 if (gate) {
; #pragma unroll
;                     for (int e = 0; e < 4; ++e) { v0[e] = sigmoidf_(v0[e]); v1[e] = sigmoidf_(v1[e]); } }
;                 u32x4 w; w.x = cvtpk(v0[0], v0[1]); w.y = cvtpk(v0[2], v0[3]); w.z = cvtpk(v1[0], v1[1]); w.w = cvtpk(v1[2], v1[3]);
;                 st16_wt(rowp + bj * HALF, w); }
.LBB0_720:
	v_mov_b32_e32 v0, v1
	s_lshl_b32 s1, s4, 8
	v_mbcnt_lo_u32_b32 v0, -1, v0
	v_mbcnt_hi_u32_b32 v0, -1, v0
	v_add_u32_e32 v142, s27, v0
	v_and_b32_e32 v181, 63, v0
	v_readfirstlane_b32 s0, v142
	s_bfe_u32 s77, s0, 0x20006
	s_ashr_i32 s0, s0, 2
	s_andn2_b32 s0, s0, 63
	s_add_i32 s0, s0, s1
	v_and_or_b32 v162, v0, 15, s0
	v_lshrrev_b32_e32 v182, 1, v0
	v_and_b32_e32 v0, 48, v0
	v_ashrrev_i32_e32 v163, 31, v162
	v_lshl_add_u64 v[176:177], s[70:71], 0, v[0:1]
	v_lshlrev_b64 v[188:189], 6, v[162:163]
	v_lshl_add_u64 v[188:189], v[176:177], 0, v[188:189]
	global_load_dwordx4 v[196:199], v[188:189], off
	v_or_b32_e32 v156, 16, v162
	v_ashrrev_i32_e32 v157, 31, v156
	v_lshlrev_b64 v[188:189], 6, v[156:157]
	v_lshl_add_u64 v[188:189], v[176:177], 0, v[188:189]
	global_load_dwordx4 v[200:203], v[188:189], off
	v_or_b32_e32 v152, 32, v162
	v_ashrrev_i32_e32 v153, 31, v152
	v_lshlrev_b64 v[188:189], 6, v[152:153]
	v_lshl_add_u64 v[188:189], v[176:177], 0, v[188:189]
	global_load_dwordx4 v[204:207], v[188:189], off
	v_or_b32_e32 v150, 48, v162
	v_ashrrev_i32_e32 v151, 31, v150
	v_lshlrev_b64 v[188:189], 6, v[150:151]
	v_lshl_add_u64 v[188:189], v[176:177], 0, v[188:189]
	global_load_dwordx4 v[208:211], v[188:189], off
	v_add_u32_e32 v148, 0x80, v162
	v_ashrrev_i32_e32 v149, 31, v148
	v_lshlrev_b64 v[188:189], 6, v[148:149]
	v_lshl_add_u64 v[188:189], v[176:177], 0, v[188:189]
	global_load_dwordx4 v[212:215], v[188:189], off
	v_add_u32_e32 v146, 0x90, v162
	v_ashrrev_i32_e32 v147, 31, v146
	v_lshlrev_b64 v[188:189], 6, v[146:147]
	v_lshl_add_u64 v[188:189], v[176:177], 0, v[188:189]
	global_load_dwordx4 v[216:219], v[188:189], off
	v_add_u32_e32 v144, 0xa0, v162
	v_ashrrev_i32_e32 v145, 31, v144
	v_lshlrev_b64 v[188:189], 6, v[144:145]
	v_lshl_add_u64 v[188:189], v[176:177], 0, v[188:189]
	global_load_dwordx4 v[220:223], v[188:189], off
	v_add_u32_e32 v142, 0xb0, v162
	v_ashrrev_i32_e32 v143, 31, v142
	v_lshlrev_b64 v[188:189], 6, v[142:143]
	v_lshl_add_u64 v[188:189], v[176:177], 0, v[188:189]
	global_load_dwordx4 v[224:227], v[188:189], off
	v_lshlrev_b32_e32 v0, 2, v181
	v_xor_b32_e32 v180, 64, v0
	v_xor_b32_e32 v0, 0x80, v0
	s_lshl_b32 s5, s77, 5
	s_lshl_b32 s0, s6, 8
	s_or_b32 s7, s5, s0
	s_cmp_eq_u32 s6, 0
	s_cselect_b64 s[10:11], -1, 0
	s_cmp_lt_u32 s6, 2
	s_waitcnt vmcnt(0)
	v_add_f32_e32 v160, v197, v196
	v_add_f32_e32 v161, v198, v199
	v_add_f32_e32 v170, v201, v200
	v_add_f32_e32 v171, v202, v203
	v_add_f32_e32 v154, v205, v204
	v_add_f32_e32 v155, v206, v207
	v_add_f32_e32 v164, v209, v208
	v_add_f32_e32 v165, v210, v211
	v_add_f32_e32 v158, v213, v212
	v_add_f32_e32 v159, v214, v215
	v_add_f32_e32 v166, v217, v216
	v_add_f32_e32 v167, v218, v219
	v_add_f32_e32 v168, v221, v220
	v_add_f32_e32 v169, v222, v223
	v_add_f32_e32 v172, v225, v224
	v_add_f32_e32 v173, v226, v227
	v_mov_b32_e32 v174, v170
	v_mov_b32_e32 v175, v160
	v_mov_b32_e32 v160, v171
	v_pk_add_f32 v[160:161], v[174:175], v[160:161]
	ds_bpermute_b32 v171, v180, v161
	ds_bpermute_b32 v170, v180, v160
	s_waitcnt lgkmcnt(0)
	v_pk_add_f32 v[160:161], v[160:161], v[170:171]
	ds_bpermute_b32 v171, v0, v161
	ds_bpermute_b32 v170, v0, v160
	s_waitcnt lgkmcnt(0)
	v_pk_add_f32 v[160:161], v[160:161], v[170:171]
	s_nop 0
	v_pk_fma_f32 v[176:177], v[160:161], s[56:57], v[194:195] op_sel_hi:[1,0,0]
	s_nop 0
	v_mul_f32_e32 v160, 0x4b800000, v177
	v_cmp_gt_f32_e64 s[4:5], s97, v177
	v_cmp_gt_f32_e32 vcc, s97, v176
	s_nop 0
	v_cndmask_b32_e64 v160, v177, v160, s[4:5]
	v_rsq_f32_e32 v160, v160
	s_nop 0
	v_mul_f32_e32 v161, 0x45800000, v160
	v_cndmask_b32_e64 v184, v160, v161, s[4:5]
	v_mov_b32_e32 v160, v164
	v_mov_b32_e32 v161, v154
	v_mov_b32_e32 v154, v165
	v_pk_add_f32 v[154:155], v[160:161], v[154:155]
	ds_bpermute_b32 v161, v180, v155
	ds_bpermute_b32 v160, v180, v154
	v_pk_mul_f32 v[126:127], v[126:127], v[184:185] op_sel_hi:[1,0]
	v_pk_mul_f32 v[128:129], v[128:129], v[184:185] op_sel_hi:[1,0]
	s_cselect_b64 s[4:5], -1, 0
	v_mov_b32_e32 v186, v129
	s_waitcnt lgkmcnt(0)
	v_pk_add_f32 v[170:171], v[154:155], v[160:161]
	v_mov_b32_e32 v154, v166
	v_mov_b32_e32 v155, v158
	v_mov_b32_e32 v158, v167
	v_pk_add_f32 v[154:155], v[154:155], v[158:159]
	ds_bpermute_b32 v159, v180, v155
	ds_bpermute_b32 v158, v180, v154
	ds_bpermute_b32 v175, v0, v171
	ds_bpermute_b32 v174, v0, v170
	s_cmp_lg_u32 s6, 0
	v_pk_mul_f32 v[120:121], v[120:121], v[184:185] op_sel_hi:[1,0]
	s_waitcnt lgkmcnt(2)
	v_pk_add_f32 v[164:165], v[154:155], v[158:159]
	v_mov_b32_e32 v154, v172
	v_mov_b32_e32 v155, v168
	v_mov_b32_e32 v168, v173
	v_pk_add_f32 v[154:155], v[154:155], v[168:169]
	ds_bpermute_b32 v159, v180, v155
	ds_bpermute_b32 v158, v180, v154
	v_pk_mul_f32 v[172:173], v[124:125], v[184:185] op_sel_hi:[1,0]
	v_mov_b32_e32 v124, v127
	v_mov_b32_e32 v187, v173
	ds_bpermute_b32 v167, v0, v165
	s_waitcnt lgkmcnt(1)
	v_pk_add_f32 v[158:159], v[154:155], v[158:159]
	v_and_or_b32 v154, v182, 24, s7
	v_pk_mul_f32 v[182:183], v[122:123], v[184:185] op_sel_hi:[1,0]
	v_mov_b32_e32 v122, v126
	v_mov_b32_e32 v125, v183
	v_mov_b32_e32 v123, v182
	v_pk_mul_f32 v[124:125], v[124:125], v[124:125]
	ds_bpermute_b32 v166, v0, v164
	ds_bpermute_b32 v161, v0, v159
	ds_bpermute_b32 v160, v0, v158
	v_ashrrev_i32_e32 v155, 31, v154
	v_pk_fma_f32 v[122:123], v[122:123], v[122:123], v[124:125]
	v_mov_b32_e32 v124, v128
	v_mov_b32_e32 v125, v172
	v_pk_mul_f32 v[186:187], v[186:187], v[186:187]
	v_lshl_add_u64 v[154:155], v[154:155], 1, s[68:69]
	v_lshlrev_b64 v[168:169], 13, v[162:163]
	v_pk_fma_f32 v[124:125], v[124:125], v[124:125], v[186:187]
	v_lshl_add_u64 v[168:169], v[154:155], 0, v[168:169]
	v_pk_add_f32 v[122:123], v[122:123], v[124:125]
	v_cvt_pk_bf16_f32 v124, v126, v127
	v_cvt_pk_bf16_f32 v125, v128, v129
	v_cvt_pk_bf16_f32 v126, v182, v183
	v_cvt_pk_bf16_f32 v127, v172, v173
	global_store_dwordx4 v[168:169], v[124:127], off sc1 nt
	s_nop 2
	v_pk_add_f32 v[122:123], v[122:123], v[122:123] op_sel:[0,1] op_sel_hi:[1,0]
	v_pk_mul_f32 v[118:119], v[118:119], v[184:185] op_sel_hi:[1,0]
	v_pk_mul_f32 v[116:117], v[116:117], v[184:185] op_sel_hi:[1,0]
	v_pk_mul_f32 v[114:115], v[114:115], v[184:185] op_sel_hi:[1,0]
	s_cbranch_scc0 .LBB0_722
	v_cndmask_b32_e64 v122, 0, v122, s[4:5]
	s_branch .LBB0_723

; __device__ __forceinline__ unsigned cvtpk(float lo, float hi) { f32x2 v = {lo, hi}; bf16x2_t b = __builtin_convertvector(v, bf16x2_t); return __builtin_bit_cast(unsigned, b); }
; __device__ __forceinline__ float shx(float v, int o, int lane) { return __builtin_bit_cast(float, __builtin_amdgcn_ds_bpermute((lane ^ o) << 2, __builtin_bit_cast(int, v))); }
; __device__ __forceinline__ float sigmoidf_(float v) { return __builtin_amdgcn_rcpf(1.0f + __expf(-v)); }
; __device__ __forceinline__ void st16_wt(void* p, u32x4 v) { asm volatile("global_store_dwordx4 %0, %1, off sc1\n\ts_nop 2" :: "v"(p), "v"(v) : "memory"); }
;     __device__ __forceinline__ void operator()(const f32x4 (&acc)[2][2][4][2], const Unit& u, int wv) const {
;     ...
;             for (int bj = 0; bj < 2; ++bj) { f32x4 v0 = acc[ai][bj][m][0] * rstd, v1 = acc[ai][bj][m][1] * rstd;
;                 if (RSM && (u.pn == 0 || (u.pn == 1 && bj == 0))) ssm += ((v0[0] * v0[0] + v0[1] * v0[1]) + (v0[2] * v0[2] + v0[3] * v0[3])) + ((v1[0] * v1[0] + v1[1] * v1[1]) + (v1[2] * v1[2] + v1[3] * v1[3]));
;                 if (gate) {
; #pragma unroll
;                     for (int e = 0; e < 4; ++e) { v0[e] = sigmoidf_(v0[e]); v1[e] = sigmoidf_(v1[e]); } }
;                 u32x4 w; w.x = cvtpk(v0[0], v0[1]); w.y = cvtpk(v0[2], v0[3]); w.z = cvtpk(v1[0], v1[1]); w.w = cvtpk(v1[2], v1[3]);
;                 st16_wt(rowp + bj * HALF, w); }
;             if (RSM && u.pn < 2) { ssm += shx(ssm, 16, t_ & 63); ssm += shx(ssm, 32, t_ & 63);
;                 if (fq == 0) RSM[(size_t)(row0 + ai * HALF + m * 16) * 8 + u.pn * 4 + wc] = ssm; } }
.LBB0_723:
	s_cmp_lt_i32 s6, 2
	s_mov_b64 s[0:1], 0x100
	s_cselect_b64 s[12:13], -1, 0
	s_lshl_b32 s84, s6, 2
	v_cvt_pk_bf16_f32 v118, v118, v119
	v_cvt_pk_bf16_f32 v119, v120, v121
	v_cvt_pk_bf16_f32 v120, v114, v115
	v_cvt_pk_bf16_f32 v121, v116, v117
	v_lshl_add_u64 v[114:115], v[168:169], 0, s[0:1]
	global_store_dwordx4 v[114:115], v[118:121], off sc1 nt
	s_nop 2
	s_ashr_i32 s85, s84, 31
	s_cmp_gt_i32 s6, 1
	v_cmp_gt_u32_e64 s[6:7], 16, v181
	s_cbranch_scc1 .LBB0_727
	ds_bpermute_b32 v114, v180, v122
	s_waitcnt lgkmcnt(0)
	v_add_f32_e32 v114, v122, v114
	ds_bpermute_b32 v115, v0, v114
	s_and_saveexec_b64 s[8:9], s[6:7]
	s_cbranch_execz .LBB0_726
	v_lshlrev_b64 v[116:117], 5, v[162:163]
	v_lshl_add_u64 v[116:117], s[72:73], 0, v[116:117]
	v_lshl_add_u64 v[116:117], s[84:85], 2, v[116:117]
	s_lshl_b32 s22, s77, 2
	v_lshl_add_u64 v[116:117], v[116:117], 0, s[22:23]
	s_waitcnt lgkmcnt(0)
	v_add_f32_e32 v114, v114, v115
	global_store_dword v[116:117], v114, off

; __device__ __forceinline__ unsigned cvtpk(float lo, float hi) { f32x2 v = {lo, hi}; bf16x2_t b = __builtin_convertvector(v, bf16x2_t); return __builtin_bit_cast(unsigned, b); }
; __device__ __forceinline__ float sigmoidf_(float v) { return __builtin_amdgcn_rcpf(1.0f + __expf(-v)); }
; __device__ __forceinline__ void st16_wt(void* p, u32x4 v) { asm volatile("global_store_dwordx4 %0, %1, off sc1\n\ts_nop 2" :: "v"(p), "v"(v) : "memory"); }
; #define EPI_LOOP_ROWS for (int ai = 0; ai < 2; ++ai) _Pragma("unroll") for (int m = 0; m < 4; ++m)
; __device__ __forceinline__ float row_rstd_fin(float s, int lane) { s += shx(s, 16, lane); s += shx(s, 32, lane); return rsqrtf(s * (1.0f / 1024.0f) + EPS); }
;     __device__ __forceinline__ void operator()(const f32x4 (&acc)[2][2][4][2], const Unit& u, int wv) const {
;     ...
;         EPI_LOOP_ROWS rs[ai][m] = RS ? row_rstd_fin(rs[ai][m], t_ & 63) : 1.0f;
; #pragma unroll
;         EPI_LOOP_ROWS { bf16_t* rowp = base + (size_t)(row0 + ai * HALF + m * 16) * ldc + col0;
;             const float rstd = rs[ai][m];
;             float ssm = 0.f;
; #pragma unroll
;             for (int bj = 0; bj < 2; ++bj) { f32x4 v0 = acc[ai][bj][m][0] * rstd, v1 = acc[ai][bj][m][1] * rstd;
;                 if (RSM && (u.pn == 0 || (u.pn == 1 && bj == 0))) ssm += ((v0[0] * v0[0] + v0[1] * v0[1]) + (v0[2] * v0[2] + v0[3] * v0[3])) + ((v1[0] * v1[0] + v1[1] * v1[1]) + (v1[2] * v1[2] + v1[3] * v1[3]));
;                 if (gate) {
; #pragma unroll
;                     for (int e = 0; e < 4; ++e) { v0[e] = sigmoidf_(v0[e]); v1[e] = sigmoidf_(v1[e]); } }
;                 u32x4 w; w.x = cvtpk(v0[0], v0[1]); w.y = cvtpk(v0[2], v0[3]); w.z = cvtpk(v1[0], v1[1]); w.w = cvtpk(v1[2], v1[3]);
;                 st16_wt(rowp + bj * HALF, w); }
.LBB0_727:
	v_mul_f32_e32 v114, 0x4b800000, v176
	v_cndmask_b32_e32 v114, v176, v114, vcc
	v_rsq_f32_e32 v116, v114
	s_waitcnt lgkmcnt(0)
	v_lshlrev_b64 v[114:115], 13, v[156:157]
	v_lshl_add_u64 v[114:115], v[154:155], 0, v[114:115]
	v_mul_f32_e32 v117, 0x45800000, v116
	v_cndmask_b32_e32 v116, v116, v117, vcc
	v_pk_mul_f32 v[110:111], v[110:111], v[116:117] op_sel_hi:[1,0]
	v_pk_mul_f32 v[120:121], v[106:107], v[116:117] op_sel_hi:[1,0]
	v_pk_mul_f32 v[112:113], v[112:113], v[116:117] op_sel_hi:[1,0]
	v_pk_mul_f32 v[118:119], v[108:109], v[116:117] op_sel_hi:[1,0]
	v_mov_b32_e32 v108, v111
	v_mov_b32_e32 v109, v121
	v_mov_b32_e32 v106, v110
	v_mov_b32_e32 v107, v120
	v_pk_mul_f32 v[108:109], v[108:109], v[108:109]
	v_mov_b32_e32 v122, v113
	v_mov_b32_e32 v123, v119
	v_pk_fma_f32 v[106:107], v[106:107], v[106:107], v[108:109]
	v_mov_b32_e32 v108, v112
	v_mov_b32_e32 v109, v118
	v_pk_mul_f32 v[122:123], v[122:123], v[122:123]
	v_pk_mul_f32 v[104:105], v[104:105], v[116:117] op_sel_hi:[1,0]
	v_pk_fma_f32 v[108:109], v[108:109], v[108:109], v[122:123]
	v_pk_mul_f32 v[102:103], v[102:103], v[116:117] op_sel_hi:[1,0]
	v_pk_add_f32 v[106:107], v[106:107], v[108:109]
	v_cvt_pk_bf16_f32 v108, v110, v111
	v_pk_add_f32 v[106:107], v[106:107], v[106:107] op_sel:[0,1] op_sel_hi:[1,0]
	v_cvt_pk_bf16_f32 v109, v112, v113
	v_cvt_pk_bf16_f32 v110, v120, v121
	v_cvt_pk_bf16_f32 v111, v118, v119
	global_store_dwordx4 v[114:115], v[108:111], off sc1 nt
	s_nop 2
	v_cndmask_b32_e64 v107, 0, 1, s[10:11]
	v_pk_mul_f32 v[100:101], v[100:101], v[116:117] op_sel_hi:[1,0]
	v_cmp_ne_u32_e64 s[8:9], 1, v107
	s_andn2_b64 vcc, exec, s[10:11]
	v_pk_mul_f32 v[98:99], v[98:99], v[116:117] op_sel_hi:[1,0]
	s_cbranch_vccz .LBB0_729
	v_cndmask_b32_e64 v106, 0, v106, s[4:5]
	s_branch .LBB0_730

; __device__ __forceinline__ unsigned cvtpk(float lo, float hi) { f32x2 v = {lo, hi}; bf16x2_t b = __builtin_convertvector(v, bf16x2_t); return __builtin_bit_cast(unsigned, b); }
; __device__ __forceinline__ float shx(float v, int o, int lane) { return __builtin_bit_cast(float, __builtin_amdgcn_ds_bpermute((lane ^ o) << 2, __builtin_bit_cast(int, v))); }
; __device__ __forceinline__ float sigmoidf_(float v) { return __builtin_amdgcn_rcpf(1.0f + __expf(-v)); }
; __device__ __forceinline__ void st16_wt(void* p, u32x4 v) { asm volatile("global_store_dwordx4 %0, %1, off sc1\n\ts_nop 2" :: "v"(p), "v"(v) : "memory"); }
;     __device__ __forceinline__ void operator()(const f32x4 (&acc)[2][2][4][2], const Unit& u, int wv) const {
;     ...
;             for (int bj = 0; bj < 2; ++bj) { f32x4 v0 = acc[ai][bj][m][0] * rstd, v1 = acc[ai][bj][m][1] * rstd;
;                 if (RSM && (u.pn == 0 || (u.pn == 1 && bj == 0))) ssm += ((v0[0] * v0[0] + v0[1] * v0[1]) + (v0[2] * v0[2] + v0[3] * v0[3])) + ((v1[0] * v1[0] + v1[1] * v1[1]) + (v1[2] * v1[2] + v1[3] * v1[3]));
;                 if (gate) {
; #pragma unroll
;                     for (int e = 0; e < 4; ++e) { v0[e] = sigmoidf_(v0[e]); v1[e] = sigmoidf_(v1[e]); } }
;                 u32x4 w; w.x = cvtpk(v0[0], v0[1]); w.y = cvtpk(v0[2], v0[3]); w.z = cvtpk(v1[0], v1[1]); w.w = cvtpk(v1[2], v1[3]);
;                 st16_wt(rowp + bj * HALF, w); }
;             if (RSM && u.pn < 2) { ssm += shx(ssm, 16, t_ & 63); ssm += shx(ssm, 32, t_ & 63);
;                 if (fq == 0) RSM[(size_t)(row0 + ai * HALF + m * 16) * 8 + u.pn * 4 + wc] = ssm; } }
.LBB0_730:
	v_cvt_pk_bf16_f32 v102, v102, v103
	v_cvt_pk_bf16_f32 v103, v104, v105
	v_cvt_pk_bf16_f32 v104, v98, v99
	v_cvt_pk_bf16_f32 v105, v100, v101
	v_lshl_add_u64 v[98:99], v[114:115], 0, s[0:1]
	global_store_dwordx4 v[98:99], v[102:105], off sc1 nt
	s_nop 2
	v_cndmask_b32_e64 v100, 0, 1, s[12:13]
	v_cmp_ne_u32_e64 s[10:11], 1, v100
	s_andn2_b64 vcc, exec, s[12:13]
	s_cbranch_vccnz .LBB0_734
	ds_bpermute_b32 v98, v180, v106
	s_waitcnt lgkmcnt(0)
	v_add_f32_e32 v98, v106, v98
	ds_bpermute_b32 v99, v0, v98
	s_and_saveexec_b64 s[12:13], s[6:7]
	s_cbranch_execz .LBB0_733
	v_lshlrev_b64 v[100:101], 5, v[156:157]
	v_lshl_add_u64 v[100:101], s[72:73], 0, v[100:101]
	v_lshl_add_u64 v[100:101], s[84:85], 2, v[100:101]
	s_lshl_b32 s22, s77, 2
	v_lshl_add_u64 v[100:101], v[100:101], 0, s[22:23]
	s_waitcnt lgkmcnt(0)
	v_add_f32_e32 v98, v98, v99
	global_store_dword v[100:101], v98, off

; __device__ __forceinline__ unsigned cvtpk(float lo, float hi) { f32x2 v = {lo, hi}; bf16x2_t b = __builtin_convertvector(v, bf16x2_t); return __builtin_bit_cast(unsigned, b); }
; __device__ __forceinline__ float sigmoidf_(float v) { return __builtin_amdgcn_rcpf(1.0f + __expf(-v)); }
; __device__ __forceinline__ void st16_wt(void* p, u32x4 v) { asm volatile("global_store_dwordx4 %0, %1, off sc1\n\ts_nop 2" :: "v"(p), "v"(v) : "memory"); }
; #define EPI_LOOP_ROWS for (int ai = 0; ai < 2; ++ai) _Pragma("unroll") for (int m = 0; m < 4; ++m)
; __device__ __forceinline__ float row_rstd_fin(float s, int lane) { s += shx(s, 16, lane); s += shx(s, 32, lane); return rsqrtf(s * (1.0f / 1024.0f) + EPS); }
;     __device__ __forceinline__ void operator()(const f32x4 (&acc)[2][2][4][2], const Unit& u, int wv) const {
;     ...
;         EPI_LOOP_ROWS rs[ai][m] = RS ? row_rstd_fin(rs[ai][m], t_ & 63) : 1.0f;
; #pragma unroll
;         EPI_LOOP_ROWS { bf16_t* rowp = base + (size_t)(row0 + ai * HALF + m * 16) * ldc + col0;
;             const float rstd = rs[ai][m];
;             float ssm = 0.f;
; #pragma unroll
;             for (int bj = 0; bj < 2; ++bj) { f32x4 v0 = acc[ai][bj][m][0] * rstd, v1 = acc[ai][bj][m][1] * rstd;
;                 if (RSM && (u.pn == 0 || (u.pn == 1 && bj == 0))) ssm += ((v0[0] * v0[0] + v0[1] * v0[1]) + (v0[2] * v0[2] + v0[3] * v0[3])) + ((v1[0] * v1[0] + v1[1] * v1[1]) + (v1[2] * v1[2] + v1[3] * v1[3]));
;                 if (gate) {
; #pragma unroll
;                     for (int e = 0; e < 4; ++e) { v0[e] = sigmoidf_(v0[e]); v1[e] = sigmoidf_(v1[e]); } }
;                 u32x4 w; w.x = cvtpk(v0[0], v0[1]); w.y = cvtpk(v0[2], v0[3]); w.z = cvtpk(v1[0], v1[1]); w.w = cvtpk(v1[2], v1[3]);
;                 st16_wt(rowp + bj * HALF, w); }
.LBB0_734:
	s_waitcnt lgkmcnt(0)
	v_pk_add_f32 v[98:99], v[170:171], v[174:175]
	s_nop 0
	v_pk_fma_f32 v[98:99], v[98:99], s[56:57], v[194:195] op_sel_hi:[1,0,0]
	s_nop 0
	v_mul_f32_e32 v100, 0x4b800000, v99
	v_cmp_gt_f32_e32 vcc, s97, v99
	v_cmp_gt_f32_e64 s[12:13], s97, v98
	s_nop 0
	v_cndmask_b32_e32 v99, v99, v100, vcc
	v_rsq_f32_e32 v99, v99
	v_lshlrev_b64 v[100:101], 13, v[152:153]
	v_lshl_add_u64 v[100:101], v[154:155], 0, v[100:101]
	v_mul_f32_e32 v102, 0x45800000, v99
	v_cndmask_b32_e32 v102, v99, v102, vcc
	v_pk_mul_f32 v[94:95], v[94:95], v[102:103] op_sel_hi:[1,0]
	v_pk_mul_f32 v[106:107], v[90:91], v[102:103] op_sel_hi:[1,0]
	v_pk_mul_f32 v[96:97], v[96:97], v[102:103] op_sel_hi:[1,0]
	v_pk_mul_f32 v[104:105], v[92:93], v[102:103] op_sel_hi:[1,0]
	v_mov_b32_e32 v92, v95
	v_mov_b32_e32 v93, v107
	v_mov_b32_e32 v90, v94
	v_mov_b32_e32 v91, v106
	v_pk_mul_f32 v[92:93], v[92:93], v[92:93]
	v_mov_b32_e32 v108, v97
	v_mov_b32_e32 v109, v105
	v_pk_fma_f32 v[90:91], v[90:91], v[90:91], v[92:93]
	v_mov_b32_e32 v92, v96
	v_mov_b32_e32 v93, v104
	v_pk_mul_f32 v[108:109], v[108:109], v[108:109]
	v_pk_mul_f32 v[88:89], v[88:89], v[102:103] op_sel_hi:[1,0]
	v_pk_fma_f32 v[92:93], v[92:93], v[92:93], v[108:109]
	v_pk_mul_f32 v[86:87], v[86:87], v[102:103] op_sel_hi:[1,0]
	v_pk_add_f32 v[90:91], v[90:91], v[92:93]
	v_cvt_pk_bf16_f32 v92, v94, v95
	v_cvt_pk_bf16_f32 v93, v96, v97
	v_cvt_pk_bf16_f32 v94, v106, v107
	v_cvt_pk_bf16_f32 v95, v104, v105
	global_store_dwordx4 v[100:101], v[92:95], off sc1 nt
	s_nop 2
	v_pk_add_f32 v[90:91], v[90:91], v[90:91] op_sel:[0,1] op_sel_hi:[1,0]
	v_pk_mul_f32 v[84:85], v[84:85], v[102:103] op_sel_hi:[1,0]
	s_and_b64 vcc, exec, s[8:9]
	v_pk_mul_f32 v[82:83], v[82:83], v[102:103] op_sel_hi:[1,0]
	s_cbranch_vccz .LBB0_736
	v_cndmask_b32_e64 v90, 0, v90, s[4:5]
	s_branch .LBB0_737

; __device__ __forceinline__ unsigned cvtpk(float lo, float hi) { f32x2 v = {lo, hi}; bf16x2_t b = __builtin_convertvector(v, bf16x2_t); return __builtin_bit_cast(unsigned, b); }
; __device__ __forceinline__ float shx(float v, int o, int lane) { return __builtin_bit_cast(float, __builtin_amdgcn_ds_bpermute((lane ^ o) << 2, __builtin_bit_cast(int, v))); }
; __device__ __forceinline__ float sigmoidf_(float v) { return __builtin_amdgcn_rcpf(1.0f + __expf(-v)); }
; __device__ __forceinline__ void st16_wt(void* p, u32x4 v) { asm volatile("global_store_dwordx4 %0, %1, off sc1\n\ts_nop 2" :: "v"(p), "v"(v) : "memory"); }
;     __device__ __forceinline__ void operator()(const f32x4 (&acc)[2][2][4][2], const Unit& u, int wv) const {
;     ...
;             for (int bj = 0; bj < 2; ++bj) { f32x4 v0 = acc[ai][bj][m][0] * rstd, v1 = acc[ai][bj][m][1] * rstd;
;                 if (RSM && (u.pn == 0 || (u.pn == 1 && bj == 0))) ssm += ((v0[0] * v0[0] + v0[1] * v0[1]) + (v0[2] * v0[2] + v0[3] * v0[3])) + ((v1[0] * v1[0] + v1[1] * v1[1]) + (v1[2] * v1[2] + v1[3] * v1[3]));
;                 if (gate) {
; #pragma unroll
;                     for (int e = 0; e < 4; ++e) { v0[e] = sigmoidf_(v0[e]); v1[e] = sigmoidf_(v1[e]); } }
;                 u32x4 w; w.x = cvtpk(v0[0], v0[1]); w.y = cvtpk(v0[2], v0[3]); w.z = cvtpk(v1[0], v1[1]); w.w = cvtpk(v1[2], v1[3]);
;                 st16_wt(rowp + bj * HALF, w); }
;             if (RSM && u.pn < 2) { ssm += shx(ssm, 16, t_ & 63); ssm += shx(ssm, 32, t_ & 63);
;                 if (fq == 0) RSM[(size_t)(row0 + ai * HALF + m * 16) * 8 + u.pn * 4 + wc] = ssm; } }
.LBB0_737:
	v_cvt_pk_bf16_f32 v86, v86, v87
	v_cvt_pk_bf16_f32 v87, v88, v89
	v_cvt_pk_bf16_f32 v88, v82, v83
	v_cvt_pk_bf16_f32 v89, v84, v85
	v_lshl_add_u64 v[82:83], v[100:101], 0, s[0:1]
	global_store_dwordx4 v[82:83], v[86:89], off sc1 nt
	s_nop 2
	s_and_b64 vcc, exec, s[10:11]
	s_cbranch_vccnz .LBB0_741
	ds_bpermute_b32 v82, v180, v90
	s_waitcnt lgkmcnt(0)
	v_add_f32_e32 v82, v90, v82
	ds_bpermute_b32 v83, v0, v82
	s_and_saveexec_b64 s[86:87], s[6:7]
	s_cbranch_execz .LBB0_740
	v_lshlrev_b64 v[84:85], 5, v[152:153]
	v_lshl_add_u64 v[84:85], s[72:73], 0, v[84:85]
	v_lshl_add_u64 v[84:85], s[84:85], 2, v[84:85]
	s_lshl_b32 s22, s77, 2
	v_lshl_add_u64 v[84:85], v[84:85], 0, s[22:23]
	s_waitcnt lgkmcnt(0)
	v_add_f32_e32 v82, v82, v83
	global_store_dword v[84:85], v82, off

; __device__ __forceinline__ unsigned cvtpk(float lo, float hi) { f32x2 v = {lo, hi}; bf16x2_t b = __builtin_convertvector(v, bf16x2_t); return __builtin_bit_cast(unsigned, b); }
; __device__ __forceinline__ float sigmoidf_(float v) { return __builtin_amdgcn_rcpf(1.0f + __expf(-v)); }
; __device__ __forceinline__ void st16_wt(void* p, u32x4 v) { asm volatile("global_store_dwordx4 %0, %1, off sc1\n\ts_nop 2" :: "v"(p), "v"(v) : "memory"); }
; #define EPI_LOOP_ROWS for (int ai = 0; ai < 2; ++ai) _Pragma("unroll") for (int m = 0; m < 4; ++m)
; __device__ __forceinline__ float row_rstd_fin(float s, int lane) { s += shx(s, 16, lane); s += shx(s, 32, lane); return rsqrtf(s * (1.0f / 1024.0f) + EPS); }
;     __device__ __forceinline__ void operator()(const f32x4 (&acc)[2][2][4][2], const Unit& u, int wv) const {
;     ...
;         EPI_LOOP_ROWS rs[ai][m] = RS ? row_rstd_fin(rs[ai][m], t_ & 63) : 1.0f;
; #pragma unroll
;         EPI_LOOP_ROWS { bf16_t* rowp = base + (size_t)(row0 + ai * HALF + m * 16) * ldc + col0;
;             const float rstd = rs[ai][m];
;             float ssm = 0.f;
; #pragma unroll
;             for (int bj = 0; bj < 2; ++bj) { f32x4 v0 = acc[ai][bj][m][0] * rstd, v1 = acc[ai][bj][m][1] * rstd;
;                 if (RSM && (u.pn == 0 || (u.pn == 1 && bj == 0))) ssm += ((v0[0] * v0[0] + v0[1] * v0[1]) + (v0[2] * v0[2] + v0[3] * v0[3])) + ((v1[0] * v1[0] + v1[1] * v1[1]) + (v1[2] * v1[2] + v1[3] * v1[3]));
;                 if (gate) {
; #pragma unroll
;                     for (int e = 0; e < 4; ++e) { v0[e] = sigmoidf_(v0[e]); v1[e] = sigmoidf_(v1[e]); } }
;                 u32x4 w; w.x = cvtpk(v0[0], v0[1]); w.y = cvtpk(v0[2], v0[3]); w.z = cvtpk(v1[0], v1[1]); w.w = cvtpk(v1[2], v1[3]);
;                 st16_wt(rowp + bj * HALF, w); }
.LBB0_741:
	v_mul_f32_e32 v82, 0x4b800000, v98
	v_cndmask_b32_e64 v82, v98, v82, s[12:13]
	v_rsq_f32_e32 v84, v82
	s_waitcnt lgkmcnt(0)
	v_lshlrev_b64 v[82:83], 13, v[150:151]
	v_lshl_add_u64 v[82:83], v[154:155], 0, v[82:83]
	s_and_b64 vcc, exec, s[8:9]
	v_mul_f32_e32 v85, 0x45800000, v84
	v_cndmask_b32_e64 v84, v84, v85, s[12:13]
	v_pk_mul_f32 v[78:79], v[78:79], v[84:85] op_sel_hi:[1,0]
	v_pk_mul_f32 v[88:89], v[74:75], v[84:85] op_sel_hi:[1,0]
	v_pk_mul_f32 v[80:81], v[80:81], v[84:85] op_sel_hi:[1,0]
	v_pk_mul_f32 v[86:87], v[76:77], v[84:85] op_sel_hi:[1,0]
	v_mov_b32_e32 v76, v79
	v_mov_b32_e32 v77, v89
	v_mov_b32_e32 v74, v78
	v_mov_b32_e32 v75, v88
	v_pk_mul_f32 v[76:77], v[76:77], v[76:77]
	v_mov_b32_e32 v90, v81
	v_mov_b32_e32 v91, v87
	v_pk_fma_f32 v[74:75], v[74:75], v[74:75], v[76:77]
	v_mov_b32_e32 v76, v80
	v_mov_b32_e32 v77, v86
	v_pk_mul_f32 v[90:91], v[90:91], v[90:91]
	v_pk_mul_f32 v[72:73], v[72:73], v[84:85] op_sel_hi:[1,0]
	v_pk_fma_f32 v[76:77], v[76:77], v[76:77], v[90:91]
	v_pk_mul_f32 v[70:71], v[70:71], v[84:85] op_sel_hi:[1,0]
	v_pk_add_f32 v[74:75], v[74:75], v[76:77]
	v_cvt_pk_bf16_f32 v76, v78, v79
	v_cvt_pk_bf16_f32 v77, v80, v81
	v_cvt_pk_bf16_f32 v78, v88, v89
	v_cvt_pk_bf16_f32 v79, v86, v87
	global_store_dwordx4 v[82:83], v[76:79], off sc1 nt
	s_nop 2
	v_pk_add_f32 v[74:75], v[74:75], v[74:75] op_sel:[0,1] op_sel_hi:[1,0]
	v_pk_mul_f32 v[68:69], v[68:69], v[84:85] op_sel_hi:[1,0]
	v_pk_mul_f32 v[66:67], v[66:67], v[84:85] op_sel_hi:[1,0]
	s_cbranch_vccz .LBB0_743
	v_cndmask_b32_e64 v74, 0, v74, s[4:5]
	s_branch .LBB0_744

; __device__ __forceinline__ unsigned cvtpk(float lo, float hi) { f32x2 v = {lo, hi}; bf16x2_t b = __builtin_convertvector(v, bf16x2_t); return __builtin_bit_cast(unsigned, b); }
; __device__ __forceinline__ float shx(float v, int o, int lane) { return __builtin_bit_cast(float, __builtin_amdgcn_ds_bpermute((lane ^ o) << 2, __builtin_bit_cast(int, v))); }
; __device__ __forceinline__ float sigmoidf_(float v) { return __builtin_amdgcn_rcpf(1.0f + __expf(-v)); }
; __device__ __forceinline__ void st16_wt(void* p, u32x4 v) { asm volatile("global_store_dwordx4 %0, %1, off sc1\n\ts_nop 2" :: "v"(p), "v"(v) : "memory"); }
;     __device__ __forceinline__ void operator()(const f32x4 (&acc)[2][2][4][2], const Unit& u, int wv) const {
;     ...
;             for (int bj = 0; bj < 2; ++bj) { f32x4 v0 = acc[ai][bj][m][0] * rstd, v1 = acc[ai][bj][m][1] * rstd;
;                 if (RSM && (u.pn == 0 || (u.pn == 1 && bj == 0))) ssm += ((v0[0] * v0[0] + v0[1] * v0[1]) + (v0[2] * v0[2] + v0[3] * v0[3])) + ((v1[0] * v1[0] + v1[1] * v1[1]) + (v1[2] * v1[2] + v1[3] * v1[3]));
;                 if (gate) {
; #pragma unroll
;                     for (int e = 0; e < 4; ++e) { v0[e] = sigmoidf_(v0[e]); v1[e] = sigmoidf_(v1[e]); } }
;                 u32x4 w; w.x = cvtpk(v0[0], v0[1]); w.y = cvtpk(v0[2], v0[3]); w.z = cvtpk(v1[0], v1[1]); w.w = cvtpk(v1[2], v1[3]);
;                 st16_wt(rowp + bj * HALF, w); }
;             if (RSM && u.pn < 2) { ssm += shx(ssm, 16, t_ & 63); ssm += shx(ssm, 32, t_ & 63);
;                 if (fq == 0) RSM[(size_t)(row0 + ai * HALF + m * 16) * 8 + u.pn * 4 + wc] = ssm; } }
.LBB0_744:
	v_cvt_pk_bf16_f32 v70, v70, v71
	v_cvt_pk_bf16_f32 v71, v72, v73
	v_cvt_pk_bf16_f32 v72, v66, v67
	v_cvt_pk_bf16_f32 v73, v68, v69
	v_lshl_add_u64 v[66:67], v[82:83], 0, s[0:1]
	global_store_dwordx4 v[66:67], v[70:73], off sc1 nt
	s_nop 2
	s_and_b64 vcc, exec, s[10:11]
	s_cbranch_vccnz .LBB0_748
	ds_bpermute_b32 v66, v180, v74
	s_waitcnt lgkmcnt(0)
	v_add_f32_e32 v66, v74, v66
	ds_bpermute_b32 v67, v0, v66
	s_and_saveexec_b64 s[12:13], s[6:7]
	s_cbranch_execz .LBB0_747
	v_lshlrev_b64 v[68:69], 5, v[150:151]
	v_lshl_add_u64 v[68:69], s[72:73], 0, v[68:69]
	v_lshl_add_u64 v[68:69], s[84:85], 2, v[68:69]
	s_lshl_b32 s22, s77, 2
	v_lshl_add_u64 v[68:69], v[68:69], 0, s[22:23]
	s_waitcnt lgkmcnt(0)
	v_add_f32_e32 v66, v66, v67
	global_store_dword v[68:69], v66, off

; __device__ __forceinline__ unsigned cvtpk(float lo, float hi) { f32x2 v = {lo, hi}; bf16x2_t b = __builtin_convertvector(v, bf16x2_t); return __builtin_bit_cast(unsigned, b); }
; __device__ __forceinline__ float sigmoidf_(float v) { return __builtin_amdgcn_rcpf(1.0f + __expf(-v)); }
; __device__ __forceinline__ void st16_wt(void* p, u32x4 v) { asm volatile("global_store_dwordx4 %0, %1, off sc1\n\ts_nop 2" :: "v"(p), "v"(v) : "memory"); }
; #define EPI_LOOP_ROWS for (int ai = 0; ai < 2; ++ai) _Pragma("unroll") for (int m = 0; m < 4; ++m)
; __device__ __forceinline__ float row_rstd_fin(float s, int lane) { s += shx(s, 16, lane); s += shx(s, 32, lane); return rsqrtf(s * (1.0f / 1024.0f) + EPS); }
;     __device__ __forceinline__ void operator()(const f32x4 (&acc)[2][2][4][2], const Unit& u, int wv) const {
;     ...
;         EPI_LOOP_ROWS rs[ai][m] = RS ? row_rstd_fin(rs[ai][m], t_ & 63) : 1.0f;
; #pragma unroll
;         EPI_LOOP_ROWS { bf16_t* rowp = base + (size_t)(row0 + ai * HALF + m * 16) * ldc + col0;
;             const float rstd = rs[ai][m];
;             float ssm = 0.f;
; #pragma unroll
;             for (int bj = 0; bj < 2; ++bj) { f32x4 v0 = acc[ai][bj][m][0] * rstd, v1 = acc[ai][bj][m][1] * rstd;
;                 if (RSM && (u.pn == 0 || (u.pn == 1 && bj == 0))) ssm += ((v0[0] * v0[0] + v0[1] * v0[1]) + (v0[2] * v0[2] + v0[3] * v0[3])) + ((v1[0] * v1[0] + v1[1] * v1[1]) + (v1[2] * v1[2] + v1[3] * v1[3]));
;                 if (gate) {
; #pragma unroll
;                     for (int e = 0; e < 4; ++e) { v0[e] = sigmoidf_(v0[e]); v1[e] = sigmoidf_(v1[e]); } }
;                 u32x4 w; w.x = cvtpk(v0[0], v0[1]); w.y = cvtpk(v0[2], v0[3]); w.z = cvtpk(v1[0], v1[1]); w.w = cvtpk(v1[2], v1[3]);
;                 st16_wt(rowp + bj * HALF, w); }
.LBB0_748:
	s_waitcnt lgkmcnt(0)
	v_pk_add_f32 v[66:67], v[164:165], v[166:167]
	s_nop 0
	v_pk_fma_f32 v[66:67], v[66:67], s[56:57], v[194:195] op_sel_hi:[1,0,0]
	s_nop 0
	v_mul_f32_e32 v68, 0x4b800000, v67
	v_cmp_gt_f32_e32 vcc, s97, v67
	v_cmp_gt_f32_e64 s[12:13], s97, v66
	s_nop 0
	v_cndmask_b32_e32 v67, v67, v68, vcc
	v_rsq_f32_e32 v67, v67
	v_lshlrev_b64 v[68:69], 13, v[148:149]
	v_lshl_add_u64 v[68:69], v[154:155], 0, v[68:69]
	v_mul_f32_e32 v70, 0x45800000, v67
	v_cndmask_b32_e32 v70, v67, v70, vcc
	v_pk_mul_f32 v[62:63], v[62:63], v[70:71] op_sel_hi:[1,0]
	v_pk_mul_f32 v[74:75], v[58:59], v[70:71] op_sel_hi:[1,0]
	v_pk_mul_f32 v[64:65], v[64:65], v[70:71] op_sel_hi:[1,0]
	v_pk_mul_f32 v[72:73], v[60:61], v[70:71] op_sel_hi:[1,0]
	v_mov_b32_e32 v60, v63
	v_mov_b32_e32 v61, v75
	v_mov_b32_e32 v58, v62
	v_mov_b32_e32 v59, v74
	v_pk_mul_f32 v[60:61], v[60:61], v[60:61]
	v_mov_b32_e32 v76, v65
	v_mov_b32_e32 v77, v73
	v_pk_fma_f32 v[58:59], v[58:59], v[58:59], v[60:61]
	v_mov_b32_e32 v60, v64
	v_mov_b32_e32 v61, v72
	v_pk_mul_f32 v[76:77], v[76:77], v[76:77]
	v_pk_mul_f32 v[56:57], v[56:57], v[70:71] op_sel_hi:[1,0]
	v_pk_fma_f32 v[60:61], v[60:61], v[60:61], v[76:77]
	v_pk_mul_f32 v[54:55], v[54:55], v[70:71] op_sel_hi:[1,0]
	v_pk_add_f32 v[58:59], v[58:59], v[60:61]
	v_cvt_pk_bf16_f32 v60, v62, v63
	v_cvt_pk_bf16_f32 v61, v64, v65
	v_cvt_pk_bf16_f32 v62, v74, v75
	v_cvt_pk_bf16_f32 v63, v72, v73
	global_store_dwordx4 v[68:69], v[60:63], off sc1 nt
	s_nop 2
	v_pk_add_f32 v[58:59], v[58:59], v[58:59] op_sel:[0,1] op_sel_hi:[1,0]
	v_pk_mul_f32 v[52:53], v[52:53], v[70:71] op_sel_hi:[1,0]
	s_and_b64 vcc, exec, s[8:9]
	v_pk_mul_f32 v[50:51], v[50:51], v[70:71] op_sel_hi:[1,0]
	s_cbranch_vccz .LBB0_750
	v_cndmask_b32_e64 v58, 0, v58, s[4:5]
	s_branch .LBB0_751

; __device__ __forceinline__ unsigned cvtpk(float lo, float hi) { f32x2 v = {lo, hi}; bf16x2_t b = __builtin_convertvector(v, bf16x2_t); return __builtin_bit_cast(unsigned, b); }
; __device__ __forceinline__ float shx(float v, int o, int lane) { return __builtin_bit_cast(float, __builtin_amdgcn_ds_bpermute((lane ^ o) << 2, __builtin_bit_cast(int, v))); }
; __device__ __forceinline__ float sigmoidf_(float v) { return __builtin_amdgcn_rcpf(1.0f + __expf(-v)); }
; __device__ __forceinline__ void st16_wt(void* p, u32x4 v) { asm volatile("global_store_dwordx4 %0, %1, off sc1\n\ts_nop 2" :: "v"(p), "v"(v) : "memory"); }
;     __device__ __forceinline__ void operator()(const f32x4 (&acc)[2][2][4][2], const Unit& u, int wv) const {
;     ...
;             for (int bj = 0; bj < 2; ++bj) { f32x4 v0 = acc[ai][bj][m][0] * rstd, v1 = acc[ai][bj][m][1] * rstd;
;                 if (RSM && (u.pn == 0 || (u.pn == 1 && bj == 0))) ssm += ((v0[0] * v0[0] + v0[1] * v0[1]) + (v0[2] * v0[2] + v0[3] * v0[3])) + ((v1[0] * v1[0] + v1[1] * v1[1]) + (v1[2] * v1[2] + v1[3] * v1[3]));
;                 if (gate) {
; #pragma unroll
;                     for (int e = 0; e < 4; ++e) { v0[e] = sigmoidf_(v0[e]); v1[e] = sigmoidf_(v1[e]); } }
;                 u32x4 w; w.x = cvtpk(v0[0], v0[1]); w.y = cvtpk(v0[2], v0[3]); w.z = cvtpk(v1[0], v1[1]); w.w = cvtpk(v1[2], v1[3]);
;                 st16_wt(rowp + bj * HALF, w); }
;             if (RSM && u.pn < 2) { ssm += shx(ssm, 16, t_ & 63); ssm += shx(ssm, 32, t_ & 63);
;                 if (fq == 0) RSM[(size_t)(row0 + ai * HALF + m * 16) * 8 + u.pn * 4 + wc] = ssm; } }
.LBB0_751:
	v_cvt_pk_bf16_f32 v54, v54, v55
	v_cvt_pk_bf16_f32 v55, v56, v57
	v_cvt_pk_bf16_f32 v56, v50, v51
	v_cvt_pk_bf16_f32 v57, v52, v53
	v_lshl_add_u64 v[50:51], v[68:69], 0, s[0:1]
	global_store_dwordx4 v[50:51], v[54:57], off sc1 nt
	s_nop 2
	s_and_b64 vcc, exec, s[10:11]
	s_cbranch_vccnz .LBB0_755
	ds_bpermute_b32 v50, v180, v58
	s_waitcnt lgkmcnt(0)
	v_add_f32_e32 v50, v58, v50
	ds_bpermute_b32 v51, v0, v50
	s_and_saveexec_b64 s[86:87], s[6:7]
	s_cbranch_execz .LBB0_754
	v_lshlrev_b64 v[52:53], 5, v[148:149]
	v_lshl_add_u64 v[52:53], s[72:73], 0, v[52:53]
	v_lshl_add_u64 v[52:53], s[84:85], 2, v[52:53]
	s_lshl_b32 s22, s77, 2
	v_lshl_add_u64 v[52:53], v[52:53], 0, s[22:23]
	s_waitcnt lgkmcnt(0)
	v_add_f32_e32 v50, v50, v51
	global_store_dword v[52:53], v50, off

; __device__ __forceinline__ unsigned cvtpk(float lo, float hi) { f32x2 v = {lo, hi}; bf16x2_t b = __builtin_convertvector(v, bf16x2_t); return __builtin_bit_cast(unsigned, b); }
; __device__ __forceinline__ float sigmoidf_(float v) { return __builtin_amdgcn_rcpf(1.0f + __expf(-v)); }
; __device__ __forceinline__ void st16_wt(void* p, u32x4 v) { asm volatile("global_store_dwordx4 %0, %1, off sc1\n\ts_nop 2" :: "v"(p), "v"(v) : "memory"); }
; #define EPI_LOOP_ROWS for (int ai = 0; ai < 2; ++ai) _Pragma("unroll") for (int m = 0; m < 4; ++m)
; __device__ __forceinline__ float row_rstd_fin(float s, int lane) { s += shx(s, 16, lane); s += shx(s, 32, lane); return rsqrtf(s * (1.0f / 1024.0f) + EPS); }
;     __device__ __forceinline__ void operator()(const f32x4 (&acc)[2][2][4][2], const Unit& u, int wv) const {
;     ...
;         EPI_LOOP_ROWS rs[ai][m] = RS ? row_rstd_fin(rs[ai][m], t_ & 63) : 1.0f;
; #pragma unroll
;         EPI_LOOP_ROWS { bf16_t* rowp = base + (size_t)(row0 + ai * HALF + m * 16) * ldc + col0;
;             const float rstd = rs[ai][m];
;             float ssm = 0.f;
; #pragma unroll
;             for (int bj = 0; bj < 2; ++bj) { f32x4 v0 = acc[ai][bj][m][0] * rstd, v1 = acc[ai][bj][m][1] * rstd;
;                 if (RSM && (u.pn == 0 || (u.pn == 1 && bj == 0))) ssm += ((v0[0] * v0[0] + v0[1] * v0[1]) + (v0[2] * v0[2] + v0[3] * v0[3])) + ((v1[0] * v1[0] + v1[1] * v1[1]) + (v1[2] * v1[2] + v1[3] * v1[3]));
;                 if (gate) {
; #pragma unroll
;                     for (int e = 0; e < 4; ++e) { v0[e] = sigmoidf_(v0[e]); v1[e] = sigmoidf_(v1[e]); } }
;                 u32x4 w; w.x = cvtpk(v0[0], v0[1]); w.y = cvtpk(v0[2], v0[3]); w.z = cvtpk(v1[0], v1[1]); w.w = cvtpk(v1[2], v1[3]);
;                 st16_wt(rowp + bj * HALF, w); }
.LBB0_755:
	v_mul_f32_e32 v50, 0x4b800000, v66
	v_cndmask_b32_e64 v50, v66, v50, s[12:13]
	v_rsq_f32_e32 v52, v50
	s_waitcnt lgkmcnt(0)
	v_lshlrev_b64 v[50:51], 13, v[146:147]
	v_lshl_add_u64 v[50:51], v[154:155], 0, v[50:51]
	s_and_b64 vcc, exec, s[8:9]
	v_mul_f32_e32 v53, 0x45800000, v52
	v_cndmask_b32_e64 v52, v52, v53, s[12:13]
	v_pk_mul_f32 v[46:47], v[46:47], v[52:53] op_sel_hi:[1,0]
	v_pk_mul_f32 v[56:57], v[42:43], v[52:53] op_sel_hi:[1,0]
	v_pk_mul_f32 v[48:49], v[48:49], v[52:53] op_sel_hi:[1,0]
	v_pk_mul_f32 v[54:55], v[44:45], v[52:53] op_sel_hi:[1,0]
	v_mov_b32_e32 v44, v47
	v_mov_b32_e32 v45, v57
	v_mov_b32_e32 v42, v46
	v_mov_b32_e32 v43, v56
	v_pk_mul_f32 v[44:45], v[44:45], v[44:45]
	v_mov_b32_e32 v58, v49
	v_mov_b32_e32 v59, v55
	v_pk_fma_f32 v[42:43], v[42:43], v[42:43], v[44:45]
	v_mov_b32_e32 v44, v48
	v_mov_b32_e32 v45, v54
	v_pk_mul_f32 v[58:59], v[58:59], v[58:59]
	v_pk_mul_f32 v[40:41], v[40:41], v[52:53] op_sel_hi:[1,0]
	v_pk_fma_f32 v[44:45], v[44:45], v[44:45], v[58:59]
	v_pk_mul_f32 v[38:39], v[38:39], v[52:53] op_sel_hi:[1,0]
	v_pk_add_f32 v[42:43], v[42:43], v[44:45]
	v_cvt_pk_bf16_f32 v44, v46, v47
	v_cvt_pk_bf16_f32 v45, v48, v49
	v_cvt_pk_bf16_f32 v46, v56, v57
	v_cvt_pk_bf16_f32 v47, v54, v55
	global_store_dwordx4 v[50:51], v[44:47], off sc1 nt
	s_nop 2
	v_pk_add_f32 v[42:43], v[42:43], v[42:43] op_sel:[0,1] op_sel_hi:[1,0]
	v_pk_mul_f32 v[36:37], v[36:37], v[52:53] op_sel_hi:[1,0]
	v_pk_mul_f32 v[34:35], v[34:35], v[52:53] op_sel_hi:[1,0]
	s_cbranch_vccz .LBB0_757
	v_cndmask_b32_e64 v42, 0, v42, s[4:5]
	s_branch .LBB0_758

; __device__ __forceinline__ unsigned cvtpk(float lo, float hi) { f32x2 v = {lo, hi}; bf16x2_t b = __builtin_convertvector(v, bf16x2_t); return __builtin_bit_cast(unsigned, b); }
; __device__ __forceinline__ float shx(float v, int o, int lane) { return __builtin_bit_cast(float, __builtin_amdgcn_ds_bpermute((lane ^ o) << 2, __builtin_bit_cast(int, v))); }
; __device__ __forceinline__ float sigmoidf_(float v) { return __builtin_amdgcn_rcpf(1.0f + __expf(-v)); }
; __device__ __forceinline__ void st16_wt(void* p, u32x4 v) { asm volatile("global_store_dwordx4 %0, %1, off sc1\n\ts_nop 2" :: "v"(p), "v"(v) : "memory"); }
;     __device__ __forceinline__ void operator()(const f32x4 (&acc)[2][2][4][2], const Unit& u, int wv) const {
;     ...
;             for (int bj = 0; bj < 2; ++bj) { f32x4 v0 = acc[ai][bj][m][0] * rstd, v1 = acc[ai][bj][m][1] * rstd;
;                 if (RSM && (u.pn == 0 || (u.pn == 1 && bj == 0))) ssm += ((v0[0] * v0[0] + v0[1] * v0[1]) + (v0[2] * v0[2] + v0[3] * v0[3])) + ((v1[0] * v1[0] + v1[1] * v1[1]) + (v1[2] * v1[2] + v1[3] * v1[3]));
;                 if (gate) {
; #pragma unroll
;                     for (int e = 0; e < 4; ++e) { v0[e] = sigmoidf_(v0[e]); v1[e] = sigmoidf_(v1[e]); } }
;                 u32x4 w; w.x = cvtpk(v0[0], v0[1]); w.y = cvtpk(v0[2], v0[3]); w.z = cvtpk(v1[0], v1[1]); w.w = cvtpk(v1[2], v1[3]);
;                 st16_wt(rowp + bj * HALF, w); }
;             if (RSM && u.pn < 2) { ssm += shx(ssm, 16, t_ & 63); ssm += shx(ssm, 32, t_ & 63);
;                 if (fq == 0) RSM[(size_t)(row0 + ai * HALF + m * 16) * 8 + u.pn * 4 + wc] = ssm; } }
.LBB0_758:
	v_cvt_pk_bf16_f32 v38, v38, v39
	v_cvt_pk_bf16_f32 v39, v40, v41
	v_cvt_pk_bf16_f32 v40, v34, v35
	v_cvt_pk_bf16_f32 v41, v36, v37
	v_lshl_add_u64 v[34:35], v[50:51], 0, s[0:1]
	global_store_dwordx4 v[34:35], v[38:41], off sc1 nt
	s_nop 2
	s_and_b64 vcc, exec, s[10:11]
	s_cbranch_vccnz .LBB0_762
	ds_bpermute_b32 v34, v180, v42
	s_waitcnt lgkmcnt(0)
	v_add_f32_e32 v34, v42, v34
	ds_bpermute_b32 v35, v0, v34
	s_and_saveexec_b64 s[12:13], s[6:7]
	s_cbranch_execz .LBB0_761
	v_lshlrev_b64 v[36:37], 5, v[146:147]
	v_lshl_add_u64 v[36:37], s[72:73], 0, v[36:37]
	v_lshl_add_u64 v[36:37], s[84:85], 2, v[36:37]
	s_lshl_b32 s22, s77, 2
	v_lshl_add_u64 v[36:37], v[36:37], 0, s[22:23]
	s_waitcnt lgkmcnt(0)
	v_add_f32_e32 v34, v34, v35
	global_store_dword v[36:37], v34, off

; __device__ __forceinline__ unsigned cvtpk(float lo, float hi) { f32x2 v = {lo, hi}; bf16x2_t b = __builtin_convertvector(v, bf16x2_t); return __builtin_bit_cast(unsigned, b); }
; __device__ __forceinline__ float sigmoidf_(float v) { return __builtin_amdgcn_rcpf(1.0f + __expf(-v)); }
; __device__ __forceinline__ void st16_wt(void* p, u32x4 v) { asm volatile("global_store_dwordx4 %0, %1, off sc1\n\ts_nop 2" :: "v"(p), "v"(v) : "memory"); }
; #define EPI_LOOP_ROWS for (int ai = 0; ai < 2; ++ai) _Pragma("unroll") for (int m = 0; m < 4; ++m)
; __device__ __forceinline__ float row_rstd_fin(float s, int lane) { s += shx(s, 16, lane); s += shx(s, 32, lane); return rsqrtf(s * (1.0f / 1024.0f) + EPS); }
;     __device__ __forceinline__ void operator()(const f32x4 (&acc)[2][2][4][2], const Unit& u, int wv) const {
;     ...
;         EPI_LOOP_ROWS rs[ai][m] = RS ? row_rstd_fin(rs[ai][m], t_ & 63) : 1.0f;
; #pragma unroll
;         EPI_LOOP_ROWS { bf16_t* rowp = base + (size_t)(row0 + ai * HALF + m * 16) * ldc + col0;
;             const float rstd = rs[ai][m];
;             float ssm = 0.f;
; #pragma unroll
;             for (int bj = 0; bj < 2; ++bj) { f32x4 v0 = acc[ai][bj][m][0] * rstd, v1 = acc[ai][bj][m][1] * rstd;
;                 if (RSM && (u.pn == 0 || (u.pn == 1 && bj == 0))) ssm += ((v0[0] * v0[0] + v0[1] * v0[1]) + (v0[2] * v0[2] + v0[3] * v0[3])) + ((v1[0] * v1[0] + v1[1] * v1[1]) + (v1[2] * v1[2] + v1[3] * v1[3]));
;                 if (gate) {
; #pragma unroll
;                     for (int e = 0; e < 4; ++e) { v0[e] = sigmoidf_(v0[e]); v1[e] = sigmoidf_(v1[e]); } }
;                 u32x4 w; w.x = cvtpk(v0[0], v0[1]); w.y = cvtpk(v0[2], v0[3]); w.z = cvtpk(v1[0], v1[1]); w.w = cvtpk(v1[2], v1[3]);
;                 st16_wt(rowp + bj * HALF, w); }
.LBB0_762:
	s_waitcnt lgkmcnt(0)
	v_pk_add_f32 v[34:35], v[158:159], v[160:161]
	s_nop 0
	v_pk_fma_f32 v[34:35], v[34:35], s[56:57], v[194:195] op_sel_hi:[1,0,0]
	s_nop 0
	v_mul_f32_e32 v36, 0x4b800000, v35
	v_cmp_gt_f32_e32 vcc, s97, v35
	v_cmp_gt_f32_e64 s[12:13], s97, v34
	s_nop 0
	v_cndmask_b32_e32 v35, v35, v36, vcc
	v_rsq_f32_e32 v35, v35
	v_lshlrev_b64 v[36:37], 13, v[144:145]
	v_lshl_add_u64 v[36:37], v[154:155], 0, v[36:37]
	v_mul_f32_e32 v38, 0x45800000, v35
	v_cndmask_b32_e32 v38, v35, v38, vcc
	v_pk_mul_f32 v[30:31], v[30:31], v[38:39] op_sel_hi:[1,0]
	v_pk_mul_f32 v[42:43], v[26:27], v[38:39] op_sel_hi:[1,0]
	v_pk_mul_f32 v[32:33], v[32:33], v[38:39] op_sel_hi:[1,0]
	v_pk_mul_f32 v[40:41], v[28:29], v[38:39] op_sel_hi:[1,0]
	v_mov_b32_e32 v28, v31
	v_mov_b32_e32 v29, v43
	v_mov_b32_e32 v26, v30
	v_mov_b32_e32 v27, v42
	v_pk_mul_f32 v[28:29], v[28:29], v[28:29]
	v_mov_b32_e32 v44, v33
	v_mov_b32_e32 v45, v41
	v_pk_fma_f32 v[26:27], v[26:27], v[26:27], v[28:29]
	v_mov_b32_e32 v28, v32
	v_mov_b32_e32 v29, v40
	v_pk_mul_f32 v[44:45], v[44:45], v[44:45]
	v_pk_mul_f32 v[24:25], v[24:25], v[38:39] op_sel_hi:[1,0]
	v_pk_fma_f32 v[28:29], v[28:29], v[28:29], v[44:45]
	v_pk_mul_f32 v[22:23], v[22:23], v[38:39] op_sel_hi:[1,0]
	v_pk_add_f32 v[26:27], v[26:27], v[28:29]
	v_cvt_pk_bf16_f32 v28, v30, v31
	v_cvt_pk_bf16_f32 v29, v32, v33
	v_cvt_pk_bf16_f32 v30, v42, v43
	v_cvt_pk_bf16_f32 v31, v40, v41
	global_store_dwordx4 v[36:37], v[28:31], off sc1 nt
	s_nop 2
	v_pk_add_f32 v[26:27], v[26:27], v[26:27] op_sel:[0,1] op_sel_hi:[1,0]
	v_pk_mul_f32 v[20:21], v[20:21], v[38:39] op_sel_hi:[1,0]
	s_and_b64 vcc, exec, s[8:9]
	v_pk_mul_f32 v[18:19], v[18:19], v[38:39] op_sel_hi:[1,0]
	s_cbranch_vccz .LBB0_764
	v_cndmask_b32_e64 v26, 0, v26, s[4:5]
	s_branch .LBB0_765

; __device__ __forceinline__ unsigned cvtpk(float lo, float hi) { f32x2 v = {lo, hi}; bf16x2_t b = __builtin_convertvector(v, bf16x2_t); return __builtin_bit_cast(unsigned, b); }
; __device__ __forceinline__ float shx(float v, int o, int lane) { return __builtin_bit_cast(float, __builtin_amdgcn_ds_bpermute((lane ^ o) << 2, __builtin_bit_cast(int, v))); }
; __device__ __forceinline__ float sigmoidf_(float v) { return __builtin_amdgcn_rcpf(1.0f + __expf(-v)); }
; __device__ __forceinline__ void st16_wt(void* p, u32x4 v) { asm volatile("global_store_dwordx4 %0, %1, off sc1\n\ts_nop 2" :: "v"(p), "v"(v) : "memory"); }
;     __device__ __forceinline__ void operator()(const f32x4 (&acc)[2][2][4][2], const Unit& u, int wv) const {
;     ...
;             for (int bj = 0; bj < 2; ++bj) { f32x4 v0 = acc[ai][bj][m][0] * rstd, v1 = acc[ai][bj][m][1] * rstd;
;                 if (RSM && (u.pn == 0 || (u.pn == 1 && bj == 0))) ssm += ((v0[0] * v0[0] + v0[1] * v0[1]) + (v0[2] * v0[2] + v0[3] * v0[3])) + ((v1[0] * v1[0] + v1[1] * v1[1]) + (v1[2] * v1[2] + v1[3] * v1[3]));
;                 if (gate) {
; #pragma unroll
;                     for (int e = 0; e < 4; ++e) { v0[e] = sigmoidf_(v0[e]); v1[e] = sigmoidf_(v1[e]); } }
;                 u32x4 w; w.x = cvtpk(v0[0], v0[1]); w.y = cvtpk(v0[2], v0[3]); w.z = cvtpk(v1[0], v1[1]); w.w = cvtpk(v1[2], v1[3]);
;                 st16_wt(rowp + bj * HALF, w); }
;             if (RSM && u.pn < 2) { ssm += shx(ssm, 16, t_ & 63); ssm += shx(ssm, 32, t_ & 63);
;                 if (fq == 0) RSM[(size_t)(row0 + ai * HALF + m * 16) * 8 + u.pn * 4 + wc] = ssm; } }
.LBB0_765:
	v_cvt_pk_bf16_f32 v22, v22, v23
	v_cvt_pk_bf16_f32 v23, v24, v25
	v_cvt_pk_bf16_f32 v24, v18, v19
	v_cvt_pk_bf16_f32 v25, v20, v21
	v_lshl_add_u64 v[18:19], v[36:37], 0, s[0:1]
	global_store_dwordx4 v[18:19], v[22:25], off sc1 nt
	s_nop 2
	s_and_b64 vcc, exec, s[10:11]
	s_cbranch_vccnz .LBB0_769
	ds_bpermute_b32 v18, v180, v26
	s_waitcnt lgkmcnt(0)
	v_add_f32_e32 v18, v26, v18
	ds_bpermute_b32 v19, v0, v18
	s_and_saveexec_b64 s[86:87], s[6:7]
	s_cbranch_execz .LBB0_768
	v_lshlrev_b64 v[20:21], 5, v[144:145]
	v_lshl_add_u64 v[20:21], s[72:73], 0, v[20:21]
	v_lshl_add_u64 v[20:21], s[84:85], 2, v[20:21]
	s_lshl_b32 s22, s77, 2
	v_lshl_add_u64 v[20:21], v[20:21], 0, s[22:23]
	s_waitcnt lgkmcnt(0)
	v_add_f32_e32 v18, v18, v19
	global_store_dword v[20:21], v18, off

; __device__ __forceinline__ unsigned cvtpk(float lo, float hi) { f32x2 v = {lo, hi}; bf16x2_t b = __builtin_convertvector(v, bf16x2_t); return __builtin_bit_cast(unsigned, b); }
; __device__ __forceinline__ float sigmoidf_(float v) { return __builtin_amdgcn_rcpf(1.0f + __expf(-v)); }
; __device__ __forceinline__ void st16_wt(void* p, u32x4 v) { asm volatile("global_store_dwordx4 %0, %1, off sc1\n\ts_nop 2" :: "v"(p), "v"(v) : "memory"); }
; #define EPI_LOOP_ROWS for (int ai = 0; ai < 2; ++ai) _Pragma("unroll") for (int m = 0; m < 4; ++m)
; __device__ __forceinline__ float row_rstd_fin(float s, int lane) { s += shx(s, 16, lane); s += shx(s, 32, lane); return rsqrtf(s * (1.0f / 1024.0f) + EPS); }
;     __device__ __forceinline__ void operator()(const f32x4 (&acc)[2][2][4][2], const Unit& u, int wv) const {
;     ...
;         EPI_LOOP_ROWS rs[ai][m] = RS ? row_rstd_fin(rs[ai][m], t_ & 63) : 1.0f;
; #pragma unroll
;         EPI_LOOP_ROWS { bf16_t* rowp = base + (size_t)(row0 + ai * HALF + m * 16) * ldc + col0;
;             const float rstd = rs[ai][m];
;             float ssm = 0.f;
; #pragma unroll
;             for (int bj = 0; bj < 2; ++bj) { f32x4 v0 = acc[ai][bj][m][0] * rstd, v1 = acc[ai][bj][m][1] * rstd;
;                 if (RSM && (u.pn == 0 || (u.pn == 1 && bj == 0))) ssm += ((v0[0] * v0[0] + v0[1] * v0[1]) + (v0[2] * v0[2] + v0[3] * v0[3])) + ((v1[0] * v1[0] + v1[1] * v1[1]) + (v1[2] * v1[2] + v1[3] * v1[3]));
;                 if (gate) {
; #pragma unroll
;                     for (int e = 0; e < 4; ++e) { v0[e] = sigmoidf_(v0[e]); v1[e] = sigmoidf_(v1[e]); } }
;                 u32x4 w; w.x = cvtpk(v0[0], v0[1]); w.y = cvtpk(v0[2], v0[3]); w.z = cvtpk(v1[0], v1[1]); w.w = cvtpk(v1[2], v1[3]);
;                 st16_wt(rowp + bj * HALF, w); }
.LBB0_769:
	v_mul_f32_e32 v18, 0x4b800000, v34
	v_cndmask_b32_e64 v18, v34, v18, s[12:13]
	v_rsq_f32_e32 v20, v18
	s_waitcnt lgkmcnt(0)
	v_lshlrev_b64 v[18:19], 13, v[142:143]
	v_lshl_add_u64 v[18:19], v[154:155], 0, v[18:19]
	s_and_b64 vcc, exec, s[8:9]
	v_mul_f32_e32 v21, 0x45800000, v20
	v_cndmask_b32_e64 v20, v20, v21, s[12:13]
	v_pk_mul_f32 v[14:15], v[14:15], v[20:21] op_sel_hi:[1,0]
	v_pk_mul_f32 v[24:25], v[10:11], v[20:21] op_sel_hi:[1,0]
	v_pk_mul_f32 v[16:17], v[16:17], v[20:21] op_sel_hi:[1,0]
	v_pk_mul_f32 v[22:23], v[12:13], v[20:21] op_sel_hi:[1,0]
	v_mov_b32_e32 v12, v15
	v_mov_b32_e32 v13, v25
	v_mov_b32_e32 v10, v14
	v_mov_b32_e32 v11, v24
	v_pk_mul_f32 v[12:13], v[12:13], v[12:13]
	v_mov_b32_e32 v26, v17
	v_mov_b32_e32 v27, v23
	v_pk_fma_f32 v[10:11], v[10:11], v[10:11], v[12:13]
	v_mov_b32_e32 v12, v16
	v_mov_b32_e32 v13, v22
	v_pk_mul_f32 v[26:27], v[26:27], v[26:27]
	v_pk_mul_f32 v[8:9], v[8:9], v[20:21] op_sel_hi:[1,0]
	v_pk_fma_f32 v[12:13], v[12:13], v[12:13], v[26:27]
	v_pk_mul_f32 v[6:7], v[6:7], v[20:21] op_sel_hi:[1,0]
	v_pk_add_f32 v[10:11], v[10:11], v[12:13]
	v_cvt_pk_bf16_f32 v12, v14, v15
	v_cvt_pk_bf16_f32 v13, v16, v17
	v_cvt_pk_bf16_f32 v14, v24, v25
	v_cvt_pk_bf16_f32 v15, v22, v23
	global_store_dwordx4 v[18:19], v[12:15], off sc1 nt
	s_nop 2
	v_pk_add_f32 v[10:11], v[10:11], v[10:11] op_sel:[0,1] op_sel_hi:[1,0]
	v_pk_mul_f32 v[4:5], v[4:5], v[20:21] op_sel_hi:[1,0]
	v_pk_mul_f32 v[2:3], v[2:3], v[20:21] op_sel_hi:[1,0]
	s_cbranch_vccz .LBB0_771
	v_cndmask_b32_e64 v10, 0, v10, s[4:5]
	s_branch .LBB0_772

; __device__ __forceinline__ unsigned cvtpk(float lo, float hi) { f32x2 v = {lo, hi}; bf16x2_t b = __builtin_convertvector(v, bf16x2_t); return __builtin_bit_cast(unsigned, b); }
; __device__ __forceinline__ float shx(float v, int o, int lane) { return __builtin_bit_cast(float, __builtin_amdgcn_ds_bpermute((lane ^ o) << 2, __builtin_bit_cast(int, v))); }
; __device__ __forceinline__ float sigmoidf_(float v) { return __builtin_amdgcn_rcpf(1.0f + __expf(-v)); }
; __device__ __forceinline__ void st16_wt(void* p, u32x4 v) { asm volatile("global_store_dwordx4 %0, %1, off sc1\n\ts_nop 2" :: "v"(p), "v"(v) : "memory"); }
;     __device__ __forceinline__ void operator()(const f32x4 (&acc)[2][2][4][2], const Unit& u, int wv) const {
;     ...
;             for (int bj = 0; bj < 2; ++bj) { f32x4 v0 = acc[ai][bj][m][0] * rstd, v1 = acc[ai][bj][m][1] * rstd;
;                 if (RSM && (u.pn == 0 || (u.pn == 1 && bj == 0))) ssm += ((v0[0] * v0[0] + v0[1] * v0[1]) + (v0[2] * v0[2] + v0[3] * v0[3])) + ((v1[0] * v1[0] + v1[1] * v1[1]) + (v1[2] * v1[2] + v1[3] * v1[3]));
;                 if (gate) {
; #pragma unroll
;                     for (int e = 0; e < 4; ++e) { v0[e] = sigmoidf_(v0[e]); v1[e] = sigmoidf_(v1[e]); } }
;                 u32x4 w; w.x = cvtpk(v0[0], v0[1]); w.y = cvtpk(v0[2], v0[3]); w.z = cvtpk(v1[0], v1[1]); w.w = cvtpk(v1[2], v1[3]);
;                 st16_wt(rowp + bj * HALF, w); }
;             if (RSM && u.pn < 2) { ssm += shx(ssm, 16, t_ & 63); ssm += shx(ssm, 32, t_ & 63);
;                 if (fq == 0) RSM[(size_t)(row0 + ai * HALF + m * 16) * 8 + u.pn * 4 + wc] = ssm; } }
.LBB0_772:
	v_cvt_pk_bf16_f32 v6, v6, v7
	v_cvt_pk_bf16_f32 v7, v8, v9
	v_cvt_pk_bf16_f32 v8, v2, v3
	v_cvt_pk_bf16_f32 v9, v4, v5
	v_lshl_add_u64 v[2:3], v[18:19], 0, s[0:1]
	global_store_dwordx4 v[2:3], v[6:9], off sc1 nt
	s_nop 2
	s_and_b64 vcc, exec, s[10:11]
	s_cbranch_vccnz .LBB0_776
	ds_bpermute_b32 v2, v180, v10
	s_waitcnt lgkmcnt(0)
	v_add_f32_e32 v2, v10, v2
	ds_bpermute_b32 v0, v0, v2
	s_and_saveexec_b64 s[4:5], s[6:7]
	s_cbranch_execz .LBB0_775
	v_lshlrev_b64 v[4:5], 5, v[142:143]
	v_lshl_add_u64 v[4:5], s[72:73], 0, v[4:5]
	v_lshl_add_u64 v[4:5], s[84:85], 2, v[4:5]
	s_lshl_b32 s22, s77, 2
	v_lshl_add_u64 v[4:5], v[4:5], 0, s[22:23]
	s_waitcnt lgkmcnt(0)
	v_add_f32_e32 v0, v2, v0
	global_store_dword v[4:5], v0, off
